# duplicate consecutive s_waitcnt lgkmcnt(0) in the five GEMM K-loops deleted (on top of static priority raise)
# speedup vs baseline: 1.1014x; 1.0026x over previous
; #define G8_STAGE(bufoff, gbase, voff) do { _Pragma("unroll") for (int _i = 0; _i < 2; ++_i) \
;     __builtin_amdgcn_global_load_lds((const unsigned*)((const char*)(gbase) + (voff)[_i]), (LAS unsigned*)(lds + (bufoff) + ldsw + _i * 8192), 16, 0, 0); } while (0)
; #define G8_LDA(dst, b, h) do { _Pragma("unroll") for (int m = 0; m < 4; ++m) _Pragma("unroll") for (int k = 0; k < 2; ++k) dst[m][k] = *(const LAS bf16x8*)(lds + G8_SA(b, h) + aoff + m * 2048 + k * 1024); } while (0)
; #define G8_LDB(dst, b, h) do { _Pragma("unroll") for (int n = 0; n < 2; ++n) _Pragma("unroll") for (int k = 0; k < 2; ++k) dst[n][k] = *(const LAS bf16x8*)(lds + G8_SB(b, h) + boff + n * 2048 + k * 1024); } while (0)
; #define G8_MMA(ai, bj, At, Bt) do { __builtin_amdgcn_s_setprio(1); _Pragma("unroll") for (int m = 0; m < 4; ++m) _Pragma("unroll") for (int n = 0; n < 2; ++n) _Pragma("unroll") for (int k = 0; k < 2; ++k) \
;     acc[ai][bj][m][n] = __builtin_amdgcn_mfma_f32_16x16x32_bf16(Bt[n][k], At[m][k], acc[ai][bj][m][n], 0, 0, 0); __builtin_amdgcn_s_setprio(0); } while (0)
; #define G8_WAIT_V(n) asm volatile("s_waitcnt vmcnt(" #n ")" ::: "memory")
; template <class Epi, class Sched>
; __device__ __forceinline__ void gemm_phase(const int wv_, LAS unsigned char* lds, const int lda, const int ldb, const int K, const Sched& S, const Epi& E) {
;     ...
;     for (int t = 0; t < nt; t += 2) {
;       const bool last = (t == nt - 2);
;       const char* a1 = cA + (size_t)(t + 1) * kstep;
;       const char* a2 = last ? nA : cA + (size_t)(t + 2) * kstep; const char* b2 = last ? nB : cB + (size_t)(t + 2) * kstep;
;       const char* a3 = a2 + kstep; const char* b3 = b2 + kstep;
;       G8_LDB(B0, 0, 0); G8_SCHED; G8_LDA(At, 0, 0); G8_STAGE(G8_SA(1, 1), a1 + hstepA, voffA);
;       G8_WAIT_L(8); G8_BAR; G8_WAIT_L(0); G8_MMA(0, 0, At, B0); G8_BAR; G8_SCHED;
;       G8_LDB(B1, 0, 1); G8_STAGE(G8_SB(0, 0), b2, voffB);
;       G8_BAR; G8_WAIT_L(0); G8_MMA(0, 1, At, B1); G8_BAR;
;       G8_LDA(At, 0, 1); G8_STAGE(G8_SA(0, 0), a2, voffA);
;       G8_BAR; G8_WAIT_L(0); G8_MMA(1, 0, At, B0); G8_BAR; G8_SCHED;
;       G8_STAGE(G8_SB(0, 1), b2 + hstepB, voffB);
;       G8_WAIT_V(6); G8_BAR; G8_MMA(1, 1, At, B1); G8_BAR;
;       G8_LDB(B0, 1, 0); G8_SCHED; G8_LDA(At, 1, 0); G8_STAGE(G8_SA(0, 1), a2 + hstepA, voffA);
;       G8_WAIT_L(8); G8_BAR; G8_WAIT_L(0); G8_MMA(0, 0, At, B0); G8_BAR; G8_SCHED;
.Lg1_noprio:
.LBB0_207:
	s_add_i32 s53, s18, 2
	s_add_u32 s19, s4, 0xfff80080
	s_addc_u32 s20, s5, -1
	s_add_i32 s56, 0, 0x10000
	v_add_u32_e32 v147, s56, v148
	ds_read_b128 v[132:135], v147
	ds_read_b128 v[156:159], v147 offset:1024
	ds_read_b128 v[160:163], v147 offset:2048
	ds_read_b128 v[164:167], v147 offset:3072
	s_cmp_eq_u32 s13, s18
	s_cselect_b32 s18, s16, s50
	s_cselect_b32 s21, s15, s20
	s_cselect_b32 s20, s14, s19
	s_cselect_b32 s19, s17, s51
	v_lshl_add_u64 v[150:151], s[4:5], 0, v[142:143]
	s_add_i32 m0, s29, 0xc000
	ds_read_b128 v[190:193], v149
	ds_read_b128 v[194:197], v149 offset:1024
	ds_read_b128 v[198:201], v149 offset:2048
	ds_read_b128 v[202:205], v149 offset:3072
	ds_read_b128 v[206:209], v149 offset:4096
	ds_read_b128 v[210:213], v149 offset:5120
	ds_read_b128 v[214:217], v149 offset:6144
	ds_read_b128 v[218:221], v149 offset:7168
	global_load_lds_dwordx4 v[150:151], off
	v_lshl_add_u64 v[150:151], s[4:5], 0, v[144:145]
	s_add_i32 m0, s29, 0xe000
	s_nop 0
	global_load_lds_dwordx4 v[150:151], off
	s_waitcnt lgkmcnt(8)
	s_barrier
	s_waitcnt lgkmcnt(0)
	v_mfma_f32_16x16x32_bf16 v[128:131], v[132:135], v[190:193], v[128:131]
	v_mfma_f32_16x16x32_bf16 v[124:127], v[160:163], v[190:193], v[124:127]
	v_mfma_f32_16x16x32_bf16 v[112:115], v[132:135], v[198:201], v[112:115]
	v_mfma_f32_16x16x32_bf16 v[108:111], v[160:163], v[198:201], v[108:111]
	v_mfma_f32_16x16x32_bf16 v[96:99], v[132:135], v[206:209], v[96:99]
	v_mfma_f32_16x16x32_bf16 v[92:95], v[160:163], v[206:209], v[92:95]
	v_mfma_f32_16x16x32_bf16 v[80:83], v[132:135], v[214:217], v[80:83]
	v_mfma_f32_16x16x32_bf16 v[76:79], v[160:163], v[214:217], v[76:79]
	v_mfma_f32_16x16x32_bf16 v[128:131], v[156:159], v[194:197], v[128:131]
	v_mfma_f32_16x16x32_bf16 v[124:127], v[164:167], v[194:197], v[124:127]
	v_mfma_f32_16x16x32_bf16 v[112:115], v[156:159], v[202:205], v[112:115]
	v_mfma_f32_16x16x32_bf16 v[108:111], v[164:167], v[202:205], v[108:111]
	v_mfma_f32_16x16x32_bf16 v[96:99], v[156:159], v[210:213], v[96:99]
	v_mfma_f32_16x16x32_bf16 v[92:95], v[164:167], v[210:213], v[92:95]
	v_mfma_f32_16x16x32_bf16 v[80:83], v[156:159], v[218:221], v[80:83]
	v_mfma_f32_16x16x32_bf16 v[76:79], v[164:167], v[218:221], v[76:79]
	s_barrier
	s_add_i32 s58, 0, 0x14000
	s_add_i32 s56, s56, s28
	v_add_u32_e32 v147, s58, v148
	v_lshl_add_u64 v[150:151], s[18:19], 0, v[136:137]
	s_mov_b32 m0, s56
	ds_read_b128 v[222:225], v147
	ds_read_b128 v[226:229], v147 offset:1024
	ds_read_b128 v[230:233], v147 offset:2048
	ds_read_b128 v[234:237], v147 offset:3072
	global_load_lds_dwordx4 v[150:151], off
	v_lshl_add_u64 v[168:169], s[18:19], 0, v[140:141]
	s_add_i32 m0, s56, 0x2000
	s_nop 0
	global_load_lds_dwordx4 v[168:169], off
	s_barrier
	s_waitcnt lgkmcnt(0)
	v_mfma_f32_16x16x32_bf16 v[120:123], v[222:225], v[190:193], v[120:123]
	v_mfma_f32_16x16x32_bf16 v[116:119], v[230:233], v[190:193], v[116:119]
	v_mfma_f32_16x16x32_bf16 v[104:107], v[222:225], v[198:201], v[104:107]
	v_mfma_f32_16x16x32_bf16 v[100:103], v[230:233], v[198:201], v[100:103]
	v_mfma_f32_16x16x32_bf16 v[88:91], v[222:225], v[206:209], v[88:91]
	v_mfma_f32_16x16x32_bf16 v[84:87], v[230:233], v[206:209], v[84:87]
	v_mfma_f32_16x16x32_bf16 v[72:75], v[222:225], v[214:217], v[72:75]
	v_mfma_f32_16x16x32_bf16 v[68:71], v[230:233], v[214:217], v[68:71]
	v_mfma_f32_16x16x32_bf16 v[120:123], v[226:229], v[194:197], v[120:123]
	v_mfma_f32_16x16x32_bf16 v[116:119], v[234:237], v[194:197], v[116:119]
	v_mfma_f32_16x16x32_bf16 v[104:107], v[226:229], v[202:205], v[104:107]
	v_mfma_f32_16x16x32_bf16 v[100:103], v[234:237], v[202:205], v[100:103]
	v_mfma_f32_16x16x32_bf16 v[88:91], v[226:229], v[210:213], v[88:91]
	v_mfma_f32_16x16x32_bf16 v[84:87], v[234:237], v[210:213], v[84:87]
	v_mfma_f32_16x16x32_bf16 v[72:75], v[226:229], v[218:221], v[72:75]
	v_mfma_f32_16x16x32_bf16 v[68:71], v[234:237], v[218:221], v[68:71]
	s_mov_b32 m0, s29
	v_lshl_add_u64 v[238:239], s[20:21], 0, v[0:1]
	s_barrier
	ds_read_b128 v[190:193], v149 offset:16384
	ds_read_b128 v[194:197], v149 offset:17408
	ds_read_b128 v[198:201], v149 offset:18432
	ds_read_b128 v[202:205], v149 offset:19456
	ds_read_b128 v[206:209], v149 offset:20480
	ds_read_b128 v[210:213], v149 offset:21504
	ds_read_b128 v[214:217], v149 offset:22528
	ds_read_b128 v[218:221], v149 offset:23552
	global_load_lds_dwordx4 v[238:239], off
	v_lshl_add_u64 v[240:241], s[20:21], 0, v[138:139]
	s_mov_b32 m0, s30
	s_nop 0
	global_load_lds_dwordx4 v[240:241], off
	s_barrier
	s_waitcnt lgkmcnt(0)
	v_mfma_f32_16x16x32_bf16 v[64:67], v[132:135], v[190:193], v[64:67]
	v_mfma_f32_16x16x32_bf16 v[60:63], v[160:163], v[190:193], v[60:63]
	v_mfma_f32_16x16x32_bf16 v[48:51], v[132:135], v[198:201], v[48:51]
	v_mfma_f32_16x16x32_bf16 v[44:47], v[160:163], v[198:201], v[44:47]
	v_mfma_f32_16x16x32_bf16 v[32:35], v[132:135], v[206:209], v[32:35]
	v_mfma_f32_16x16x32_bf16 v[28:31], v[160:163], v[206:209], v[28:31]
	v_mfma_f32_16x16x32_bf16 v[16:19], v[132:135], v[214:217], v[16:19]
	v_mfma_f32_16x16x32_bf16 v[12:15], v[160:163], v[214:217], v[12:15]
	v_mfma_f32_16x16x32_bf16 v[64:67], v[156:159], v[194:197], v[64:67]
	v_mfma_f32_16x16x32_bf16 v[60:63], v[164:167], v[194:197], v[60:63]
	v_mfma_f32_16x16x32_bf16 v[48:51], v[156:159], v[202:205], v[48:51]
	v_mfma_f32_16x16x32_bf16 v[44:47], v[164:167], v[202:205], v[44:47]
	v_mfma_f32_16x16x32_bf16 v[32:35], v[156:159], v[210:213], v[32:35]
	v_mfma_f32_16x16x32_bf16 v[28:31], v[164:167], v[210:213], v[28:31]
	v_mfma_f32_16x16x32_bf16 v[16:19], v[156:159], v[218:221], v[16:19]
	v_mfma_f32_16x16x32_bf16 v[12:15], v[164:167], v[218:221], v[12:15]
	s_barrier
; #define G8_STAGE(bufoff, gbase, voff) do { _Pragma("unroll") for (int _i = 0; _i < 2; ++_i) \
;     __builtin_amdgcn_global_load_lds((const unsigned*)((const char*)(gbase) + (voff)[_i]), (LAS unsigned*)(lds + (bufoff) + ldsw + _i * 8192), 16, 0, 0); } while (0)
; #define G8_LDA(dst, b, h) do { _Pragma("unroll") for (int m = 0; m < 4; ++m) _Pragma("unroll") for (int k = 0; k < 2; ++k) dst[m][k] = *(const LAS bf16x8*)(lds + G8_SA(b, h) + aoff + m * 2048 + k * 1024); } while (0)
; #define G8_LDB(dst, b, h) do { _Pragma("unroll") for (int n = 0; n < 2; ++n) _Pragma("unroll") for (int k = 0; k < 2; ++k) dst[n][k] = *(const LAS bf16x8*)(lds + G8_SB(b, h) + boff + n * 2048 + k * 1024); } while (0)
; #define G8_MMA(ai, bj, At, Bt) do { __builtin_amdgcn_s_setprio(1); _Pragma("unroll") for (int m = 0; m < 4; ++m) _Pragma("unroll") for (int n = 0; n < 2; ++n) _Pragma("unroll") for (int k = 0; k < 2; ++k) \
;     acc[ai][bj][m][n] = __builtin_amdgcn_mfma_f32_16x16x32_bf16(Bt[n][k], At[m][k], acc[ai][bj][m][n], 0, 0, 0); __builtin_amdgcn_s_setprio(0); } while (0)
; #define G8_WAIT_V(n) asm volatile("s_waitcnt vmcnt(" #n ")" ::: "memory")
; #define G8_WAIT_L(n) asm volatile("s_waitcnt lgkmcnt(" #n ")" ::: "memory")
; #define G8_BAR __builtin_amdgcn_s_barrier()
; #define G8_SCHED __builtin_amdgcn_sched_barrier(0)
; template <class Epi, class Sched>
; __device__ __forceinline__ void gemm_phase(const int wv_, LAS unsigned char* lds, const int lda, const int ldb, const int K, const Sched& S, const Epi& E) {
;     ...
;       G8_STAGE(G8_SB(0, 1), b2 + hstepB, voffB);
;       G8_WAIT_V(6); G8_BAR; G8_MMA(1, 1, At, B1); G8_BAR;
;       G8_LDB(B0, 1, 0); G8_SCHED; G8_LDA(At, 1, 0); G8_STAGE(G8_SA(0, 1), a2 + hstepA, voffA);
;       G8_WAIT_L(8); G8_BAR; G8_WAIT_L(0); G8_MMA(0, 0, At, B0); G8_BAR; G8_SCHED;
;       G8_LDB(B1, 1, 1); G8_STAGE(G8_SB(1, 0), b3, voffB);
;       G8_BAR; G8_WAIT_L(0); G8_MMA(0, 1, At, B1); G8_BAR;
;       G8_LDA(At, 1, 1); G8_STAGE(G8_SA(1, 0), a3, voffA);
;       G8_BAR; G8_WAIT_L(0); G8_MMA(1, 0, At, B0); G8_BAR; G8_SCHED;
	s_add_u32 s56, s18, 0x80000
	s_addc_u32 s57, s19, 0
	s_add_i32 s58, s58, s28
	v_lshl_add_u64 v[132:133], s[56:57], 0, v[136:137]
	s_mov_b32 m0, s58
	s_nop 0
	global_load_lds_dwordx4 v[132:133], off
	v_lshl_add_u64 v[132:133], s[56:57], 0, v[140:141]
	s_add_i32 m0, s58, 0x2000
	s_nop 0
	global_load_lds_dwordx4 v[132:133], off
	s_waitcnt vmcnt(6)
	s_barrier
	v_mfma_f32_16x16x32_bf16 v[56:59], v[222:225], v[190:193], v[56:59]
	v_mfma_f32_16x16x32_bf16 v[52:55], v[230:233], v[190:193], v[52:55]
	v_mfma_f32_16x16x32_bf16 v[40:43], v[222:225], v[198:201], v[40:43]
	v_mfma_f32_16x16x32_bf16 v[36:39], v[230:233], v[198:201], v[36:39]
	v_mfma_f32_16x16x32_bf16 v[24:27], v[222:225], v[206:209], v[24:27]
	v_mfma_f32_16x16x32_bf16 v[20:23], v[230:233], v[206:209], v[20:23]
	v_mfma_f32_16x16x32_bf16 v[8:11], v[222:225], v[214:217], v[8:11]
	v_mfma_f32_16x16x32_bf16 v[4:7], v[230:233], v[214:217], v[4:7]
	v_mfma_f32_16x16x32_bf16 v[56:59], v[226:229], v[194:197], v[56:59]
	v_mfma_f32_16x16x32_bf16 v[52:55], v[234:237], v[194:197], v[52:55]
	v_mfma_f32_16x16x32_bf16 v[40:43], v[226:229], v[202:205], v[40:43]
	v_mfma_f32_16x16x32_bf16 v[36:39], v[234:237], v[202:205], v[36:39]
	v_mfma_f32_16x16x32_bf16 v[24:27], v[226:229], v[210:213], v[24:27]
	v_mfma_f32_16x16x32_bf16 v[20:23], v[234:237], v[210:213], v[20:23]
	v_mfma_f32_16x16x32_bf16 v[8:11], v[226:229], v[218:221], v[8:11]
	v_mfma_f32_16x16x32_bf16 v[4:7], v[234:237], v[218:221], v[4:7]
	s_add_i32 s56, 0, 0x18000
	v_add_u32_e32 v147, s56, v148
	s_barrier
	ds_read_b128 v[132:135], v147
	ds_read_b128 v[156:159], v147 offset:1024
	ds_read_b128 v[160:163], v147 offset:2048
	ds_read_b128 v[164:167], v147 offset:3072
	s_add_u32 s20, s20, 0x80000
	s_addc_u32 s21, s21, 0
	s_mov_b32 m0, s31
	v_lshl_add_u64 v[222:223], s[20:21], 0, v[0:1]
	ds_read_b128 v[190:193], v149 offset:32768
	ds_read_b128 v[194:197], v149 offset:33792
	ds_read_b128 v[198:201], v149 offset:34816
	ds_read_b128 v[202:205], v149 offset:35840
	ds_read_b128 v[206:209], v149 offset:36864
	ds_read_b128 v[210:213], v149 offset:37888
	ds_read_b128 v[214:217], v149 offset:38912
	ds_read_b128 v[218:221], v149 offset:39936
	global_load_lds_dwordx4 v[222:223], off
	v_lshl_add_u64 v[222:223], s[20:21], 0, v[138:139]
	s_mov_b32 m0, s34
	s_nop 0
	global_load_lds_dwordx4 v[222:223], off
	s_waitcnt lgkmcnt(8)
	s_barrier
	s_waitcnt lgkmcnt(0)
	v_mfma_f32_16x16x32_bf16 v[128:131], v[132:135], v[190:193], v[128:131]
	v_mfma_f32_16x16x32_bf16 v[124:127], v[160:163], v[190:193], v[124:127]
	v_mfma_f32_16x16x32_bf16 v[112:115], v[132:135], v[198:201], v[112:115]
	v_mfma_f32_16x16x32_bf16 v[108:111], v[160:163], v[198:201], v[108:111]
	v_mfma_f32_16x16x32_bf16 v[96:99], v[132:135], v[206:209], v[96:99]
	v_mfma_f32_16x16x32_bf16 v[92:95], v[160:163], v[206:209], v[92:95]
	v_mfma_f32_16x16x32_bf16 v[80:83], v[132:135], v[214:217], v[80:83]
	v_mfma_f32_16x16x32_bf16 v[76:79], v[160:163], v[214:217], v[76:79]
	v_mfma_f32_16x16x32_bf16 v[128:131], v[156:159], v[194:197], v[128:131]
	v_mfma_f32_16x16x32_bf16 v[124:127], v[164:167], v[194:197], v[124:127]
	v_mfma_f32_16x16x32_bf16 v[112:115], v[156:159], v[202:205], v[112:115]
	v_mfma_f32_16x16x32_bf16 v[108:111], v[164:167], v[202:205], v[108:111]
	v_mfma_f32_16x16x32_bf16 v[96:99], v[156:159], v[210:213], v[96:99]
	v_mfma_f32_16x16x32_bf16 v[92:95], v[164:167], v[210:213], v[92:95]
	v_mfma_f32_16x16x32_bf16 v[80:83], v[156:159], v[218:221], v[80:83]
	v_mfma_f32_16x16x32_bf16 v[76:79], v[164:167], v[218:221], v[76:79]
	s_barrier
	s_add_i32 s20, 0, 0x1c000
	s_add_i32 s21, s56, s28
	v_add_u32_e32 v147, s20, v148
	v_lshl_add_u64 v[150:151], v[150:151], 0, s[90:91]
	s_mov_b32 m0, s21
	ds_read_b128 v[222:225], v147
	ds_read_b128 v[226:229], v147 offset:1024
	ds_read_b128 v[230:233], v147 offset:2048
	ds_read_b128 v[234:237], v147 offset:3072
	global_load_lds_dwordx4 v[150:151], off
	v_lshl_add_u64 v[150:151], v[168:169], 0, s[90:91]
	s_add_i32 m0, s21, 0x2000
	s_nop 0
	global_load_lds_dwordx4 v[150:151], off
	s_barrier
; #define G8_STAGE(bufoff, gbase, voff) do { _Pragma("unroll") for (int _i = 0; _i < 2; ++_i) \
;     __builtin_amdgcn_global_load_lds((const unsigned*)((const char*)(gbase) + (voff)[_i]), (LAS unsigned*)(lds + (bufoff) + ldsw + _i * 8192), 16, 0, 0); } while (0)
; #define G8_LDA(dst, b, h) do { _Pragma("unroll") for (int m = 0; m < 4; ++m) _Pragma("unroll") for (int k = 0; k < 2; ++k) dst[m][k] = *(const LAS bf16x8*)(lds + G8_SA(b, h) + aoff + m * 2048 + k * 1024); } while (0)
; #define G8_LDB(dst, b, h) do { _Pragma("unroll") for (int n = 0; n < 2; ++n) _Pragma("unroll") for (int k = 0; k < 2; ++k) dst[n][k] = *(const LAS bf16x8*)(lds + G8_SB(b, h) + boff + n * 2048 + k * 1024); } while (0)
; #define G8_MMA(ai, bj, At, Bt) do { __builtin_amdgcn_s_setprio(1); _Pragma("unroll") for (int m = 0; m < 4; ++m) _Pragma("unroll") for (int n = 0; n < 2; ++n) _Pragma("unroll") for (int k = 0; k < 2; ++k) \
;     acc[ai][bj][m][n] = __builtin_amdgcn_mfma_f32_16x16x32_bf16(Bt[n][k], At[m][k], acc[ai][bj][m][n], 0, 0, 0); __builtin_amdgcn_s_setprio(0); } while (0)
; #define G8_WAIT_V(n) asm volatile("s_waitcnt vmcnt(" #n ")" ::: "memory")
; #define G8_WAIT_L(n) asm volatile("s_waitcnt lgkmcnt(" #n ")" ::: "memory")
; #define G8_BAR __builtin_amdgcn_s_barrier()
; #define G8_SCHED __builtin_amdgcn_sched_barrier(0)
; template <class Epi, class Sched>
; __device__ __forceinline__ void gemm_phase(const int wv_, LAS unsigned char* lds, const int lda, const int ldb, const int K, const Sched& S, const Epi& E) {
;     ...
;       G8_LDB(B1, 1, 1); G8_STAGE(G8_SB(1, 0), b3, voffB);
;       G8_BAR; G8_WAIT_L(0); G8_MMA(0, 1, At, B1); G8_BAR;
;       G8_LDA(At, 1, 1); G8_STAGE(G8_SA(1, 0), a3, voffA);
;       G8_BAR; G8_WAIT_L(0); G8_MMA(1, 0, At, B0); G8_BAR; G8_SCHED;
;       G8_STAGE(G8_SB(1, 1), b3 + hstepB, voffB);
;       G8_WAIT_V(6); G8_BAR; G8_MMA(1, 1, At, B1); G8_BAR;
;     }
;   __device__ __forceinline__ bool operator()(f32x4 (&acc)[2][2][4][2], const Unit& u, int wr, int wc, int fr, int fq) const {
;     if (u.split == 2) return true;
;     const int row0 = u.pm * BM + wr * 64 + fr;
;     const bool gate = u.pn >= 28;
;     bf16_t* base = gate ? pg + (size_t)(u.pn - 28) * BM : png + (size_t)u.pn * BM;
;     const size_t ldc = gate ? 8192 : NNGP;
	s_waitcnt lgkmcnt(0)
	v_mfma_f32_16x16x32_bf16 v[120:123], v[222:225], v[190:193], v[120:123]
	v_mfma_f32_16x16x32_bf16 v[116:119], v[230:233], v[190:193], v[116:119]
	v_mfma_f32_16x16x32_bf16 v[104:107], v[222:225], v[198:201], v[104:107]
	v_mfma_f32_16x16x32_bf16 v[100:103], v[230:233], v[198:201], v[100:103]
	v_mfma_f32_16x16x32_bf16 v[88:91], v[222:225], v[206:209], v[88:91]
	v_mfma_f32_16x16x32_bf16 v[84:87], v[230:233], v[206:209], v[84:87]
	v_mfma_f32_16x16x32_bf16 v[72:75], v[222:225], v[214:217], v[72:75]
	v_mfma_f32_16x16x32_bf16 v[68:71], v[230:233], v[214:217], v[68:71]
	v_mfma_f32_16x16x32_bf16 v[120:123], v[226:229], v[194:197], v[120:123]
	v_mfma_f32_16x16x32_bf16 v[116:119], v[234:237], v[194:197], v[116:119]
	v_mfma_f32_16x16x32_bf16 v[104:107], v[226:229], v[202:205], v[104:107]
	v_mfma_f32_16x16x32_bf16 v[100:103], v[234:237], v[202:205], v[100:103]
	v_mfma_f32_16x16x32_bf16 v[88:91], v[226:229], v[210:213], v[88:91]
	v_mfma_f32_16x16x32_bf16 v[84:87], v[234:237], v[210:213], v[84:87]
	v_mfma_f32_16x16x32_bf16 v[72:75], v[226:229], v[218:221], v[72:75]
	v_mfma_f32_16x16x32_bf16 v[68:71], v[234:237], v[218:221], v[68:71]
	s_mov_b32 m0, s39
	v_lshl_add_u64 v[150:151], v[238:239], 0, s[90:91]
	s_barrier
	ds_read_b128 v[190:193], v149 offset:49152
	ds_read_b128 v[194:197], v149 offset:50176
	ds_read_b128 v[198:201], v149 offset:51200
	ds_read_b128 v[202:205], v149 offset:52224
	ds_read_b128 v[206:209], v149 offset:53248
	ds_read_b128 v[210:213], v149 offset:54272
	ds_read_b128 v[214:217], v149 offset:55296
	ds_read_b128 v[218:221], v149 offset:56320
	global_load_lds_dwordx4 v[150:151], off
	v_lshl_add_u64 v[150:151], v[240:241], 0, s[90:91]
	s_mov_b32 m0, s40
	s_nop 0
	global_load_lds_dwordx4 v[150:151], off
	s_barrier
	s_waitcnt lgkmcnt(0)
	v_mfma_f32_16x16x32_bf16 v[64:67], v[132:135], v[190:193], v[64:67]
	v_mfma_f32_16x16x32_bf16 v[60:63], v[160:163], v[190:193], v[60:63]
	v_mfma_f32_16x16x32_bf16 v[48:51], v[132:135], v[198:201], v[48:51]
	v_mfma_f32_16x16x32_bf16 v[44:47], v[160:163], v[198:201], v[44:47]
	v_mfma_f32_16x16x32_bf16 v[32:35], v[132:135], v[206:209], v[32:35]
	v_mfma_f32_16x16x32_bf16 v[28:31], v[160:163], v[206:209], v[28:31]
	v_mfma_f32_16x16x32_bf16 v[16:19], v[132:135], v[214:217], v[16:19]
	v_mfma_f32_16x16x32_bf16 v[12:15], v[160:163], v[214:217], v[12:15]
	v_mfma_f32_16x16x32_bf16 v[64:67], v[156:159], v[194:197], v[64:67]
	v_mfma_f32_16x16x32_bf16 v[60:63], v[164:167], v[194:197], v[60:63]
	v_mfma_f32_16x16x32_bf16 v[48:51], v[156:159], v[202:205], v[48:51]
	v_mfma_f32_16x16x32_bf16 v[44:47], v[164:167], v[202:205], v[44:47]
	v_mfma_f32_16x16x32_bf16 v[32:35], v[156:159], v[210:213], v[32:35]
	v_mfma_f32_16x16x32_bf16 v[28:31], v[164:167], v[210:213], v[28:31]
	v_mfma_f32_16x16x32_bf16 v[16:19], v[156:159], v[218:221], v[16:19]
	v_mfma_f32_16x16x32_bf16 v[12:15], v[164:167], v[218:221], v[12:15]
	s_barrier
	s_add_u32 s18, s18, 0x80080
	s_addc_u32 s19, s19, 0
	s_add_i32 s20, s20, s28
	v_lshl_add_u64 v[132:133], s[18:19], 0, v[136:137]
	s_mov_b32 m0, s20
	s_nop 0
	global_load_lds_dwordx4 v[132:133], off
	v_lshl_add_u64 v[132:133], s[18:19], 0, v[140:141]
	s_add_i32 m0, s20, 0x2000
	s_nop 0
	global_load_lds_dwordx4 v[132:133], off
	s_waitcnt vmcnt(6)
	s_barrier
	v_mfma_f32_16x16x32_bf16 v[56:59], v[222:225], v[190:193], v[56:59]
	v_mfma_f32_16x16x32_bf16 v[52:55], v[230:233], v[190:193], v[52:55]
	v_mfma_f32_16x16x32_bf16 v[40:43], v[222:225], v[198:201], v[40:43]
	v_mfma_f32_16x16x32_bf16 v[36:39], v[230:233], v[198:201], v[36:39]
	v_mfma_f32_16x16x32_bf16 v[24:27], v[222:225], v[206:209], v[24:27]
	v_mfma_f32_16x16x32_bf16 v[20:23], v[230:233], v[206:209], v[20:23]
	v_mfma_f32_16x16x32_bf16 v[8:11], v[222:225], v[214:217], v[8:11]
	v_mfma_f32_16x16x32_bf16 v[4:7], v[230:233], v[214:217], v[4:7]
	v_mfma_f32_16x16x32_bf16 v[56:59], v[226:229], v[194:197], v[56:59]
	v_mfma_f32_16x16x32_bf16 v[52:55], v[234:237], v[194:197], v[52:55]
	v_mfma_f32_16x16x32_bf16 v[40:43], v[226:229], v[202:205], v[40:43]
	v_mfma_f32_16x16x32_bf16 v[36:39], v[234:237], v[202:205], v[36:39]
	v_mfma_f32_16x16x32_bf16 v[24:27], v[226:229], v[210:213], v[24:27]
	v_mfma_f32_16x16x32_bf16 v[20:23], v[234:237], v[210:213], v[20:23]
	v_mfma_f32_16x16x32_bf16 v[8:11], v[226:229], v[218:221], v[8:11]
	v_mfma_f32_16x16x32_bf16 v[4:7], v[234:237], v[218:221], v[4:7]
	s_add_u32 s4, s4, 0x100
	s_addc_u32 s5, s5, 0
	s_add_u32 s50, s50, 0x100
	s_addc_u32 s51, s51, 0
	s_cmp_ge_i32 s53, s47
	s_mov_b32 s18, s53
	s_barrier
	s_cbranch_scc0 .LBB0_207
	s_setprio 0
	s_cmp_eq_u32 s46, 2
	s_cbranch_scc1 .LBB0_202
	s_cmp_gt_i32 s27, 27
	s_cselect_b64 s[18:19], -1, 0
	s_cmp_lt_i32 s27, 28
	s_cselect_b64 s[20:21], -1, 0
	s_mov_b64 s[4:5], -1
	s_and_b64 vcc, exec, s[18:19]
	s_cbranch_vccnz .LBB0_211
	s_mov_b64 s[4:5], 0

; #define G8_STAGE(bufoff, gbase, voff) do { _Pragma("unroll") for (int _i = 0; _i < 2; ++_i) \
;     __builtin_amdgcn_global_load_lds((const unsigned*)((const char*)(gbase) + (voff)[_i]), (LAS unsigned*)(lds + (bufoff) + ldsw + _i * 8192), 16, 0, 0); } while (0)
; #define G8_LDA(dst, b, h) do { _Pragma("unroll") for (int m = 0; m < 4; ++m) _Pragma("unroll") for (int k = 0; k < 2; ++k) dst[m][k] = *(const LAS bf16x8*)(lds + G8_SA(b, h) + aoff + m * 2048 + k * 1024); } while (0)
; #define G8_LDB(dst, b, h) do { _Pragma("unroll") for (int n = 0; n < 2; ++n) _Pragma("unroll") for (int k = 0; k < 2; ++k) dst[n][k] = *(const LAS bf16x8*)(lds + G8_SB(b, h) + boff + n * 2048 + k * 1024); } while (0)
; #define G8_MMA(ai, bj, At, Bt) do { __builtin_amdgcn_s_setprio(1); _Pragma("unroll") for (int m = 0; m < 4; ++m) _Pragma("unroll") for (int n = 0; n < 2; ++n) _Pragma("unroll") for (int k = 0; k < 2; ++k) \
;     acc[ai][bj][m][n] = __builtin_amdgcn_mfma_f32_16x16x32_bf16(Bt[n][k], At[m][k], acc[ai][bj][m][n], 0, 0, 0); __builtin_amdgcn_s_setprio(0); } while (0)
; #define G8_WAIT_L(n) asm volatile("s_waitcnt lgkmcnt(" #n ")" ::: "memory")
; #define G8_BAR __builtin_amdgcn_s_barrier()
; #define G8_SCHED __builtin_amdgcn_sched_barrier(0)
; template <class Epi, class Sched>
; __device__ __forceinline__ void gemm_phase(const int wv_, LAS unsigned char* lds, const int lda, const int ldb, const int K, const Sched& S, const Epi& E) {
;     ...
;     for (int t = 0; t < nt; t += 2) {
;       const bool last = (t == nt - 2);
;       const char* a1 = cA + (size_t)(t + 1) * kstep;
;       const char* a2 = last ? nA : cA + (size_t)(t + 2) * kstep; const char* b2 = last ? nB : cB + (size_t)(t + 2) * kstep;
;       const char* a3 = a2 + kstep; const char* b3 = b2 + kstep;
;       G8_LDB(B0, 0, 0); G8_SCHED; G8_LDA(At, 0, 0); G8_STAGE(G8_SA(1, 1), a1 + hstepA, voffA);
;       G8_WAIT_L(8); G8_BAR; G8_WAIT_L(0); G8_MMA(0, 0, At, B0); G8_BAR; G8_SCHED;
;       G8_LDB(B1, 0, 1); G8_STAGE(G8_SB(0, 0), b2, voffB);
;       G8_BAR; G8_WAIT_L(0); G8_MMA(0, 1, At, B1); G8_BAR;
;       G8_LDA(At, 0, 1); G8_STAGE(G8_SA(0, 0), a2, voffA);
;       G8_BAR; G8_WAIT_L(0); G8_MMA(1, 0, At, B0); G8_BAR; G8_SCHED;
.Lg2_noprio:
.LBB0_812:
	s_add_u32 s23, s28, 0xfffe0080
	s_addc_u32 s30, s29, -1
	s_add_i32 s69, 0, 0x10000
	v_add_u32_e32 v150, s69, v162
	ds_read_b128 v[142:145], v150
	ds_read_b128 v[146:149], v150 offset:1024
	ds_read_b128 v[156:159], v150 offset:2048
	ds_read_b128 v[166:169], v150 offset:3072
	s_cmp_eq_u32 s21, 4
	s_cselect_b32 s35, s25, s30
	s_cselect_b32 s34, s24, s23
	s_cselect_b32 s31, s27, s13
	s_cselect_b32 s30, s26, s11
	v_lshl_add_u64 v[150:151], s[28:29], 0, v[138:139]
	s_add_i32 m0, s46, 0xc000
	ds_read_b128 v[190:193], v164
	ds_read_b128 v[194:197], v164 offset:1024
	ds_read_b128 v[198:201], v164 offset:2048
	ds_read_b128 v[202:205], v164 offset:3072
	ds_read_b128 v[206:209], v164 offset:4096
	ds_read_b128 v[210:213], v164 offset:5120
	ds_read_b128 v[214:217], v164 offset:6144
	ds_read_b128 v[218:221], v164 offset:7168
	global_load_lds_dwordx4 v[150:151], off
	v_lshl_add_u64 v[150:151], s[28:29], 0, v[140:141]
	s_add_i32 m0, s46, 0xe000
	s_nop 0
	global_load_lds_dwordx4 v[150:151], off
	s_waitcnt lgkmcnt(8)
	s_barrier
	s_waitcnt lgkmcnt(0)
	v_mfma_f32_16x16x32_bf16 v[128:131], v[142:145], v[190:193], v[128:131]
	v_mfma_f32_16x16x32_bf16 v[124:127], v[156:159], v[190:193], v[124:127]
	v_mfma_f32_16x16x32_bf16 v[120:123], v[142:145], v[198:201], v[120:123]
	v_mfma_f32_16x16x32_bf16 v[116:119], v[156:159], v[198:201], v[116:119]
	v_mfma_f32_16x16x32_bf16 v[112:115], v[142:145], v[206:209], v[112:115]
	v_mfma_f32_16x16x32_bf16 v[108:111], v[156:159], v[206:209], v[108:111]
	v_mfma_f32_16x16x32_bf16 v[104:107], v[142:145], v[214:217], v[104:107]
	v_mfma_f32_16x16x32_bf16 v[100:103], v[156:159], v[214:217], v[100:103]
	v_mfma_f32_16x16x32_bf16 v[128:131], v[146:149], v[194:197], v[128:131]
	v_mfma_f32_16x16x32_bf16 v[124:127], v[166:169], v[194:197], v[124:127]
	v_mfma_f32_16x16x32_bf16 v[120:123], v[146:149], v[202:205], v[120:123]
	v_mfma_f32_16x16x32_bf16 v[116:119], v[166:169], v[202:205], v[116:119]
	v_mfma_f32_16x16x32_bf16 v[112:115], v[146:149], v[210:213], v[112:115]
	v_mfma_f32_16x16x32_bf16 v[108:111], v[166:169], v[210:213], v[108:111]
	v_mfma_f32_16x16x32_bf16 v[104:107], v[146:149], v[218:221], v[104:107]
	v_mfma_f32_16x16x32_bf16 v[100:103], v[166:169], v[218:221], v[100:103]
	s_barrier
	s_add_i32 s23, 0, 0x14000
	v_add_u32_e32 v150, s23, v162
	s_add_i32 s69, s69, s43
	ds_read_b128 v[222:225], v150
	ds_read_b128 v[226:229], v150 offset:1024
	ds_read_b128 v[230:233], v150 offset:2048
	ds_read_b128 v[234:237], v150 offset:3072
	v_lshl_add_u64 v[150:151], s[30:31], 0, v[132:133]
	s_mov_b32 m0, s69
	v_lshl_add_u64 v[160:161], s[30:31], 0, v[136:137]
	global_load_lds_dwordx4 v[150:151], off
	s_add_i32 m0, s69, 0x2000
	s_nop 0
	global_load_lds_dwordx4 v[160:161], off
	s_barrier
	s_waitcnt lgkmcnt(0)
	v_mfma_f32_16x16x32_bf16 v[96:99], v[222:225], v[190:193], v[96:99]
	v_mfma_f32_16x16x32_bf16 v[92:95], v[230:233], v[190:193], v[92:95]
	v_mfma_f32_16x16x32_bf16 v[88:91], v[222:225], v[198:201], v[88:91]
	v_mfma_f32_16x16x32_bf16 v[84:87], v[230:233], v[198:201], v[84:87]
	v_mfma_f32_16x16x32_bf16 v[80:83], v[222:225], v[206:209], v[80:83]
	v_mfma_f32_16x16x32_bf16 v[76:79], v[230:233], v[206:209], v[76:79]
	v_mfma_f32_16x16x32_bf16 v[72:75], v[222:225], v[214:217], v[72:75]
	v_mfma_f32_16x16x32_bf16 v[68:71], v[230:233], v[214:217], v[68:71]
	v_mfma_f32_16x16x32_bf16 v[96:99], v[226:229], v[194:197], v[96:99]
	v_mfma_f32_16x16x32_bf16 v[92:95], v[234:237], v[194:197], v[92:95]
	v_mfma_f32_16x16x32_bf16 v[88:91], v[226:229], v[202:205], v[88:91]
	v_mfma_f32_16x16x32_bf16 v[84:87], v[234:237], v[202:205], v[84:87]
	v_mfma_f32_16x16x32_bf16 v[80:83], v[226:229], v[210:213], v[80:83]
	v_mfma_f32_16x16x32_bf16 v[76:79], v[234:237], v[210:213], v[76:79]
	v_mfma_f32_16x16x32_bf16 v[72:75], v[226:229], v[218:221], v[72:75]
	v_mfma_f32_16x16x32_bf16 v[68:71], v[234:237], v[218:221], v[68:71]
	s_mov_b32 m0, s46
	v_lshl_add_u64 v[238:239], s[34:35], 0, v[0:1]
	s_barrier
	ds_read_b128 v[190:193], v164 offset:16384
	ds_read_b128 v[194:197], v164 offset:17408
	ds_read_b128 v[198:201], v164 offset:18432
	ds_read_b128 v[202:205], v164 offset:19456
	ds_read_b128 v[206:209], v164 offset:20480
	ds_read_b128 v[210:213], v164 offset:21504
	ds_read_b128 v[214:217], v164 offset:22528
	ds_read_b128 v[218:221], v164 offset:23552
	global_load_lds_dwordx4 v[238:239], off
	v_lshl_add_u64 v[240:241], s[34:35], 0, v[134:135]
	s_mov_b32 m0, s47
	s_nop 0
	global_load_lds_dwordx4 v[240:241], off
	s_barrier
	s_waitcnt lgkmcnt(0)
	v_mfma_f32_16x16x32_bf16 v[64:67], v[142:145], v[190:193], v[64:67]
	v_mfma_f32_16x16x32_bf16 v[60:63], v[156:159], v[190:193], v[60:63]
	v_mfma_f32_16x16x32_bf16 v[56:59], v[142:145], v[198:201], v[56:59]
	v_mfma_f32_16x16x32_bf16 v[52:55], v[156:159], v[198:201], v[52:55]
	v_mfma_f32_16x16x32_bf16 v[48:51], v[142:145], v[206:209], v[48:51]
	v_mfma_f32_16x16x32_bf16 v[44:47], v[156:159], v[206:209], v[44:47]
	v_mfma_f32_16x16x32_bf16 v[40:43], v[142:145], v[214:217], v[40:43]
	v_mfma_f32_16x16x32_bf16 v[36:39], v[156:159], v[214:217], v[36:39]
	v_mfma_f32_16x16x32_bf16 v[64:67], v[146:149], v[194:197], v[64:67]
	v_mfma_f32_16x16x32_bf16 v[60:63], v[166:169], v[194:197], v[60:63]
	v_mfma_f32_16x16x32_bf16 v[56:59], v[146:149], v[202:205], v[56:59]
	v_mfma_f32_16x16x32_bf16 v[52:55], v[166:169], v[202:205], v[52:55]
	v_mfma_f32_16x16x32_bf16 v[48:51], v[146:149], v[210:213], v[48:51]
	v_mfma_f32_16x16x32_bf16 v[44:47], v[166:169], v[210:213], v[44:47]
	v_mfma_f32_16x16x32_bf16 v[40:43], v[146:149], v[218:221], v[40:43]
	v_mfma_f32_16x16x32_bf16 v[36:39], v[166:169], v[218:221], v[36:39]
	s_barrier
; #define G8_STAGE(bufoff, gbase, voff) do { _Pragma("unroll") for (int _i = 0; _i < 2; ++_i) \
;     __builtin_amdgcn_global_load_lds((const unsigned*)((const char*)(gbase) + (voff)[_i]), (LAS unsigned*)(lds + (bufoff) + ldsw + _i * 8192), 16, 0, 0); } while (0)
; #define G8_LDA(dst, b, h) do { _Pragma("unroll") for (int m = 0; m < 4; ++m) _Pragma("unroll") for (int k = 0; k < 2; ++k) dst[m][k] = *(const LAS bf16x8*)(lds + G8_SA(b, h) + aoff + m * 2048 + k * 1024); } while (0)
; #define G8_LDB(dst, b, h) do { _Pragma("unroll") for (int n = 0; n < 2; ++n) _Pragma("unroll") for (int k = 0; k < 2; ++k) dst[n][k] = *(const LAS bf16x8*)(lds + G8_SB(b, h) + boff + n * 2048 + k * 1024); } while (0)
; #define G8_MMA(ai, bj, At, Bt) do { __builtin_amdgcn_s_setprio(1); _Pragma("unroll") for (int m = 0; m < 4; ++m) _Pragma("unroll") for (int n = 0; n < 2; ++n) _Pragma("unroll") for (int k = 0; k < 2; ++k) \
;     acc[ai][bj][m][n] = __builtin_amdgcn_mfma_f32_16x16x32_bf16(Bt[n][k], At[m][k], acc[ai][bj][m][n], 0, 0, 0); __builtin_amdgcn_s_setprio(0); } while (0)
; #define G8_WAIT_V(n) asm volatile("s_waitcnt vmcnt(" #n ")" ::: "memory")
; #define G8_WAIT_L(n) asm volatile("s_waitcnt lgkmcnt(" #n ")" ::: "memory")
; #define G8_BAR __builtin_amdgcn_s_barrier()
; #define G8_SCHED __builtin_amdgcn_sched_barrier(0)
; template <class Epi, class Sched>
; __device__ __forceinline__ void gemm_phase(const int wv_, LAS unsigned char* lds, const int lda, const int ldb, const int K, const Sched& S, const Epi& E) {
;     ...
;       G8_STAGE(G8_SB(0, 1), b2 + hstepB, voffB);
;       G8_WAIT_V(6); G8_BAR; G8_MMA(1, 1, At, B1); G8_BAR;
;       G8_LDB(B0, 1, 0); G8_SCHED; G8_LDA(At, 1, 0); G8_STAGE(G8_SA(0, 1), a2 + hstepA, voffA);
;       G8_WAIT_L(8); G8_BAR; G8_WAIT_L(0); G8_MMA(0, 0, At, B0); G8_BAR; G8_SCHED;
;       G8_LDB(B1, 1, 1); G8_STAGE(G8_SB(1, 0), b3, voffB);
;       G8_BAR; G8_WAIT_L(0); G8_MMA(0, 1, At, B1); G8_BAR;
;       G8_LDA(At, 1, 1); G8_STAGE(G8_SA(1, 0), a3, voffA);
	s_add_u32 s70, s30, 0x20000
	s_addc_u32 s71, s31, 0
	s_add_i32 s23, s23, s43
	v_lshl_add_u64 v[142:143], s[70:71], 0, v[132:133]
	s_mov_b32 m0, s23
	s_nop 0
	global_load_lds_dwordx4 v[142:143], off
	v_lshl_add_u64 v[142:143], s[70:71], 0, v[136:137]
	s_add_i32 m0, s23, 0x2000
	s_nop 0
	global_load_lds_dwordx4 v[142:143], off
	s_waitcnt vmcnt(6)
	s_barrier
	v_mfma_f32_16x16x32_bf16 v[32:35], v[222:225], v[190:193], v[32:35]
	v_mfma_f32_16x16x32_bf16 v[28:31], v[230:233], v[190:193], v[28:31]
	v_mfma_f32_16x16x32_bf16 v[24:27], v[222:225], v[198:201], v[24:27]
	v_mfma_f32_16x16x32_bf16 v[20:23], v[230:233], v[198:201], v[20:23]
	v_mfma_f32_16x16x32_bf16 v[16:19], v[222:225], v[206:209], v[16:19]
	v_mfma_f32_16x16x32_bf16 v[12:15], v[230:233], v[206:209], v[12:15]
	v_mfma_f32_16x16x32_bf16 v[8:11], v[222:225], v[214:217], v[8:11]
	v_mfma_f32_16x16x32_bf16 v[4:7], v[230:233], v[214:217], v[4:7]
	v_mfma_f32_16x16x32_bf16 v[32:35], v[226:229], v[194:197], v[32:35]
	v_mfma_f32_16x16x32_bf16 v[28:31], v[234:237], v[194:197], v[28:31]
	v_mfma_f32_16x16x32_bf16 v[24:27], v[226:229], v[202:205], v[24:27]
	v_mfma_f32_16x16x32_bf16 v[20:23], v[234:237], v[202:205], v[20:23]
	v_mfma_f32_16x16x32_bf16 v[16:19], v[226:229], v[210:213], v[16:19]
	v_mfma_f32_16x16x32_bf16 v[12:15], v[234:237], v[210:213], v[12:15]
	v_mfma_f32_16x16x32_bf16 v[8:11], v[226:229], v[218:221], v[8:11]
	v_mfma_f32_16x16x32_bf16 v[4:7], v[234:237], v[218:221], v[4:7]
	s_add_i32 s23, 0, 0x18000
	v_add_u32_e32 v165, s23, v162
	s_barrier
	ds_read_b128 v[142:145], v165
	ds_read_b128 v[146:149], v165 offset:1024
	ds_read_b128 v[156:159], v165 offset:2048
	ds_read_b128 v[166:169], v165 offset:3072
	s_add_u32 s34, s34, 0x20000
	s_addc_u32 s35, s35, 0
	s_mov_b32 m0, s50
	v_lshl_add_u64 v[222:223], s[34:35], 0, v[0:1]
	ds_read_b128 v[190:193], v164 offset:32768
	ds_read_b128 v[194:197], v164 offset:33792
	ds_read_b128 v[198:201], v164 offset:34816
	ds_read_b128 v[202:205], v164 offset:35840
	ds_read_b128 v[206:209], v164 offset:36864
	ds_read_b128 v[210:213], v164 offset:37888
	ds_read_b128 v[214:217], v164 offset:38912
	ds_read_b128 v[218:221], v164 offset:39936
	global_load_lds_dwordx4 v[222:223], off
	v_lshl_add_u64 v[222:223], s[34:35], 0, v[134:135]
	s_mov_b32 m0, s51
	s_nop 0
	global_load_lds_dwordx4 v[222:223], off
	s_waitcnt lgkmcnt(8)
	s_barrier
	s_waitcnt lgkmcnt(0)
	v_mfma_f32_16x16x32_bf16 v[128:131], v[142:145], v[190:193], v[128:131]
	v_mfma_f32_16x16x32_bf16 v[124:127], v[156:159], v[190:193], v[124:127]
	v_mfma_f32_16x16x32_bf16 v[120:123], v[142:145], v[198:201], v[120:123]
	v_mfma_f32_16x16x32_bf16 v[116:119], v[156:159], v[198:201], v[116:119]
	v_mfma_f32_16x16x32_bf16 v[112:115], v[142:145], v[206:209], v[112:115]
	v_mfma_f32_16x16x32_bf16 v[108:111], v[156:159], v[206:209], v[108:111]
	v_mfma_f32_16x16x32_bf16 v[104:107], v[142:145], v[214:217], v[104:107]
	v_mfma_f32_16x16x32_bf16 v[100:103], v[156:159], v[214:217], v[100:103]
	v_mfma_f32_16x16x32_bf16 v[128:131], v[146:149], v[194:197], v[128:131]
	v_mfma_f32_16x16x32_bf16 v[124:127], v[166:169], v[194:197], v[124:127]
	v_mfma_f32_16x16x32_bf16 v[120:123], v[146:149], v[202:205], v[120:123]
	v_mfma_f32_16x16x32_bf16 v[116:119], v[166:169], v[202:205], v[116:119]
	v_mfma_f32_16x16x32_bf16 v[112:115], v[146:149], v[210:213], v[112:115]
	v_mfma_f32_16x16x32_bf16 v[108:111], v[166:169], v[210:213], v[108:111]
	v_mfma_f32_16x16x32_bf16 v[104:107], v[146:149], v[218:221], v[104:107]
	v_mfma_f32_16x16x32_bf16 v[100:103], v[166:169], v[218:221], v[100:103]
	s_barrier
	s_add_i32 s34, 0, 0x1c000
	s_add_i32 s23, s23, s43
	v_add_u32_e32 v165, s34, v162
	v_lshl_add_u64 v[150:151], v[150:151], 0, s[90:91]
	s_mov_b32 m0, s23
	ds_read_b128 v[222:225], v165
	ds_read_b128 v[226:229], v165 offset:1024
	ds_read_b128 v[230:233], v165 offset:2048
	ds_read_b128 v[234:237], v165 offset:3072
	global_load_lds_dwordx4 v[150:151], off
	v_lshl_add_u64 v[150:151], v[160:161], 0, s[90:91]
	s_add_i32 m0, s23, 0x2000
	s_nop 0
	global_load_lds_dwordx4 v[150:151], off
	s_barrier
	s_waitcnt lgkmcnt(0)
	v_mfma_f32_16x16x32_bf16 v[96:99], v[222:225], v[190:193], v[96:99]
	v_mfma_f32_16x16x32_bf16 v[92:95], v[230:233], v[190:193], v[92:95]
	v_mfma_f32_16x16x32_bf16 v[88:91], v[222:225], v[198:201], v[88:91]
	v_mfma_f32_16x16x32_bf16 v[84:87], v[230:233], v[198:201], v[84:87]
	v_mfma_f32_16x16x32_bf16 v[80:83], v[222:225], v[206:209], v[80:83]
	v_mfma_f32_16x16x32_bf16 v[76:79], v[230:233], v[206:209], v[76:79]
	v_mfma_f32_16x16x32_bf16 v[72:75], v[222:225], v[214:217], v[72:75]
	v_mfma_f32_16x16x32_bf16 v[68:71], v[230:233], v[214:217], v[68:71]
	v_mfma_f32_16x16x32_bf16 v[96:99], v[226:229], v[194:197], v[96:99]
	v_mfma_f32_16x16x32_bf16 v[92:95], v[234:237], v[194:197], v[92:95]
	v_mfma_f32_16x16x32_bf16 v[88:91], v[226:229], v[202:205], v[88:91]
	v_mfma_f32_16x16x32_bf16 v[84:87], v[234:237], v[202:205], v[84:87]
	v_mfma_f32_16x16x32_bf16 v[80:83], v[226:229], v[210:213], v[80:83]
	v_mfma_f32_16x16x32_bf16 v[76:79], v[234:237], v[210:213], v[76:79]
	v_mfma_f32_16x16x32_bf16 v[72:75], v[226:229], v[218:221], v[72:75]
	v_mfma_f32_16x16x32_bf16 v[68:71], v[234:237], v[218:221], v[68:71]
	s_mov_b32 m0, s56
	v_lshl_add_u64 v[150:151], v[238:239], 0, s[90:91]
	s_barrier
	ds_read_b128 v[190:193], v164 offset:49152
	ds_read_b128 v[194:197], v164 offset:50176
	ds_read_b128 v[198:201], v164 offset:51200
	ds_read_b128 v[202:205], v164 offset:52224
	ds_read_b128 v[206:209], v164 offset:53248
	ds_read_b128 v[210:213], v164 offset:54272
	ds_read_b128 v[214:217], v164 offset:55296
	ds_read_b128 v[218:221], v164 offset:56320
	global_load_lds_dwordx4 v[150:151], off
	v_lshl_add_u64 v[150:151], v[240:241], 0, s[90:91]
	s_mov_b32 m0, s57
	s_nop 0
	global_load_lds_dwordx4 v[150:151], off
	s_barrier
; __device__ __forceinline__ float lo16(unsigned u) { return __uint_as_float(u << 16); }
; __device__ __forceinline__ float hi16(unsigned u) { return __uint_as_float(u & 0xffff0000u); }
; #define G8_STAGE(bufoff, gbase, voff) do { _Pragma("unroll") for (int _i = 0; _i < 2; ++_i) \
;     __builtin_amdgcn_global_load_lds((const unsigned*)((const char*)(gbase) + (voff)[_i]), (LAS unsigned*)(lds + (bufoff) + ldsw + _i * 8192), 16, 0, 0); } while (0)
; #define G8_WAIT_V(n) asm volatile("s_waitcnt vmcnt(" #n ")" ::: "memory")
; #define G8_WAIT_L(n) asm volatile("s_waitcnt lgkmcnt(" #n ")" ::: "memory")
; #define G8_BAR __builtin_amdgcn_s_barrier()
; #define G8_SCHED __builtin_amdgcn_sched_barrier(0)
; template <class Epi, class Sched>
; __device__ __forceinline__ void gemm_phase(const int wv_, LAS unsigned char* lds, const int lda, const int ldb, const int K, const Sched& S, const Epi& E) {
;     ...
;       G8_BAR; G8_WAIT_L(0); G8_MMA(1, 0, At, B0); G8_BAR; G8_SCHED;
;       G8_STAGE(G8_SB(1, 1), b3 + hstepB, voffB);
;       G8_WAIT_V(6); G8_BAR; G8_MMA(1, 1, At, B1); G8_BAR;
;     }
;   __device__ __forceinline__ bool operator()(f32x4 (&acc)[2][2][4][2], const Unit& u, int wr, int wc, int fr, int fq) const {
;     const int row0 = u.pm * BM + wr * 64 + fr, col0 = u.pn * BM + wc * 32 + 8 * fq, j = u.j;
; #pragma unroll
;     for (int ai = 0; ai < 2; ++ai)
; #pragma unroll
;       for (int m = 0; m < 4; ++m) { const size_t row = (size_t)(row0 + ai * HALF + m * 16);
; #pragma unroll
;         for (int bj = 0; bj < 2; ++bj) {
;           const bf16_t* sp = pg + row * 8192 + (size_t)j * 2048 + col0 + bj * HALF;
;           const u32x4 sc = *(const u32x4*)sp;
;           float f[8] = {lo16(sc.x), hi16(sc.x), lo16(sc.y), hi16(sc.y), lo16(sc.z), hi16(sc.z), lo16(sc.w), hi16(sc.w)};
;           if (j < 3) { const u32x4 sn = *(const u32x4*)(sp + 2048);
;             float g[8] = {lo16(sn.x), hi16(sn.x), lo16(sn.y), hi16(sn.y), lo16(sn.z), hi16(sn.z), lo16(sn.w), hi16(sn.w)};
; #pragma unroll
;             for (int e = 0; e < 8; ++e) f[e] = f[e] * __builtin_amdgcn_rcpf(fmaxf(g[e], 1e-30f)); }
;           f32x4 v0 = acc[ai][bj][m][0], v1 = acc[ai][bj][m][1];
; #pragma unroll
;           for (int e = 0; e < 4; ++e) { v0[e] *= f[e]; v1[e] *= f[4 + e]; }
;           acc[ai][bj][m][0] = v0; acc[ai][bj][m][1] = v1;
	s_waitcnt lgkmcnt(0)
	v_mfma_f32_16x16x32_bf16 v[64:67], v[142:145], v[190:193], v[64:67]
	v_mfma_f32_16x16x32_bf16 v[60:63], v[156:159], v[190:193], v[60:63]
	v_mfma_f32_16x16x32_bf16 v[56:59], v[142:145], v[198:201], v[56:59]
	v_mfma_f32_16x16x32_bf16 v[52:55], v[156:159], v[198:201], v[52:55]
	v_mfma_f32_16x16x32_bf16 v[48:51], v[142:145], v[206:209], v[48:51]
	v_mfma_f32_16x16x32_bf16 v[44:47], v[156:159], v[206:209], v[44:47]
	v_mfma_f32_16x16x32_bf16 v[40:43], v[142:145], v[214:217], v[40:43]
	v_mfma_f32_16x16x32_bf16 v[36:39], v[156:159], v[214:217], v[36:39]
	v_mfma_f32_16x16x32_bf16 v[64:67], v[146:149], v[194:197], v[64:67]
	v_mfma_f32_16x16x32_bf16 v[60:63], v[166:169], v[194:197], v[60:63]
	v_mfma_f32_16x16x32_bf16 v[56:59], v[146:149], v[202:205], v[56:59]
	v_mfma_f32_16x16x32_bf16 v[52:55], v[166:169], v[202:205], v[52:55]
	v_mfma_f32_16x16x32_bf16 v[48:51], v[146:149], v[210:213], v[48:51]
	v_mfma_f32_16x16x32_bf16 v[44:47], v[166:169], v[210:213], v[44:47]
	v_mfma_f32_16x16x32_bf16 v[40:43], v[146:149], v[218:221], v[40:43]
	v_mfma_f32_16x16x32_bf16 v[36:39], v[166:169], v[218:221], v[36:39]
	s_barrier
	s_add_u32 s30, s30, 0x20080
	s_addc_u32 s31, s31, 0
	s_add_i32 s23, s34, s43
	v_lshl_add_u64 v[142:143], s[30:31], 0, v[132:133]
	s_mov_b32 m0, s23
	s_nop 0
	global_load_lds_dwordx4 v[142:143], off
	v_lshl_add_u64 v[142:143], s[30:31], 0, v[136:137]
	s_add_i32 m0, s23, 0x2000
	s_nop 0
	global_load_lds_dwordx4 v[142:143], off
	s_waitcnt vmcnt(6)
	s_barrier
	v_mfma_f32_16x16x32_bf16 v[32:35], v[222:225], v[190:193], v[32:35]
	v_mfma_f32_16x16x32_bf16 v[28:31], v[230:233], v[190:193], v[28:31]
	v_mfma_f32_16x16x32_bf16 v[24:27], v[222:225], v[198:201], v[24:27]
	v_mfma_f32_16x16x32_bf16 v[20:23], v[230:233], v[198:201], v[20:23]
	v_mfma_f32_16x16x32_bf16 v[16:19], v[222:225], v[206:209], v[16:19]
	v_mfma_f32_16x16x32_bf16 v[12:15], v[230:233], v[206:209], v[12:15]
	v_mfma_f32_16x16x32_bf16 v[8:11], v[222:225], v[214:217], v[8:11]
	v_mfma_f32_16x16x32_bf16 v[4:7], v[230:233], v[214:217], v[4:7]
	v_mfma_f32_16x16x32_bf16 v[32:35], v[226:229], v[194:197], v[32:35]
	v_mfma_f32_16x16x32_bf16 v[28:31], v[234:237], v[194:197], v[28:31]
	v_mfma_f32_16x16x32_bf16 v[24:27], v[226:229], v[202:205], v[24:27]
	v_mfma_f32_16x16x32_bf16 v[20:23], v[234:237], v[202:205], v[20:23]
	v_mfma_f32_16x16x32_bf16 v[16:19], v[226:229], v[210:213], v[16:19]
	v_mfma_f32_16x16x32_bf16 v[12:15], v[234:237], v[210:213], v[12:15]
	v_mfma_f32_16x16x32_bf16 v[8:11], v[226:229], v[218:221], v[8:11]
	v_mfma_f32_16x16x32_bf16 v[4:7], v[234:237], v[218:221], v[4:7]
	s_add_i32 s21, s21, 2
	s_add_u32 s28, s28, 0x100
	s_addc_u32 s29, s29, 0
	s_add_u32 s11, s11, 0x100
	s_addc_u32 s13, s13, 0
	s_cmp_gt_u32 s21, 5
	s_barrier
	s_cbranch_scc0 .LBB0_812
	s_setprio 0
	s_lshl_b32 s11, s12, 22
	s_lshl_b32 s13, s10, 12
	s_add_u32 s30, s16, s11
	s_addc_u32 s31, s17, 0
	s_add_u32 s30, s30, s13
	s_addc_u32 s31, s31, 0
	s_lshl_b32 s13, s68, 9
	s_add_u32 s30, s30, s13
	s_addc_u32 s31, s31, 0
	v_lshlrev_b32_e32 v165, 1, v163
	v_lshl_add_u32 v160, v3, 14, v165
	v_mov_b32_e32 v161, 0
	v_lshl_add_u64 v[160:161], v[160:161], 0, s[30:31]
	s_mov_b32 s28, 0x40000
	s_mov_b32 s29, 0
	s_cmp_eq_u32 s10, 3
	s_cbranch_scc1 .Lg2e_eq3
	s_mov_b64 s[34:35], 0x1000
	v_lshl_add_u64 v[150:151], v[160:161], 0, s[34:35]
	global_load_dwordx4 v[190:193], v[160:161], off
	global_load_dwordx4 v[194:197], v[150:151], off
	global_load_dwordx4 v[198:201], v[160:161], off offset:256
	global_load_dwordx4 v[202:205], v[150:151], off offset:256
	v_lshl_add_u64 v[160:161], v[160:161], 0, s[28:29]
	v_lshl_add_u64 v[150:151], v[150:151], 0, s[28:29]
	global_load_dwordx4 v[206:209], v[160:161], off
	global_load_dwordx4 v[210:213], v[150:151], off
	global_load_dwordx4 v[214:217], v[160:161], off offset:256
	global_load_dwordx4 v[218:221], v[150:151], off offset:256
	v_lshl_add_u64 v[160:161], v[160:161], 0, s[28:29]
	v_lshl_add_u64 v[150:151], v[150:151], 0, s[28:29]
	global_load_dwordx4 v[222:225], v[160:161], off
	global_load_dwordx4 v[226:229], v[150:151], off
	global_load_dwordx4 v[230:233], v[160:161], off offset:256
	global_load_dwordx4 v[234:237], v[150:151], off offset:256
	v_lshl_add_u64 v[160:161], v[160:161], 0, s[28:29]
	v_lshl_add_u64 v[150:151], v[150:151], 0, s[28:29]
	global_load_dwordx4 v[238:241], v[160:161], off
	global_load_dwordx4 v[142:145], v[150:151], off
	global_load_dwordx4 v[146:149], v[160:161], off offset:256
	global_load_dwordx4 v[156:159], v[150:151], off offset:256
	s_mov_b32 s28, 0x140000
	v_lshl_add_u64 v[160:161], v[160:161], 0, s[28:29]
	s_mov_b32 s28, 0x40000
	s_mov_b32 s28, 0x140000
	v_lshl_add_u64 v[150:151], v[150:151], 0, s[28:29]
	s_mov_b32 s28, 0x40000
	s_waitcnt vmcnt(14)
	v_lshlrev_b32_e32 v168, 16, v194
	v_and_b32_e32 v169, 0xffff0000, v194
	v_max_f32_e32 v168, 0xda24260, v168
	v_max_f32_e32 v169, 0xda24260, v169
	v_rcp_f32_e32 v168, v168
	v_rcp_f32_e32 v169, v169
	v_lshlrev_b32_e32 v166, 16, v190
	v_and_b32_e32 v167, 0xffff0000, v190
	v_pk_mul_f32 v[166:167], v[168:169], v[166:167]
	v_pk_mul_f32 v[128:129], v[128:129], v[166:167]
	v_lshlrev_b32_e32 v168, 16, v195
	v_and_b32_e32 v169, 0xffff0000, v195
	v_max_f32_e32 v168, 0xda24260, v168
	v_max_f32_e32 v169, 0xda24260, v169
	v_rcp_f32_e32 v168, v168
	v_rcp_f32_e32 v169, v169
	v_lshlrev_b32_e32 v166, 16, v191
	v_and_b32_e32 v167, 0xffff0000, v191
	v_pk_mul_f32 v[166:167], v[168:169], v[166:167]
	v_pk_mul_f32 v[130:131], v[130:131], v[166:167]
	v_lshlrev_b32_e32 v168, 16, v196
	v_and_b32_e32 v169, 0xffff0000, v196
	v_max_f32_e32 v168, 0xda24260, v168
	v_max_f32_e32 v169, 0xda24260, v169
	v_rcp_f32_e32 v168, v168
	v_rcp_f32_e32 v169, v169
	v_lshlrev_b32_e32 v166, 16, v192
	v_and_b32_e32 v167, 0xffff0000, v192
	v_pk_mul_f32 v[166:167], v[168:169], v[166:167]
	v_pk_mul_f32 v[124:125], v[124:125], v[166:167]
	v_lshlrev_b32_e32 v168, 16, v197
	v_and_b32_e32 v169, 0xffff0000, v197
	v_max_f32_e32 v168, 0xda24260, v168
	v_max_f32_e32 v169, 0xda24260, v169
	v_rcp_f32_e32 v168, v168
	v_rcp_f32_e32 v169, v169
	v_lshlrev_b32_e32 v166, 16, v193
	v_and_b32_e32 v167, 0xffff0000, v193
	v_pk_mul_f32 v[166:167], v[168:169], v[166:167]
	v_pk_mul_f32 v[126:127], v[126:127], v[166:167]
	global_load_dwordx4 v[190:193], v[160:161], off
	global_load_dwordx4 v[194:197], v[150:151], off
	s_waitcnt vmcnt(14)
; __device__ __forceinline__ float lo16(unsigned u) { return __uint_as_float(u << 16); }
; __device__ __forceinline__ float hi16(unsigned u) { return __uint_as_float(u & 0xffff0000u); }
;   __device__ __forceinline__ bool operator()(f32x4 (&acc)[2][2][4][2], const Unit& u, int wr, int wc, int fr, int fq) const {
;     ...
;           const bf16_t* sp = pg + row * 8192 + (size_t)j * 2048 + col0 + bj * HALF;
;           const u32x4 sc = *(const u32x4*)sp;
;           float f[8] = {lo16(sc.x), hi16(sc.x), lo16(sc.y), hi16(sc.y), lo16(sc.z), hi16(sc.z), lo16(sc.w), hi16(sc.w)};
;           if (j < 3) { const u32x4 sn = *(const u32x4*)(sp + 2048);
;             float g[8] = {lo16(sn.x), hi16(sn.x), lo16(sn.y), hi16(sn.y), lo16(sn.z), hi16(sn.z), lo16(sn.w), hi16(sn.w)};
; #pragma unroll
;             for (int e = 0; e < 8; ++e) f[e] = f[e] * __builtin_amdgcn_rcpf(fmaxf(g[e], 1e-30f)); }
;           f32x4 v0 = acc[ai][bj][m][0], v1 = acc[ai][bj][m][1];
; #pragma unroll
;           for (int e = 0; e < 4; ++e) { v0[e] *= f[e]; v1[e] *= f[4 + e]; }
;           acc[ai][bj][m][0] = v0; acc[ai][bj][m][1] = v1;
	v_lshlrev_b32_e32 v168, 16, v202
	v_and_b32_e32 v169, 0xffff0000, v202
	v_max_f32_e32 v168, 0xda24260, v168
	v_max_f32_e32 v169, 0xda24260, v169
	v_rcp_f32_e32 v168, v168
	v_rcp_f32_e32 v169, v169
	v_lshlrev_b32_e32 v166, 16, v198
	v_and_b32_e32 v167, 0xffff0000, v198
	v_pk_mul_f32 v[166:167], v[168:169], v[166:167]
	v_pk_mul_f32 v[96:97], v[96:97], v[166:167]
	v_lshlrev_b32_e32 v168, 16, v203
	v_and_b32_e32 v169, 0xffff0000, v203
	v_max_f32_e32 v168, 0xda24260, v168
	v_max_f32_e32 v169, 0xda24260, v169
	v_rcp_f32_e32 v168, v168
	v_rcp_f32_e32 v169, v169
	v_lshlrev_b32_e32 v166, 16, v199
	v_and_b32_e32 v167, 0xffff0000, v199
	v_pk_mul_f32 v[166:167], v[168:169], v[166:167]
	v_pk_mul_f32 v[98:99], v[98:99], v[166:167]
	v_lshlrev_b32_e32 v168, 16, v204
	v_and_b32_e32 v169, 0xffff0000, v204
	v_max_f32_e32 v168, 0xda24260, v168
	v_max_f32_e32 v169, 0xda24260, v169
	v_rcp_f32_e32 v168, v168
	v_rcp_f32_e32 v169, v169
	v_lshlrev_b32_e32 v166, 16, v200
	v_and_b32_e32 v167, 0xffff0000, v200
	v_pk_mul_f32 v[166:167], v[168:169], v[166:167]
	v_pk_mul_f32 v[92:93], v[92:93], v[166:167]
	v_lshlrev_b32_e32 v168, 16, v205
	v_and_b32_e32 v169, 0xffff0000, v205
	v_max_f32_e32 v168, 0xda24260, v168
	v_max_f32_e32 v169, 0xda24260, v169
	v_rcp_f32_e32 v168, v168
	v_rcp_f32_e32 v169, v169
	v_lshlrev_b32_e32 v166, 16, v201
	v_and_b32_e32 v167, 0xffff0000, v201
	v_pk_mul_f32 v[166:167], v[168:169], v[166:167]
	v_pk_mul_f32 v[94:95], v[94:95], v[166:167]
	global_load_dwordx4 v[198:201], v[160:161], off offset:256
	global_load_dwordx4 v[202:205], v[150:151], off offset:256
	v_lshl_add_u64 v[160:161], v[160:161], 0, s[28:29]
	v_lshl_add_u64 v[150:151], v[150:151], 0, s[28:29]
	s_waitcnt vmcnt(14)
	v_lshlrev_b32_e32 v168, 16, v210
	v_and_b32_e32 v169, 0xffff0000, v210
	v_max_f32_e32 v168, 0xda24260, v168
	v_max_f32_e32 v169, 0xda24260, v169
	v_rcp_f32_e32 v168, v168
	v_rcp_f32_e32 v169, v169
	v_lshlrev_b32_e32 v166, 16, v206
	v_and_b32_e32 v167, 0xffff0000, v206
	v_pk_mul_f32 v[166:167], v[168:169], v[166:167]
	v_pk_mul_f32 v[120:121], v[120:121], v[166:167]
	v_lshlrev_b32_e32 v168, 16, v211
	v_and_b32_e32 v169, 0xffff0000, v211
	v_max_f32_e32 v168, 0xda24260, v168
	v_max_f32_e32 v169, 0xda24260, v169
	v_rcp_f32_e32 v168, v168
	v_rcp_f32_e32 v169, v169
	v_lshlrev_b32_e32 v166, 16, v207
	v_and_b32_e32 v167, 0xffff0000, v207
	v_pk_mul_f32 v[166:167], v[168:169], v[166:167]
	v_pk_mul_f32 v[122:123], v[122:123], v[166:167]
	v_lshlrev_b32_e32 v168, 16, v212
	v_and_b32_e32 v169, 0xffff0000, v212
	v_max_f32_e32 v168, 0xda24260, v168
	v_max_f32_e32 v169, 0xda24260, v169
	v_rcp_f32_e32 v168, v168
	v_rcp_f32_e32 v169, v169
	v_lshlrev_b32_e32 v166, 16, v208
	v_and_b32_e32 v167, 0xffff0000, v208
	v_pk_mul_f32 v[166:167], v[168:169], v[166:167]
	v_pk_mul_f32 v[116:117], v[116:117], v[166:167]
	v_lshlrev_b32_e32 v168, 16, v213
	v_and_b32_e32 v169, 0xffff0000, v213
	v_max_f32_e32 v168, 0xda24260, v168
	v_max_f32_e32 v169, 0xda24260, v169
	v_rcp_f32_e32 v168, v168
	v_rcp_f32_e32 v169, v169
	v_lshlrev_b32_e32 v166, 16, v209
	v_and_b32_e32 v167, 0xffff0000, v209
	v_pk_mul_f32 v[166:167], v[168:169], v[166:167]
	v_pk_mul_f32 v[118:119], v[118:119], v[166:167]
	global_load_dwordx4 v[206:209], v[160:161], off
	global_load_dwordx4 v[210:213], v[150:151], off
	s_waitcnt vmcnt(14)
	v_lshlrev_b32_e32 v168, 16, v218
	v_and_b32_e32 v169, 0xffff0000, v218
	v_max_f32_e32 v168, 0xda24260, v168
	v_max_f32_e32 v169, 0xda24260, v169
	v_rcp_f32_e32 v168, v168
	v_rcp_f32_e32 v169, v169
	v_lshlrev_b32_e32 v166, 16, v214
	v_and_b32_e32 v167, 0xffff0000, v214
	v_pk_mul_f32 v[166:167], v[168:169], v[166:167]
	v_pk_mul_f32 v[88:89], v[88:89], v[166:167]
	v_lshlrev_b32_e32 v168, 16, v219
	v_and_b32_e32 v169, 0xffff0000, v219
	v_max_f32_e32 v168, 0xda24260, v168
	v_max_f32_e32 v169, 0xda24260, v169
	v_rcp_f32_e32 v168, v168
	v_rcp_f32_e32 v169, v169
	v_lshlrev_b32_e32 v166, 16, v215
	v_and_b32_e32 v167, 0xffff0000, v215
	v_pk_mul_f32 v[166:167], v[168:169], v[166:167]
	v_pk_mul_f32 v[90:91], v[90:91], v[166:167]
	v_lshlrev_b32_e32 v168, 16, v220
	v_and_b32_e32 v169, 0xffff0000, v220
	v_max_f32_e32 v168, 0xda24260, v168
	v_max_f32_e32 v169, 0xda24260, v169
	v_rcp_f32_e32 v168, v168
	v_rcp_f32_e32 v169, v169
	v_lshlrev_b32_e32 v166, 16, v216
	v_and_b32_e32 v167, 0xffff0000, v216
	v_pk_mul_f32 v[166:167], v[168:169], v[166:167]
	v_pk_mul_f32 v[84:85], v[84:85], v[166:167]
	v_lshlrev_b32_e32 v168, 16, v221
	v_and_b32_e32 v169, 0xffff0000, v221
	v_max_f32_e32 v168, 0xda24260, v168
	v_max_f32_e32 v169, 0xda24260, v169
	v_rcp_f32_e32 v168, v168
	v_rcp_f32_e32 v169, v169
	v_lshlrev_b32_e32 v166, 16, v217
	v_and_b32_e32 v167, 0xffff0000, v217
	v_pk_mul_f32 v[166:167], v[168:169], v[166:167]
	v_pk_mul_f32 v[86:87], v[86:87], v[166:167]
	global_load_dwordx4 v[214:217], v[160:161], off offset:256
	global_load_dwordx4 v[218:221], v[150:151], off offset:256
	v_lshl_add_u64 v[160:161], v[160:161], 0, s[28:29]
	v_lshl_add_u64 v[150:151], v[150:151], 0, s[28:29]
	s_waitcnt vmcnt(14)
; __device__ __forceinline__ float lo16(unsigned u) { return __uint_as_float(u << 16); }
; __device__ __forceinline__ float hi16(unsigned u) { return __uint_as_float(u & 0xffff0000u); }
;   __device__ __forceinline__ bool operator()(f32x4 (&acc)[2][2][4][2], const Unit& u, int wr, int wc, int fr, int fq) const {
;     ...
;           const bf16_t* sp = pg + row * 8192 + (size_t)j * 2048 + col0 + bj * HALF;
;           const u32x4 sc = *(const u32x4*)sp;
;           float f[8] = {lo16(sc.x), hi16(sc.x), lo16(sc.y), hi16(sc.y), lo16(sc.z), hi16(sc.z), lo16(sc.w), hi16(sc.w)};
;           if (j < 3) { const u32x4 sn = *(const u32x4*)(sp + 2048);
;             float g[8] = {lo16(sn.x), hi16(sn.x), lo16(sn.y), hi16(sn.y), lo16(sn.z), hi16(sn.z), lo16(sn.w), hi16(sn.w)};
; #pragma unroll
;             for (int e = 0; e < 8; ++e) f[e] = f[e] * __builtin_amdgcn_rcpf(fmaxf(g[e], 1e-30f)); }
;           f32x4 v0 = acc[ai][bj][m][0], v1 = acc[ai][bj][m][1];
; #pragma unroll
;           for (int e = 0; e < 4; ++e) { v0[e] *= f[e]; v1[e] *= f[4 + e]; }
;           acc[ai][bj][m][0] = v0; acc[ai][bj][m][1] = v1;
	v_lshlrev_b32_e32 v168, 16, v226
	v_and_b32_e32 v169, 0xffff0000, v226
	v_max_f32_e32 v168, 0xda24260, v168
	v_max_f32_e32 v169, 0xda24260, v169
	v_rcp_f32_e32 v168, v168
	v_rcp_f32_e32 v169, v169
	v_lshlrev_b32_e32 v166, 16, v222
	v_and_b32_e32 v167, 0xffff0000, v222
	v_pk_mul_f32 v[166:167], v[168:169], v[166:167]
	v_pk_mul_f32 v[112:113], v[112:113], v[166:167]
	v_lshlrev_b32_e32 v168, 16, v227
	v_and_b32_e32 v169, 0xffff0000, v227
	v_max_f32_e32 v168, 0xda24260, v168
	v_max_f32_e32 v169, 0xda24260, v169
	v_rcp_f32_e32 v168, v168
	v_rcp_f32_e32 v169, v169
	v_lshlrev_b32_e32 v166, 16, v223
	v_and_b32_e32 v167, 0xffff0000, v223
	v_pk_mul_f32 v[166:167], v[168:169], v[166:167]
	v_pk_mul_f32 v[114:115], v[114:115], v[166:167]
	v_lshlrev_b32_e32 v168, 16, v228
	v_and_b32_e32 v169, 0xffff0000, v228
	v_max_f32_e32 v168, 0xda24260, v168
	v_max_f32_e32 v169, 0xda24260, v169
	v_rcp_f32_e32 v168, v168
	v_rcp_f32_e32 v169, v169
	v_lshlrev_b32_e32 v166, 16, v224
	v_and_b32_e32 v167, 0xffff0000, v224
	v_pk_mul_f32 v[166:167], v[168:169], v[166:167]
	v_pk_mul_f32 v[108:109], v[108:109], v[166:167]
	v_lshlrev_b32_e32 v168, 16, v229
	v_and_b32_e32 v169, 0xffff0000, v229
	v_max_f32_e32 v168, 0xda24260, v168
	v_max_f32_e32 v169, 0xda24260, v169
	v_rcp_f32_e32 v168, v168
	v_rcp_f32_e32 v169, v169
	v_lshlrev_b32_e32 v166, 16, v225
	v_and_b32_e32 v167, 0xffff0000, v225
	v_pk_mul_f32 v[166:167], v[168:169], v[166:167]
	v_pk_mul_f32 v[110:111], v[110:111], v[166:167]
	global_load_dwordx4 v[222:225], v[160:161], off
	global_load_dwordx4 v[226:229], v[150:151], off
	s_waitcnt vmcnt(14)
	v_lshlrev_b32_e32 v168, 16, v234
	v_and_b32_e32 v169, 0xffff0000, v234
	v_max_f32_e32 v168, 0xda24260, v168
	v_max_f32_e32 v169, 0xda24260, v169
	v_rcp_f32_e32 v168, v168
	v_rcp_f32_e32 v169, v169
	v_lshlrev_b32_e32 v166, 16, v230
	v_and_b32_e32 v167, 0xffff0000, v230
	v_pk_mul_f32 v[166:167], v[168:169], v[166:167]
	v_pk_mul_f32 v[80:81], v[80:81], v[166:167]
	v_lshlrev_b32_e32 v168, 16, v235
	v_and_b32_e32 v169, 0xffff0000, v235
	v_max_f32_e32 v168, 0xda24260, v168
	v_max_f32_e32 v169, 0xda24260, v169
	v_rcp_f32_e32 v168, v168
	v_rcp_f32_e32 v169, v169
	v_lshlrev_b32_e32 v166, 16, v231
	v_and_b32_e32 v167, 0xffff0000, v231
	v_pk_mul_f32 v[166:167], v[168:169], v[166:167]
	v_pk_mul_f32 v[82:83], v[82:83], v[166:167]
	v_lshlrev_b32_e32 v168, 16, v236
	v_and_b32_e32 v169, 0xffff0000, v236
	v_max_f32_e32 v168, 0xda24260, v168
	v_max_f32_e32 v169, 0xda24260, v169
	v_rcp_f32_e32 v168, v168
	v_rcp_f32_e32 v169, v169
	v_lshlrev_b32_e32 v166, 16, v232
	v_and_b32_e32 v167, 0xffff0000, v232
	v_pk_mul_f32 v[166:167], v[168:169], v[166:167]
	v_pk_mul_f32 v[76:77], v[76:77], v[166:167]
	v_lshlrev_b32_e32 v168, 16, v237
	v_and_b32_e32 v169, 0xffff0000, v237
	v_max_f32_e32 v168, 0xda24260, v168
	v_max_f32_e32 v169, 0xda24260, v169
	v_rcp_f32_e32 v168, v168
	v_rcp_f32_e32 v169, v169
	v_lshlrev_b32_e32 v166, 16, v233
	v_and_b32_e32 v167, 0xffff0000, v233
	v_pk_mul_f32 v[166:167], v[168:169], v[166:167]
	v_pk_mul_f32 v[78:79], v[78:79], v[166:167]
	global_load_dwordx4 v[230:233], v[160:161], off offset:256
	global_load_dwordx4 v[234:237], v[150:151], off offset:256
	v_lshl_add_u64 v[160:161], v[160:161], 0, s[28:29]
	v_lshl_add_u64 v[150:151], v[150:151], 0, s[28:29]
	s_waitcnt vmcnt(14)
	v_lshlrev_b32_e32 v168, 16, v142
	v_and_b32_e32 v169, 0xffff0000, v142
	v_max_f32_e32 v168, 0xda24260, v168
	v_max_f32_e32 v169, 0xda24260, v169
	v_rcp_f32_e32 v168, v168
	v_rcp_f32_e32 v169, v169
	v_lshlrev_b32_e32 v166, 16, v238
	v_and_b32_e32 v167, 0xffff0000, v238
	v_pk_mul_f32 v[166:167], v[168:169], v[166:167]
	v_pk_mul_f32 v[104:105], v[104:105], v[166:167]
	v_lshlrev_b32_e32 v168, 16, v143
	v_and_b32_e32 v169, 0xffff0000, v143
	v_max_f32_e32 v168, 0xda24260, v168
	v_max_f32_e32 v169, 0xda24260, v169
	v_rcp_f32_e32 v168, v168
	v_rcp_f32_e32 v169, v169
	v_lshlrev_b32_e32 v166, 16, v239
	v_and_b32_e32 v167, 0xffff0000, v239
	v_pk_mul_f32 v[166:167], v[168:169], v[166:167]
	v_pk_mul_f32 v[106:107], v[106:107], v[166:167]
	v_lshlrev_b32_e32 v168, 16, v144
	v_and_b32_e32 v169, 0xffff0000, v144
	v_max_f32_e32 v168, 0xda24260, v168
	v_max_f32_e32 v169, 0xda24260, v169
	v_rcp_f32_e32 v168, v168
	v_rcp_f32_e32 v169, v169
	v_lshlrev_b32_e32 v166, 16, v240
	v_and_b32_e32 v167, 0xffff0000, v240
	v_pk_mul_f32 v[166:167], v[168:169], v[166:167]
	v_pk_mul_f32 v[100:101], v[100:101], v[166:167]
	v_lshlrev_b32_e32 v168, 16, v145
	v_and_b32_e32 v169, 0xffff0000, v145
	v_max_f32_e32 v168, 0xda24260, v168
	v_max_f32_e32 v169, 0xda24260, v169
	v_rcp_f32_e32 v168, v168
	v_rcp_f32_e32 v169, v169
	v_lshlrev_b32_e32 v166, 16, v241
	v_and_b32_e32 v167, 0xffff0000, v241
	v_pk_mul_f32 v[166:167], v[168:169], v[166:167]
	v_pk_mul_f32 v[102:103], v[102:103], v[166:167]
	global_load_dwordx4 v[238:241], v[160:161], off
	global_load_dwordx4 v[142:145], v[150:151], off
	s_waitcnt vmcnt(14)
; __device__ __forceinline__ float lo16(unsigned u) { return __uint_as_float(u << 16); }
; __device__ __forceinline__ float hi16(unsigned u) { return __uint_as_float(u & 0xffff0000u); }
;   __device__ __forceinline__ bool operator()(f32x4 (&acc)[2][2][4][2], const Unit& u, int wr, int wc, int fr, int fq) const {
;     ...
;           const bf16_t* sp = pg + row * 8192 + (size_t)j * 2048 + col0 + bj * HALF;
;           const u32x4 sc = *(const u32x4*)sp;
;           float f[8] = {lo16(sc.x), hi16(sc.x), lo16(sc.y), hi16(sc.y), lo16(sc.z), hi16(sc.z), lo16(sc.w), hi16(sc.w)};
;           if (j < 3) { const u32x4 sn = *(const u32x4*)(sp + 2048);
;             float g[8] = {lo16(sn.x), hi16(sn.x), lo16(sn.y), hi16(sn.y), lo16(sn.z), hi16(sn.z), lo16(sn.w), hi16(sn.w)};
; #pragma unroll
;             for (int e = 0; e < 8; ++e) f[e] = f[e] * __builtin_amdgcn_rcpf(fmaxf(g[e], 1e-30f)); }
;           f32x4 v0 = acc[ai][bj][m][0], v1 = acc[ai][bj][m][1];
; #pragma unroll
;           for (int e = 0; e < 4; ++e) { v0[e] *= f[e]; v1[e] *= f[4 + e]; }
;           acc[ai][bj][m][0] = v0; acc[ai][bj][m][1] = v1;
	v_lshlrev_b32_e32 v168, 16, v156
	v_and_b32_e32 v169, 0xffff0000, v156
	v_max_f32_e32 v168, 0xda24260, v168
	v_max_f32_e32 v169, 0xda24260, v169
	v_rcp_f32_e32 v168, v168
	v_rcp_f32_e32 v169, v169
	v_lshlrev_b32_e32 v166, 16, v146
	v_and_b32_e32 v167, 0xffff0000, v146
	v_pk_mul_f32 v[166:167], v[168:169], v[166:167]
	v_pk_mul_f32 v[72:73], v[72:73], v[166:167]
	v_lshlrev_b32_e32 v168, 16, v157
	v_and_b32_e32 v169, 0xffff0000, v157
	v_max_f32_e32 v168, 0xda24260, v168
	v_max_f32_e32 v169, 0xda24260, v169
	v_rcp_f32_e32 v168, v168
	v_rcp_f32_e32 v169, v169
	v_lshlrev_b32_e32 v166, 16, v147
	v_and_b32_e32 v167, 0xffff0000, v147
	v_pk_mul_f32 v[166:167], v[168:169], v[166:167]
	v_pk_mul_f32 v[74:75], v[74:75], v[166:167]
	v_lshlrev_b32_e32 v168, 16, v158
	v_and_b32_e32 v169, 0xffff0000, v158
	v_max_f32_e32 v168, 0xda24260, v168
	v_max_f32_e32 v169, 0xda24260, v169
	v_rcp_f32_e32 v168, v168
	v_rcp_f32_e32 v169, v169
	v_lshlrev_b32_e32 v166, 16, v148
	v_and_b32_e32 v167, 0xffff0000, v148
	v_pk_mul_f32 v[166:167], v[168:169], v[166:167]
	v_pk_mul_f32 v[68:69], v[68:69], v[166:167]
	v_lshlrev_b32_e32 v168, 16, v159
	v_and_b32_e32 v169, 0xffff0000, v159
	v_max_f32_e32 v168, 0xda24260, v168
	v_max_f32_e32 v169, 0xda24260, v169
	v_rcp_f32_e32 v168, v168
	v_rcp_f32_e32 v169, v169
	v_lshlrev_b32_e32 v166, 16, v149
	v_and_b32_e32 v167, 0xffff0000, v149
	v_pk_mul_f32 v[166:167], v[168:169], v[166:167]
	v_pk_mul_f32 v[70:71], v[70:71], v[166:167]
	global_load_dwordx4 v[146:149], v[160:161], off offset:256
	global_load_dwordx4 v[156:159], v[150:151], off offset:256
	s_waitcnt vmcnt(14)
	v_lshlrev_b32_e32 v168, 16, v194
	v_and_b32_e32 v169, 0xffff0000, v194
	v_max_f32_e32 v168, 0xda24260, v168
	v_max_f32_e32 v169, 0xda24260, v169
	v_rcp_f32_e32 v168, v168
	v_rcp_f32_e32 v169, v169
	v_lshlrev_b32_e32 v166, 16, v190
	v_and_b32_e32 v167, 0xffff0000, v190
	v_pk_mul_f32 v[166:167], v[168:169], v[166:167]
	v_pk_mul_f32 v[64:65], v[64:65], v[166:167]
	v_lshlrev_b32_e32 v168, 16, v195
	v_and_b32_e32 v169, 0xffff0000, v195
	v_max_f32_e32 v168, 0xda24260, v168
	v_max_f32_e32 v169, 0xda24260, v169
	v_rcp_f32_e32 v168, v168
	v_rcp_f32_e32 v169, v169
	v_lshlrev_b32_e32 v166, 16, v191
	v_and_b32_e32 v167, 0xffff0000, v191
	v_pk_mul_f32 v[166:167], v[168:169], v[166:167]
	v_pk_mul_f32 v[66:67], v[66:67], v[166:167]
	v_lshlrev_b32_e32 v168, 16, v196
	v_and_b32_e32 v169, 0xffff0000, v196
	v_max_f32_e32 v168, 0xda24260, v168
	v_max_f32_e32 v169, 0xda24260, v169
	v_rcp_f32_e32 v168, v168
	v_rcp_f32_e32 v169, v169
	v_lshlrev_b32_e32 v166, 16, v192
	v_and_b32_e32 v167, 0xffff0000, v192
	v_pk_mul_f32 v[166:167], v[168:169], v[166:167]
	v_pk_mul_f32 v[60:61], v[60:61], v[166:167]
	v_lshlrev_b32_e32 v168, 16, v197
	v_and_b32_e32 v169, 0xffff0000, v197
	v_max_f32_e32 v168, 0xda24260, v168
	v_max_f32_e32 v169, 0xda24260, v169
	v_rcp_f32_e32 v168, v168
	v_rcp_f32_e32 v169, v169
	v_lshlrev_b32_e32 v166, 16, v193
	v_and_b32_e32 v167, 0xffff0000, v193
	v_pk_mul_f32 v[166:167], v[168:169], v[166:167]
	v_pk_mul_f32 v[62:63], v[62:63], v[166:167]
	s_waitcnt vmcnt(12)
	v_lshlrev_b32_e32 v168, 16, v202
	v_and_b32_e32 v169, 0xffff0000, v202
	v_max_f32_e32 v168, 0xda24260, v168
	v_max_f32_e32 v169, 0xda24260, v169
	v_rcp_f32_e32 v168, v168
	v_rcp_f32_e32 v169, v169
	v_lshlrev_b32_e32 v166, 16, v198
	v_and_b32_e32 v167, 0xffff0000, v198
	v_pk_mul_f32 v[166:167], v[168:169], v[166:167]
	v_pk_mul_f32 v[32:33], v[32:33], v[166:167]
	v_lshlrev_b32_e32 v168, 16, v203
	v_and_b32_e32 v169, 0xffff0000, v203
	v_max_f32_e32 v168, 0xda24260, v168
	v_max_f32_e32 v169, 0xda24260, v169
	v_rcp_f32_e32 v168, v168
	v_rcp_f32_e32 v169, v169
	v_lshlrev_b32_e32 v166, 16, v199
	v_and_b32_e32 v167, 0xffff0000, v199
	v_pk_mul_f32 v[166:167], v[168:169], v[166:167]
	v_pk_mul_f32 v[34:35], v[34:35], v[166:167]
	v_lshlrev_b32_e32 v168, 16, v204
	v_and_b32_e32 v169, 0xffff0000, v204
	v_max_f32_e32 v168, 0xda24260, v168
	v_max_f32_e32 v169, 0xda24260, v169
	v_rcp_f32_e32 v168, v168
	v_rcp_f32_e32 v169, v169
	v_lshlrev_b32_e32 v166, 16, v200
	v_and_b32_e32 v167, 0xffff0000, v200
	v_pk_mul_f32 v[166:167], v[168:169], v[166:167]
	v_pk_mul_f32 v[28:29], v[28:29], v[166:167]
	v_lshlrev_b32_e32 v168, 16, v205
	v_and_b32_e32 v169, 0xffff0000, v205
	v_max_f32_e32 v168, 0xda24260, v168
	v_max_f32_e32 v169, 0xda24260, v169
	v_rcp_f32_e32 v168, v168
	v_rcp_f32_e32 v169, v169
	v_lshlrev_b32_e32 v166, 16, v201
	v_and_b32_e32 v167, 0xffff0000, v201
	v_pk_mul_f32 v[166:167], v[168:169], v[166:167]
	v_pk_mul_f32 v[30:31], v[30:31], v[166:167]
	s_waitcnt vmcnt(10)
	v_lshlrev_b32_e32 v168, 16, v210
	v_and_b32_e32 v169, 0xffff0000, v210
	v_max_f32_e32 v168, 0xda24260, v168
	v_max_f32_e32 v169, 0xda24260, v169
	v_rcp_f32_e32 v168, v168
	v_rcp_f32_e32 v169, v169
	v_lshlrev_b32_e32 v166, 16, v206
	v_and_b32_e32 v167, 0xffff0000, v206
	v_pk_mul_f32 v[166:167], v[168:169], v[166:167]
	v_pk_mul_f32 v[56:57], v[56:57], v[166:167]
	v_lshlrev_b32_e32 v168, 16, v211
	v_and_b32_e32 v169, 0xffff0000, v211
	v_max_f32_e32 v168, 0xda24260, v168
	v_max_f32_e32 v169, 0xda24260, v169
	v_rcp_f32_e32 v168, v168
	v_rcp_f32_e32 v169, v169
	v_lshlrev_b32_e32 v166, 16, v207
	v_and_b32_e32 v167, 0xffff0000, v207
	v_pk_mul_f32 v[166:167], v[168:169], v[166:167]
	v_pk_mul_f32 v[58:59], v[58:59], v[166:167]
	v_lshlrev_b32_e32 v168, 16, v212
	v_and_b32_e32 v169, 0xffff0000, v212
	v_max_f32_e32 v168, 0xda24260, v168
	v_max_f32_e32 v169, 0xda24260, v169
	v_rcp_f32_e32 v168, v168
	v_rcp_f32_e32 v169, v169
	v_lshlrev_b32_e32 v166, 16, v208
	v_and_b32_e32 v167, 0xffff0000, v208
	v_pk_mul_f32 v[166:167], v[168:169], v[166:167]
	v_pk_mul_f32 v[52:53], v[52:53], v[166:167]
	v_lshlrev_b32_e32 v168, 16, v213
	v_and_b32_e32 v169, 0xffff0000, v213
	v_max_f32_e32 v168, 0xda24260, v168
	v_max_f32_e32 v169, 0xda24260, v169
	v_rcp_f32_e32 v168, v168
	v_rcp_f32_e32 v169, v169
	v_lshlrev_b32_e32 v166, 16, v209
	v_and_b32_e32 v167, 0xffff0000, v209
	v_pk_mul_f32 v[166:167], v[168:169], v[166:167]
	v_pk_mul_f32 v[54:55], v[54:55], v[166:167]
	s_waitcnt vmcnt(8)
; __device__ __forceinline__ float lo16(unsigned u) { return __uint_as_float(u << 16); }
; __device__ __forceinline__ float hi16(unsigned u) { return __uint_as_float(u & 0xffff0000u); }
;   __device__ __forceinline__ bool operator()(f32x4 (&acc)[2][2][4][2], const Unit& u, int wr, int wc, int fr, int fq) const {
;     ...
;           const bf16_t* sp = pg + row * 8192 + (size_t)j * 2048 + col0 + bj * HALF;
;           const u32x4 sc = *(const u32x4*)sp;
;           float f[8] = {lo16(sc.x), hi16(sc.x), lo16(sc.y), hi16(sc.y), lo16(sc.z), hi16(sc.z), lo16(sc.w), hi16(sc.w)};
;           if (j < 3) { const u32x4 sn = *(const u32x4*)(sp + 2048);
;             float g[8] = {lo16(sn.x), hi16(sn.x), lo16(sn.y), hi16(sn.y), lo16(sn.z), hi16(sn.z), lo16(sn.w), hi16(sn.w)};
; #pragma unroll
;             for (int e = 0; e < 8; ++e) f[e] = f[e] * __builtin_amdgcn_rcpf(fmaxf(g[e], 1e-30f)); }
;           f32x4 v0 = acc[ai][bj][m][0], v1 = acc[ai][bj][m][1];
; #pragma unroll
;           for (int e = 0; e < 4; ++e) { v0[e] *= f[e]; v1[e] *= f[4 + e]; }
;           acc[ai][bj][m][0] = v0; acc[ai][bj][m][1] = v1;
	v_lshlrev_b32_e32 v168, 16, v218
	v_and_b32_e32 v169, 0xffff0000, v218
	v_max_f32_e32 v168, 0xda24260, v168
	v_max_f32_e32 v169, 0xda24260, v169
	v_rcp_f32_e32 v168, v168
	v_rcp_f32_e32 v169, v169
	v_lshlrev_b32_e32 v166, 16, v214
	v_and_b32_e32 v167, 0xffff0000, v214
	v_pk_mul_f32 v[166:167], v[168:169], v[166:167]
	v_pk_mul_f32 v[24:25], v[24:25], v[166:167]
	v_lshlrev_b32_e32 v168, 16, v219
	v_and_b32_e32 v169, 0xffff0000, v219
	v_max_f32_e32 v168, 0xda24260, v168
	v_max_f32_e32 v169, 0xda24260, v169
	v_rcp_f32_e32 v168, v168
	v_rcp_f32_e32 v169, v169
	v_lshlrev_b32_e32 v166, 16, v215
	v_and_b32_e32 v167, 0xffff0000, v215
	v_pk_mul_f32 v[166:167], v[168:169], v[166:167]
	v_pk_mul_f32 v[26:27], v[26:27], v[166:167]
	v_lshlrev_b32_e32 v168, 16, v220
	v_and_b32_e32 v169, 0xffff0000, v220
	v_max_f32_e32 v168, 0xda24260, v168
	v_max_f32_e32 v169, 0xda24260, v169
	v_rcp_f32_e32 v168, v168
	v_rcp_f32_e32 v169, v169
	v_lshlrev_b32_e32 v166, 16, v216
	v_and_b32_e32 v167, 0xffff0000, v216
	v_pk_mul_f32 v[166:167], v[168:169], v[166:167]
	v_pk_mul_f32 v[20:21], v[20:21], v[166:167]
	v_lshlrev_b32_e32 v168, 16, v221
	v_and_b32_e32 v169, 0xffff0000, v221
	v_max_f32_e32 v168, 0xda24260, v168
	v_max_f32_e32 v169, 0xda24260, v169
	v_rcp_f32_e32 v168, v168
	v_rcp_f32_e32 v169, v169
	v_lshlrev_b32_e32 v166, 16, v217
	v_and_b32_e32 v167, 0xffff0000, v217
	v_pk_mul_f32 v[166:167], v[168:169], v[166:167]
	v_pk_mul_f32 v[22:23], v[22:23], v[166:167]
	s_waitcnt vmcnt(6)
	v_lshlrev_b32_e32 v168, 16, v226
	v_and_b32_e32 v169, 0xffff0000, v226
	v_max_f32_e32 v168, 0xda24260, v168
	v_max_f32_e32 v169, 0xda24260, v169
	v_rcp_f32_e32 v168, v168
	v_rcp_f32_e32 v169, v169
	v_lshlrev_b32_e32 v166, 16, v222
	v_and_b32_e32 v167, 0xffff0000, v222
	v_pk_mul_f32 v[166:167], v[168:169], v[166:167]
	v_pk_mul_f32 v[48:49], v[48:49], v[166:167]
	v_lshlrev_b32_e32 v168, 16, v227
	v_and_b32_e32 v169, 0xffff0000, v227
	v_max_f32_e32 v168, 0xda24260, v168
	v_max_f32_e32 v169, 0xda24260, v169
	v_rcp_f32_e32 v168, v168
	v_rcp_f32_e32 v169, v169
	v_lshlrev_b32_e32 v166, 16, v223
	v_and_b32_e32 v167, 0xffff0000, v223
	v_pk_mul_f32 v[166:167], v[168:169], v[166:167]
	v_pk_mul_f32 v[50:51], v[50:51], v[166:167]
	v_lshlrev_b32_e32 v168, 16, v228
	v_and_b32_e32 v169, 0xffff0000, v228
	v_max_f32_e32 v168, 0xda24260, v168
	v_max_f32_e32 v169, 0xda24260, v169
	v_rcp_f32_e32 v168, v168
	v_rcp_f32_e32 v169, v169
	v_lshlrev_b32_e32 v166, 16, v224
	v_and_b32_e32 v167, 0xffff0000, v224
	v_pk_mul_f32 v[166:167], v[168:169], v[166:167]
	v_pk_mul_f32 v[44:45], v[44:45], v[166:167]
	v_lshlrev_b32_e32 v168, 16, v229
	v_and_b32_e32 v169, 0xffff0000, v229
	v_max_f32_e32 v168, 0xda24260, v168
	v_max_f32_e32 v169, 0xda24260, v169
	v_rcp_f32_e32 v168, v168
	v_rcp_f32_e32 v169, v169
	v_lshlrev_b32_e32 v166, 16, v225
	v_and_b32_e32 v167, 0xffff0000, v225
	v_pk_mul_f32 v[166:167], v[168:169], v[166:167]
	v_pk_mul_f32 v[46:47], v[46:47], v[166:167]
	s_waitcnt vmcnt(4)
; __device__ __forceinline__ float lo16(unsigned u) { return __uint_as_float(u << 16); }
; __device__ __forceinline__ float hi16(unsigned u) { return __uint_as_float(u & 0xffff0000u); }
; __device__ __forceinline__ unsigned pk2(float lo, float hi) { f32x2n v = {lo, hi}; bf16x2n b = __builtin_convertvector(v, bf16x2n); return __builtin_bit_cast(unsigned, b); }
;   __device__ __forceinline__ bool operator()(f32x4 (&acc)[2][2][4][2], const Unit& u, int wr, int wc, int fr, int fq) const {
;     ...
;           const bf16_t* sp = pg + row * 8192 + (size_t)j * 2048 + col0 + bj * HALF;
;           const u32x4 sc = *(const u32x4*)sp;
;           float f[8] = {lo16(sc.x), hi16(sc.x), lo16(sc.y), hi16(sc.y), lo16(sc.z), hi16(sc.z), lo16(sc.w), hi16(sc.w)};
;           if (j < 3) { const u32x4 sn = *(const u32x4*)(sp + 2048);
;             float g[8] = {lo16(sn.x), hi16(sn.x), lo16(sn.y), hi16(sn.y), lo16(sn.z), hi16(sn.z), lo16(sn.w), hi16(sn.w)};
; #pragma unroll
;             for (int e = 0; e < 8; ++e) f[e] = f[e] * __builtin_amdgcn_rcpf(fmaxf(g[e], 1e-30f)); }
;           f32x4 v0 = acc[ai][bj][m][0], v1 = acc[ai][bj][m][1];
; #pragma unroll
;           for (int e = 0; e < 4; ++e) { v0[e] *= f[e]; v1[e] *= f[4 + e]; }
;           acc[ai][bj][m][0] = v0; acc[ai][bj][m][1] = v1;
;           if (j == 3) { u32x4 w; w.x = pk2(v0[0], v0[1]); w.y = pk2(v0[2], v0[3]); w.z = pk2(v1[0], v1[1]); w.w = pk2(v1[2], v1[3]);
;             *(u32x4*)(mo + row * 2048 + col0 + bj * HALF) = w; } } }
;     return j == 3;
	v_lshlrev_b32_e32 v168, 16, v234
	v_and_b32_e32 v169, 0xffff0000, v234
	v_max_f32_e32 v168, 0xda24260, v168
	v_max_f32_e32 v169, 0xda24260, v169
	v_rcp_f32_e32 v168, v168
	v_rcp_f32_e32 v169, v169
	v_lshlrev_b32_e32 v166, 16, v230
	v_and_b32_e32 v167, 0xffff0000, v230
	v_pk_mul_f32 v[166:167], v[168:169], v[166:167]
	v_pk_mul_f32 v[16:17], v[16:17], v[166:167]
	v_lshlrev_b32_e32 v168, 16, v235
	v_and_b32_e32 v169, 0xffff0000, v235
	v_max_f32_e32 v168, 0xda24260, v168
	v_max_f32_e32 v169, 0xda24260, v169
	v_rcp_f32_e32 v168, v168
	v_rcp_f32_e32 v169, v169
	v_lshlrev_b32_e32 v166, 16, v231
	v_and_b32_e32 v167, 0xffff0000, v231
	v_pk_mul_f32 v[166:167], v[168:169], v[166:167]
	v_pk_mul_f32 v[18:19], v[18:19], v[166:167]
	v_lshlrev_b32_e32 v168, 16, v236
	v_and_b32_e32 v169, 0xffff0000, v236
	v_max_f32_e32 v168, 0xda24260, v168
	v_max_f32_e32 v169, 0xda24260, v169
	v_rcp_f32_e32 v168, v168
	v_rcp_f32_e32 v169, v169
	v_lshlrev_b32_e32 v166, 16, v232
	v_and_b32_e32 v167, 0xffff0000, v232
	v_pk_mul_f32 v[166:167], v[168:169], v[166:167]
	v_pk_mul_f32 v[12:13], v[12:13], v[166:167]
	v_lshlrev_b32_e32 v168, 16, v237
	v_and_b32_e32 v169, 0xffff0000, v237
	v_max_f32_e32 v168, 0xda24260, v168
	v_max_f32_e32 v169, 0xda24260, v169
	v_rcp_f32_e32 v168, v168
	v_rcp_f32_e32 v169, v169
	v_lshlrev_b32_e32 v166, 16, v233
	v_and_b32_e32 v167, 0xffff0000, v233
	v_pk_mul_f32 v[166:167], v[168:169], v[166:167]
	v_pk_mul_f32 v[14:15], v[14:15], v[166:167]
	s_waitcnt vmcnt(2)
	v_lshlrev_b32_e32 v168, 16, v142
	v_and_b32_e32 v169, 0xffff0000, v142
	v_max_f32_e32 v168, 0xda24260, v168
	v_max_f32_e32 v169, 0xda24260, v169
	v_rcp_f32_e32 v168, v168
	v_rcp_f32_e32 v169, v169
	v_lshlrev_b32_e32 v166, 16, v238
	v_and_b32_e32 v167, 0xffff0000, v238
	v_pk_mul_f32 v[166:167], v[168:169], v[166:167]
	v_pk_mul_f32 v[40:41], v[40:41], v[166:167]
	v_lshlrev_b32_e32 v168, 16, v143
	v_and_b32_e32 v169, 0xffff0000, v143
	v_max_f32_e32 v168, 0xda24260, v168
	v_max_f32_e32 v169, 0xda24260, v169
	v_rcp_f32_e32 v168, v168
	v_rcp_f32_e32 v169, v169
	v_lshlrev_b32_e32 v166, 16, v239
	v_and_b32_e32 v167, 0xffff0000, v239
	v_pk_mul_f32 v[166:167], v[168:169], v[166:167]
	v_pk_mul_f32 v[42:43], v[42:43], v[166:167]
	v_lshlrev_b32_e32 v168, 16, v144
	v_and_b32_e32 v169, 0xffff0000, v144
	v_max_f32_e32 v168, 0xda24260, v168
	v_max_f32_e32 v169, 0xda24260, v169
	v_rcp_f32_e32 v168, v168
	v_rcp_f32_e32 v169, v169
	v_lshlrev_b32_e32 v166, 16, v240
	v_and_b32_e32 v167, 0xffff0000, v240
	v_pk_mul_f32 v[166:167], v[168:169], v[166:167]
	v_pk_mul_f32 v[36:37], v[36:37], v[166:167]
	v_lshlrev_b32_e32 v168, 16, v145
	v_and_b32_e32 v169, 0xffff0000, v145
	v_max_f32_e32 v168, 0xda24260, v168
	v_max_f32_e32 v169, 0xda24260, v169
	v_rcp_f32_e32 v168, v168
	v_rcp_f32_e32 v169, v169
	v_lshlrev_b32_e32 v166, 16, v241
	v_and_b32_e32 v167, 0xffff0000, v241
	v_pk_mul_f32 v[166:167], v[168:169], v[166:167]
	v_pk_mul_f32 v[38:39], v[38:39], v[166:167]
	s_waitcnt vmcnt(0)
	v_lshlrev_b32_e32 v168, 16, v156
	v_and_b32_e32 v169, 0xffff0000, v156
	v_max_f32_e32 v168, 0xda24260, v168
	v_max_f32_e32 v169, 0xda24260, v169
	v_rcp_f32_e32 v168, v168
	v_rcp_f32_e32 v169, v169
	v_lshlrev_b32_e32 v166, 16, v146
	v_and_b32_e32 v167, 0xffff0000, v146
	v_pk_mul_f32 v[166:167], v[168:169], v[166:167]
	v_pk_mul_f32 v[8:9], v[8:9], v[166:167]
	v_lshlrev_b32_e32 v168, 16, v157
	v_and_b32_e32 v169, 0xffff0000, v157
	v_max_f32_e32 v168, 0xda24260, v168
	v_max_f32_e32 v169, 0xda24260, v169
	v_rcp_f32_e32 v168, v168
	v_rcp_f32_e32 v169, v169
	v_lshlrev_b32_e32 v166, 16, v147
	v_and_b32_e32 v167, 0xffff0000, v147
	v_pk_mul_f32 v[166:167], v[168:169], v[166:167]
	v_pk_mul_f32 v[10:11], v[10:11], v[166:167]
	v_lshlrev_b32_e32 v168, 16, v158
	v_and_b32_e32 v169, 0xffff0000, v158
	v_max_f32_e32 v168, 0xda24260, v168
	v_max_f32_e32 v169, 0xda24260, v169
	v_rcp_f32_e32 v168, v168
	v_rcp_f32_e32 v169, v169
	v_lshlrev_b32_e32 v166, 16, v148
	v_and_b32_e32 v167, 0xffff0000, v148
	v_pk_mul_f32 v[166:167], v[168:169], v[166:167]
	v_pk_mul_f32 v[4:5], v[4:5], v[166:167]
	v_lshlrev_b32_e32 v168, 16, v159
	v_and_b32_e32 v169, 0xffff0000, v159
	v_max_f32_e32 v168, 0xda24260, v168
	v_max_f32_e32 v169, 0xda24260, v169
	v_rcp_f32_e32 v168, v168
	v_rcp_f32_e32 v169, v169
	v_lshlrev_b32_e32 v166, 16, v149
	v_and_b32_e32 v167, 0xffff0000, v149
	v_pk_mul_f32 v[166:167], v[168:169], v[166:167]
	v_pk_mul_f32 v[6:7], v[6:7], v[166:167]
	s_branch .Lg2e_done

; #define G8_STAGE(bufoff, gbase, voff) do { _Pragma("unroll") for (int _i = 0; _i < 2; ++_i) \
;     __builtin_amdgcn_global_load_lds((const unsigned*)((const char*)(gbase) + (voff)[_i]), (LAS unsigned*)(lds + (bufoff) + ldsw + _i * 8192), 16, 0, 0); } while (0)
; #define G8_LDA(dst, b, h) do { _Pragma("unroll") for (int m = 0; m < 4; ++m) _Pragma("unroll") for (int k = 0; k < 2; ++k) dst[m][k] = *(const LAS bf16x8*)(lds + G8_SA(b, h) + aoff + m * 2048 + k * 1024); } while (0)
; #define G8_LDB(dst, b, h) do { _Pragma("unroll") for (int n = 0; n < 2; ++n) _Pragma("unroll") for (int k = 0; k < 2; ++k) dst[n][k] = *(const LAS bf16x8*)(lds + G8_SB(b, h) + boff + n * 2048 + k * 1024); } while (0)
; #define G8_MMA(ai, bj, At, Bt) do { __builtin_amdgcn_s_setprio(1); _Pragma("unroll") for (int m = 0; m < 4; ++m) _Pragma("unroll") for (int n = 0; n < 2; ++n) _Pragma("unroll") for (int k = 0; k < 2; ++k) \
;     acc[ai][bj][m][n] = __builtin_amdgcn_mfma_f32_16x16x32_bf16(Bt[n][k], At[m][k], acc[ai][bj][m][n], 0, 0, 0); __builtin_amdgcn_s_setprio(0); } while (0)
; #define G8_WAIT_L(n) asm volatile("s_waitcnt lgkmcnt(" #n ")" ::: "memory")
; #define G8_BAR __builtin_amdgcn_s_barrier()
; #define G8_SCHED __builtin_amdgcn_sched_barrier(0)
; template <class Epi, class Sched>
; __device__ __forceinline__ void gemm_phase(const int wv_, LAS unsigned char* lds, const int lda, const int ldb, const int K, const Sched& S, const Epi& E) {
;     ...
;     for (int t = 0; t < nt; t += 2) {
;       const bool last = (t == nt - 2);
;       const char* a1 = cA + (size_t)(t + 1) * kstep;
;       const char* a2 = last ? nA : cA + (size_t)(t + 2) * kstep; const char* b2 = last ? nB : cB + (size_t)(t + 2) * kstep;
;       const char* a3 = a2 + kstep; const char* b3 = b2 + kstep;
;       G8_LDB(B0, 0, 0); G8_SCHED; G8_LDA(At, 0, 0); G8_STAGE(G8_SA(1, 1), a1 + hstepA, voffA);
;       G8_WAIT_L(8); G8_BAR; G8_WAIT_L(0); G8_MMA(0, 0, At, B0); G8_BAR; G8_SCHED;
;       G8_LDB(B1, 0, 1); G8_STAGE(G8_SB(0, 0), b2, voffB);
;       G8_BAR; G8_WAIT_L(0); G8_MMA(0, 1, At, B1); G8_BAR;
;       G8_LDA(At, 0, 1); G8_STAGE(G8_SA(0, 0), a2, voffA);
;       G8_BAR; G8_WAIT_L(0); G8_MMA(1, 0, At, B0); G8_BAR; G8_SCHED;
.Lg3_noprio:
.LBB0_949:
	s_add_u32 s25, s30, 0xfff80080
	s_addc_u32 s34, s31, -1
	s_add_i32 s70, 0, 0x10000
	v_add_u32_e32 v72, s70, v168
	ds_read_b128 v[56:59], v72
	ds_read_b128 v[64:67], v72 offset:1024
	ds_read_b128 v[68:71], v72 offset:2048
	ds_read_b128 v[72:75], v72 offset:3072
	s_cmp_eq_u32 s19, 28
	s_cselect_b32 s37, s27, s34
	s_cselect_b32 s36, s26, s25
	s_cselect_b32 s35, s29, s17
	s_cselect_b32 s34, s28, s11
	v_lshl_add_u64 v[166:167], s[30:31], 0, v[150:151]
	s_add_i32 m0, s50, 0xc000
	ds_read_b128 v[158:161], v189
	ds_read_b128 v[162:165], v189 offset:1024
	ds_read_b128 v[190:193], v189 offset:2048
	ds_read_b128 v[194:197], v189 offset:3072
	ds_read_b128 v[198:201], v189 offset:4096
	ds_read_b128 v[202:205], v189 offset:5120
	ds_read_b128 v[206:209], v189 offset:6144
	ds_read_b128 v[210:213], v189 offset:7168
	global_load_lds_dwordx4 v[166:167], off
	v_lshl_add_u64 v[166:167], s[30:31], 0, v[156:157]
	s_add_i32 m0, s50, 0xe000
	s_nop 0
	global_load_lds_dwordx4 v[166:167], off
	s_waitcnt lgkmcnt(8)
	s_barrier
	s_waitcnt lgkmcnt(0)
	v_mfma_f32_16x16x32_bf16 v[144:147], v[56:59], v[158:161], v[144:147]
	v_mfma_f32_16x16x32_bf16 v[140:143], v[68:71], v[158:161], v[140:143]
	v_mfma_f32_16x16x32_bf16 v[128:131], v[56:59], v[190:193], v[128:131]
	v_mfma_f32_16x16x32_bf16 v[124:127], v[68:71], v[190:193], v[124:127]
	v_mfma_f32_16x16x32_bf16 v[112:115], v[56:59], v[198:201], v[112:115]
	v_mfma_f32_16x16x32_bf16 v[108:111], v[68:71], v[198:201], v[108:111]
	v_mfma_f32_16x16x32_bf16 v[96:99], v[56:59], v[206:209], v[96:99]
	v_mfma_f32_16x16x32_bf16 v[92:95], v[68:71], v[206:209], v[92:95]
	v_mfma_f32_16x16x32_bf16 v[144:147], v[64:67], v[162:165], v[144:147]
	v_mfma_f32_16x16x32_bf16 v[140:143], v[72:75], v[162:165], v[140:143]
	v_mfma_f32_16x16x32_bf16 v[128:131], v[64:67], v[194:197], v[128:131]
	v_mfma_f32_16x16x32_bf16 v[124:127], v[72:75], v[194:197], v[124:127]
	v_mfma_f32_16x16x32_bf16 v[112:115], v[64:67], v[202:205], v[112:115]
	v_mfma_f32_16x16x32_bf16 v[108:111], v[72:75], v[202:205], v[108:111]
	v_mfma_f32_16x16x32_bf16 v[96:99], v[64:67], v[210:213], v[96:99]
	v_mfma_f32_16x16x32_bf16 v[92:95], v[72:75], v[210:213], v[92:95]
	s_barrier
	s_add_i32 s25, 0, 0x14000
	v_add_u32_e32 v166, s25, v168
	s_add_i32 s70, s70, s47
	ds_read_b128 v[214:217], v166
	ds_read_b128 v[218:221], v166 offset:1024
	ds_read_b128 v[222:225], v166 offset:2048
	ds_read_b128 v[226:229], v166 offset:3072
	v_lshl_add_u64 v[166:167], s[34:35], 0, v[0:1]
	s_mov_b32 m0, s70
	v_lshl_add_u64 v[230:231], s[34:35], 0, v[148:149]
	global_load_lds_dwordx4 v[166:167], off
	s_add_i32 m0, s70, 0x2000
	s_nop 0
	global_load_lds_dwordx4 v[230:231], off
	s_barrier
	s_waitcnt lgkmcnt(0)
	v_mfma_f32_16x16x32_bf16 v[136:139], v[214:217], v[158:161], v[136:139]
	v_mfma_f32_16x16x32_bf16 v[132:135], v[222:225], v[158:161], v[132:135]
	v_mfma_f32_16x16x32_bf16 v[120:123], v[214:217], v[190:193], v[120:123]
	v_mfma_f32_16x16x32_bf16 v[116:119], v[222:225], v[190:193], v[116:119]
	v_mfma_f32_16x16x32_bf16 v[104:107], v[214:217], v[198:201], v[104:107]
	v_mfma_f32_16x16x32_bf16 v[100:103], v[222:225], v[198:201], v[100:103]
	v_mfma_f32_16x16x32_bf16 v[88:91], v[214:217], v[206:209], v[88:91]
	v_mfma_f32_16x16x32_bf16 v[84:87], v[222:225], v[206:209], v[84:87]
	v_mfma_f32_16x16x32_bf16 v[136:139], v[218:221], v[162:165], v[136:139]
	v_mfma_f32_16x16x32_bf16 v[132:135], v[226:229], v[162:165], v[132:135]
	v_mfma_f32_16x16x32_bf16 v[120:123], v[218:221], v[194:197], v[120:123]
	v_mfma_f32_16x16x32_bf16 v[116:119], v[226:229], v[194:197], v[116:119]
	v_mfma_f32_16x16x32_bf16 v[104:107], v[218:221], v[202:205], v[104:107]
	v_mfma_f32_16x16x32_bf16 v[100:103], v[226:229], v[202:205], v[100:103]
	v_mfma_f32_16x16x32_bf16 v[88:91], v[218:221], v[210:213], v[88:91]
	v_mfma_f32_16x16x32_bf16 v[84:87], v[226:229], v[210:213], v[84:87]
	s_mov_b32 m0, s50
	v_lshl_add_u64 v[232:233], s[36:37], 0, v[0:1]
	s_barrier
	ds_read_b128 v[158:161], v189 offset:16384
	ds_read_b128 v[162:165], v189 offset:17408
	ds_read_b128 v[190:193], v189 offset:18432
	ds_read_b128 v[194:197], v189 offset:19456
	ds_read_b128 v[198:201], v189 offset:20480
	ds_read_b128 v[202:205], v189 offset:21504
	ds_read_b128 v[206:209], v189 offset:22528
	ds_read_b128 v[210:213], v189 offset:23552
	global_load_lds_dwordx4 v[232:233], off
	v_lshl_add_u64 v[234:235], s[36:37], 0, v[148:149]
	s_mov_b32 m0, s51
	s_nop 0
	global_load_lds_dwordx4 v[234:235], off
	s_barrier
	s_waitcnt lgkmcnt(0)
	v_mfma_f32_16x16x32_bf16 v[80:83], v[56:59], v[158:161], v[80:83]
	v_mfma_f32_16x16x32_bf16 v[76:79], v[68:71], v[158:161], v[76:79]
	v_mfma_f32_16x16x32_bf16 v[48:51], v[56:59], v[190:193], v[48:51]
	v_mfma_f32_16x16x32_bf16 v[44:47], v[68:71], v[190:193], v[44:47]
	v_mfma_f32_16x16x32_bf16 v[32:35], v[56:59], v[198:201], v[32:35]
	v_mfma_f32_16x16x32_bf16 v[28:31], v[68:71], v[198:201], v[28:31]
	v_mfma_f32_16x16x32_bf16 v[16:19], v[56:59], v[206:209], v[16:19]
	v_mfma_f32_16x16x32_bf16 v[12:15], v[68:71], v[206:209], v[12:15]
	v_mfma_f32_16x16x32_bf16 v[80:83], v[64:67], v[162:165], v[80:83]
	v_mfma_f32_16x16x32_bf16 v[76:79], v[72:75], v[162:165], v[76:79]
	v_mfma_f32_16x16x32_bf16 v[48:51], v[64:67], v[194:197], v[48:51]
	v_mfma_f32_16x16x32_bf16 v[44:47], v[72:75], v[194:197], v[44:47]
	v_mfma_f32_16x16x32_bf16 v[32:35], v[64:67], v[202:205], v[32:35]
	v_mfma_f32_16x16x32_bf16 v[28:31], v[72:75], v[202:205], v[28:31]
	v_mfma_f32_16x16x32_bf16 v[16:19], v[64:67], v[210:213], v[16:19]
	v_mfma_f32_16x16x32_bf16 v[12:15], v[72:75], v[210:213], v[12:15]
	s_barrier
; #define G8_STAGE(bufoff, gbase, voff) do { _Pragma("unroll") for (int _i = 0; _i < 2; ++_i) \
;     __builtin_amdgcn_global_load_lds((const unsigned*)((const char*)(gbase) + (voff)[_i]), (LAS unsigned*)(lds + (bufoff) + ldsw + _i * 8192), 16, 0, 0); } while (0)
; #define G8_LDA(dst, b, h) do { _Pragma("unroll") for (int m = 0; m < 4; ++m) _Pragma("unroll") for (int k = 0; k < 2; ++k) dst[m][k] = *(const LAS bf16x8*)(lds + G8_SA(b, h) + aoff + m * 2048 + k * 1024); } while (0)
; #define G8_LDB(dst, b, h) do { _Pragma("unroll") for (int n = 0; n < 2; ++n) _Pragma("unroll") for (int k = 0; k < 2; ++k) dst[n][k] = *(const LAS bf16x8*)(lds + G8_SB(b, h) + boff + n * 2048 + k * 1024); } while (0)
; #define G8_MMA(ai, bj, At, Bt) do { __builtin_amdgcn_s_setprio(1); _Pragma("unroll") for (int m = 0; m < 4; ++m) _Pragma("unroll") for (int n = 0; n < 2; ++n) _Pragma("unroll") for (int k = 0; k < 2; ++k) \
;     acc[ai][bj][m][n] = __builtin_amdgcn_mfma_f32_16x16x32_bf16(Bt[n][k], At[m][k], acc[ai][bj][m][n], 0, 0, 0); __builtin_amdgcn_s_setprio(0); } while (0)
; #define G8_WAIT_V(n) asm volatile("s_waitcnt vmcnt(" #n ")" ::: "memory")
; #define G8_WAIT_L(n) asm volatile("s_waitcnt lgkmcnt(" #n ")" ::: "memory")
; #define G8_BAR __builtin_amdgcn_s_barrier()
; #define G8_SCHED __builtin_amdgcn_sched_barrier(0)
; template <class Epi, class Sched>
; __device__ __forceinline__ void gemm_phase(const int wv_, LAS unsigned char* lds, const int lda, const int ldb, const int K, const Sched& S, const Epi& E) {
;     ...
;       G8_STAGE(G8_SB(0, 1), b2 + hstepB, voffB);
;       G8_WAIT_V(6); G8_BAR; G8_MMA(1, 1, At, B1); G8_BAR;
;       G8_LDB(B0, 1, 0); G8_SCHED; G8_LDA(At, 1, 0); G8_STAGE(G8_SA(0, 1), a2 + hstepA, voffA);
;       G8_WAIT_L(8); G8_BAR; G8_WAIT_L(0); G8_MMA(0, 0, At, B0); G8_BAR; G8_SCHED;
;       G8_LDB(B1, 1, 1); G8_STAGE(G8_SB(1, 0), b3, voffB);
;       G8_BAR; G8_WAIT_L(0); G8_MMA(0, 1, At, B1); G8_BAR;
;       G8_LDA(At, 1, 1); G8_STAGE(G8_SA(1, 0), a3, voffA);
;       G8_BAR; G8_WAIT_L(0); G8_MMA(1, 0, At, B0); G8_BAR; G8_SCHED;
	s_add_u32 s70, s34, 0x80000
	s_addc_u32 s71, s35, 0
	s_add_i32 s25, s25, s47
	v_lshl_add_u64 v[56:57], s[70:71], 0, v[0:1]
	s_mov_b32 m0, s25
	s_nop 0
	global_load_lds_dwordx4 v[56:57], off
	v_lshl_add_u64 v[56:57], s[70:71], 0, v[148:149]
	s_add_i32 m0, s25, 0x2000
	s_nop 0
	global_load_lds_dwordx4 v[56:57], off
	s_waitcnt vmcnt(6)
	s_barrier
	v_mfma_f32_16x16x32_bf16 v[52:55], v[222:225], v[158:161], v[52:55]
	v_mfma_f32_16x16x32_bf16 v[40:43], v[214:217], v[190:193], v[40:43]
	v_mfma_f32_16x16x32_bf16 v[36:39], v[222:225], v[190:193], v[36:39]
	v_mfma_f32_16x16x32_bf16 v[24:27], v[214:217], v[198:201], v[24:27]
	v_mfma_f32_16x16x32_bf16 v[20:23], v[222:225], v[198:201], v[20:23]
	v_mfma_f32_16x16x32_bf16 v[8:11], v[214:217], v[206:209], v[8:11]
	v_mfma_f32_16x16x32_bf16 v[4:7], v[222:225], v[206:209], v[4:7]
	v_mfma_f32_16x16x32_bf16 v[56:59], v[214:217], v[158:161], v[60:63]
	v_mfma_f32_16x16x32_bf16 v[52:55], v[226:229], v[162:165], v[52:55]
	v_mfma_f32_16x16x32_bf16 v[40:43], v[218:221], v[194:197], v[40:43]
	v_mfma_f32_16x16x32_bf16 v[36:39], v[226:229], v[194:197], v[36:39]
	v_mfma_f32_16x16x32_bf16 v[24:27], v[218:221], v[202:205], v[24:27]
	v_mfma_f32_16x16x32_bf16 v[20:23], v[226:229], v[202:205], v[20:23]
	v_mfma_f32_16x16x32_bf16 v[8:11], v[218:221], v[210:213], v[8:11]
	v_mfma_f32_16x16x32_bf16 v[4:7], v[226:229], v[210:213], v[4:7]
	v_mfma_f32_16x16x32_bf16 v[56:59], v[218:221], v[162:165], v[56:59]
	s_add_i32 s25, 0, 0x18000
	v_add_u32_e32 v72, s25, v168
	s_barrier
	ds_read_b128 v[60:63], v72
	ds_read_b128 v[64:67], v72 offset:1024
	ds_read_b128 v[68:71], v72 offset:2048
	ds_read_b128 v[72:75], v72 offset:3072
	s_add_u32 s36, s36, 0x80000
	s_addc_u32 s37, s37, 0
	s_mov_b32 m0, s58
	v_lshl_add_u64 v[214:215], s[36:37], 0, v[0:1]
	ds_read_b128 v[158:161], v189 offset:32768
	ds_read_b128 v[162:165], v189 offset:33792
	ds_read_b128 v[190:193], v189 offset:34816
	ds_read_b128 v[194:197], v189 offset:35840
	ds_read_b128 v[198:201], v189 offset:36864
	ds_read_b128 v[202:205], v189 offset:37888
	ds_read_b128 v[206:209], v189 offset:38912
	ds_read_b128 v[210:213], v189 offset:39936
	global_load_lds_dwordx4 v[214:215], off
	v_lshl_add_u64 v[214:215], s[36:37], 0, v[148:149]
	s_mov_b32 m0, s59
	s_nop 0
	global_load_lds_dwordx4 v[214:215], off
	s_waitcnt lgkmcnt(8)
	s_barrier
	s_waitcnt lgkmcnt(0)
	v_mfma_f32_16x16x32_bf16 v[144:147], v[60:63], v[158:161], v[144:147]
	v_mfma_f32_16x16x32_bf16 v[140:143], v[68:71], v[158:161], v[140:143]
	v_mfma_f32_16x16x32_bf16 v[128:131], v[60:63], v[190:193], v[128:131]
	v_mfma_f32_16x16x32_bf16 v[124:127], v[68:71], v[190:193], v[124:127]
	v_mfma_f32_16x16x32_bf16 v[112:115], v[60:63], v[198:201], v[112:115]
	v_mfma_f32_16x16x32_bf16 v[108:111], v[68:71], v[198:201], v[108:111]
	v_mfma_f32_16x16x32_bf16 v[96:99], v[60:63], v[206:209], v[96:99]
	v_mfma_f32_16x16x32_bf16 v[92:95], v[68:71], v[206:209], v[92:95]
	v_mfma_f32_16x16x32_bf16 v[144:147], v[64:67], v[162:165], v[144:147]
	v_mfma_f32_16x16x32_bf16 v[140:143], v[72:75], v[162:165], v[140:143]
	v_mfma_f32_16x16x32_bf16 v[128:131], v[64:67], v[194:197], v[128:131]
	v_mfma_f32_16x16x32_bf16 v[124:127], v[72:75], v[194:197], v[124:127]
	v_mfma_f32_16x16x32_bf16 v[112:115], v[64:67], v[202:205], v[112:115]
	v_mfma_f32_16x16x32_bf16 v[108:111], v[72:75], v[202:205], v[108:111]
	v_mfma_f32_16x16x32_bf16 v[96:99], v[64:67], v[210:213], v[96:99]
	v_mfma_f32_16x16x32_bf16 v[92:95], v[72:75], v[210:213], v[92:95]
	s_barrier
	s_add_i32 s36, 0, 0x1c000
	s_add_i32 s25, s25, s47
	v_add_u32_e32 v226, s36, v168
	v_lshl_add_u64 v[166:167], v[166:167], 0, s[90:91]
	s_mov_b32 m0, s25
	ds_read_b128 v[214:217], v226
	ds_read_b128 v[218:221], v226 offset:1024
	ds_read_b128 v[222:225], v226 offset:2048
	ds_read_b128 v[226:229], v226 offset:3072
	global_load_lds_dwordx4 v[166:167], off
	v_lshl_add_u64 v[166:167], v[230:231], 0, s[90:91]
	s_add_i32 m0, s25, 0x2000
	s_nop 0
	global_load_lds_dwordx4 v[166:167], off
	s_barrier
; #define G8_STAGE(bufoff, gbase, voff) do { _Pragma("unroll") for (int _i = 0; _i < 2; ++_i) \
;     __builtin_amdgcn_global_load_lds((const unsigned*)((const char*)(gbase) + (voff)[_i]), (LAS unsigned*)(lds + (bufoff) + ldsw + _i * 8192), 16, 0, 0); } while (0)
; #define G8_LDA(dst, b, h) do { _Pragma("unroll") for (int m = 0; m < 4; ++m) _Pragma("unroll") for (int k = 0; k < 2; ++k) dst[m][k] = *(const LAS bf16x8*)(lds + G8_SA(b, h) + aoff + m * 2048 + k * 1024); } while (0)
; #define G8_LDB(dst, b, h) do { _Pragma("unroll") for (int n = 0; n < 2; ++n) _Pragma("unroll") for (int k = 0; k < 2; ++k) dst[n][k] = *(const LAS bf16x8*)(lds + G8_SB(b, h) + boff + n * 2048 + k * 1024); } while (0)
; #define G8_WAIT_V(n) asm volatile("s_waitcnt vmcnt(" #n ")" ::: "memory")
; #define G8_WAIT_L(n) asm volatile("s_waitcnt lgkmcnt(" #n ")" ::: "memory")
; #define G8_BAR __builtin_amdgcn_s_barrier()
; #define G8_SCHED __builtin_amdgcn_sched_barrier(0)
; #define p (kparams())
; template <class Epi, class Sched>
; __device__ __forceinline__ void gemm_phase(const int wv_, LAS unsigned char* lds, const int lda, const int ldb, const int K, const Sched& S, const Epi& E) {
;     ...
;       G8_LDB(B1, 1, 1); G8_STAGE(G8_SB(1, 0), b3, voffB);
;       G8_BAR; G8_WAIT_L(0); G8_MMA(0, 1, At, B1); G8_BAR;
;       G8_LDA(At, 1, 1); G8_STAGE(G8_SA(1, 0), a3, voffA);
;       G8_BAR; G8_WAIT_L(0); G8_MMA(1, 0, At, B0); G8_BAR; G8_SCHED;
;       G8_STAGE(G8_SB(1, 1), b3 + hstepB, voffB);
;       G8_WAIT_V(6); G8_BAR; G8_MMA(1, 1, At, B1); G8_BAR;
;     }
;   __device__ __forceinline__ bool operator()(f32x4 (&acc)[2][2][4][2], const Unit& u, int wr, int wc, int fr, int fq) const {
;     const int row0 = u.pm * BM + wr * 64 + fr, col0 = u.pn * BM + wc * 32 + 4 * fq;
;     const int who = row_who(u.pm * BM);
;     const float* gp = modl + (size_t)who * 12288 + part * 2048 + col0;
;     f32x4 gv[2][2];
; #pragma unroll
;     for (int bj = 0; bj < 2; ++bj)
; #pragma unroll
;       for (int n = 0; n < 2; ++n) gv[bj][n] = *(const f32x4*)(gp + bj * HALF + n * 16);
; #pragma unroll
;     for (int ai = 0; ai < 2; ++ai)
; #pragma unroll
;       for (int m = 0; m < 4; ++m) { const int row = row0 + ai * HALF + m * 16;
;         KPR p = (KParams*)__builtin_amdgcn_kernarg_segment_ptr();
;         const float* src = xrow_ptr(p, layer_src, row) + col0; float* dst = xrow_dst(p, row) + col0;
	s_waitcnt lgkmcnt(0)
	v_mfma_f32_16x16x32_bf16 v[136:139], v[214:217], v[158:161], v[136:139]
	v_mfma_f32_16x16x32_bf16 v[132:135], v[222:225], v[158:161], v[132:135]
	v_mfma_f32_16x16x32_bf16 v[120:123], v[214:217], v[190:193], v[120:123]
	v_mfma_f32_16x16x32_bf16 v[116:119], v[222:225], v[190:193], v[116:119]
	v_mfma_f32_16x16x32_bf16 v[104:107], v[214:217], v[198:201], v[104:107]
	v_mfma_f32_16x16x32_bf16 v[100:103], v[222:225], v[198:201], v[100:103]
	v_mfma_f32_16x16x32_bf16 v[88:91], v[214:217], v[206:209], v[88:91]
	v_mfma_f32_16x16x32_bf16 v[84:87], v[222:225], v[206:209], v[84:87]
	v_mfma_f32_16x16x32_bf16 v[136:139], v[218:221], v[162:165], v[136:139]
	v_mfma_f32_16x16x32_bf16 v[132:135], v[226:229], v[162:165], v[132:135]
	v_mfma_f32_16x16x32_bf16 v[120:123], v[218:221], v[194:197], v[120:123]
	v_mfma_f32_16x16x32_bf16 v[116:119], v[226:229], v[194:197], v[116:119]
	v_mfma_f32_16x16x32_bf16 v[104:107], v[218:221], v[202:205], v[104:107]
	v_mfma_f32_16x16x32_bf16 v[100:103], v[226:229], v[202:205], v[100:103]
	v_mfma_f32_16x16x32_bf16 v[88:91], v[218:221], v[210:213], v[88:91]
	v_mfma_f32_16x16x32_bf16 v[84:87], v[226:229], v[210:213], v[84:87]
	s_mov_b32 m0, s68
	v_lshl_add_u64 v[166:167], v[232:233], 0, s[90:91]
	s_barrier
	ds_read_b128 v[158:161], v189 offset:49152
	ds_read_b128 v[162:165], v189 offset:50176
	ds_read_b128 v[190:193], v189 offset:51200
	ds_read_b128 v[194:197], v189 offset:52224
	ds_read_b128 v[198:201], v189 offset:53248
	ds_read_b128 v[202:205], v189 offset:54272
	ds_read_b128 v[206:209], v189 offset:55296
	ds_read_b128 v[210:213], v189 offset:56320
	global_load_lds_dwordx4 v[166:167], off
	v_lshl_add_u64 v[166:167], v[234:235], 0, s[90:91]
	s_mov_b32 m0, s69
	s_nop 0
	global_load_lds_dwordx4 v[166:167], off
	s_barrier
	s_waitcnt lgkmcnt(0)
	v_mfma_f32_16x16x32_bf16 v[80:83], v[60:63], v[158:161], v[80:83]
	v_mfma_f32_16x16x32_bf16 v[76:79], v[68:71], v[158:161], v[76:79]
	v_mfma_f32_16x16x32_bf16 v[48:51], v[60:63], v[190:193], v[48:51]
	v_mfma_f32_16x16x32_bf16 v[44:47], v[68:71], v[190:193], v[44:47]
	v_mfma_f32_16x16x32_bf16 v[32:35], v[60:63], v[198:201], v[32:35]
	v_mfma_f32_16x16x32_bf16 v[28:31], v[68:71], v[198:201], v[28:31]
	v_mfma_f32_16x16x32_bf16 v[16:19], v[60:63], v[206:209], v[16:19]
	v_mfma_f32_16x16x32_bf16 v[12:15], v[68:71], v[206:209], v[12:15]
	v_mfma_f32_16x16x32_bf16 v[80:83], v[64:67], v[162:165], v[80:83]
	v_mfma_f32_16x16x32_bf16 v[76:79], v[72:75], v[162:165], v[76:79]
	v_mfma_f32_16x16x32_bf16 v[48:51], v[64:67], v[194:197], v[48:51]
	v_mfma_f32_16x16x32_bf16 v[44:47], v[72:75], v[194:197], v[44:47]
	v_mfma_f32_16x16x32_bf16 v[32:35], v[64:67], v[202:205], v[32:35]
	v_mfma_f32_16x16x32_bf16 v[28:31], v[72:75], v[202:205], v[28:31]
	v_mfma_f32_16x16x32_bf16 v[16:19], v[64:67], v[210:213], v[16:19]
	v_mfma_f32_16x16x32_bf16 v[12:15], v[72:75], v[210:213], v[12:15]
	s_barrier
	s_add_u32 s34, s34, 0x80080
	s_addc_u32 s35, s35, 0
	s_add_i32 s25, s36, s47
	v_lshl_add_u64 v[60:61], s[34:35], 0, v[0:1]
	s_mov_b32 m0, s25
	s_nop 0
	global_load_lds_dwordx4 v[60:61], off
	v_lshl_add_u64 v[60:61], s[34:35], 0, v[148:149]
	s_add_i32 m0, s25, 0x2000
	s_nop 0
	global_load_lds_dwordx4 v[60:61], off
	s_waitcnt vmcnt(6)
	s_barrier
	v_mfma_f32_16x16x32_bf16 v[56:59], v[214:217], v[158:161], v[56:59]
	v_mfma_f32_16x16x32_bf16 v[52:55], v[222:225], v[158:161], v[52:55]
	v_mfma_f32_16x16x32_bf16 v[40:43], v[214:217], v[190:193], v[40:43]
	v_mfma_f32_16x16x32_bf16 v[36:39], v[222:225], v[190:193], v[36:39]
	v_mfma_f32_16x16x32_bf16 v[24:27], v[214:217], v[198:201], v[24:27]
	v_mfma_f32_16x16x32_bf16 v[20:23], v[222:225], v[198:201], v[20:23]
	v_mfma_f32_16x16x32_bf16 v[8:11], v[214:217], v[206:209], v[8:11]
	v_mfma_f32_16x16x32_bf16 v[4:7], v[222:225], v[206:209], v[4:7]
	v_mfma_f32_16x16x32_bf16 v[60:63], v[218:221], v[162:165], v[56:59]
	v_mfma_f32_16x16x32_bf16 v[52:55], v[226:229], v[162:165], v[52:55]
	v_mfma_f32_16x16x32_bf16 v[40:43], v[218:221], v[194:197], v[40:43]
	v_mfma_f32_16x16x32_bf16 v[36:39], v[226:229], v[194:197], v[36:39]
	v_mfma_f32_16x16x32_bf16 v[24:27], v[218:221], v[202:205], v[24:27]
	v_mfma_f32_16x16x32_bf16 v[20:23], v[226:229], v[202:205], v[20:23]
	v_mfma_f32_16x16x32_bf16 v[8:11], v[218:221], v[210:213], v[8:11]
	v_mfma_f32_16x16x32_bf16 v[4:7], v[226:229], v[210:213], v[4:7]
	s_add_i32 s19, s19, 2
	s_add_u32 s30, s30, 0x100
	s_addc_u32 s31, s31, 0
	s_add_u32 s11, s11, 0x100
	s_addc_u32 s17, s17, 0
	s_cmp_gt_u32 s19, 29
	s_barrier
	s_cbranch_scc0 .LBB0_949
	s_setprio 0
	v_lshl_or_b32 v158, s10, 8, v169
	s_mul_hi_i32 s11, s24, 0x78787879
	s_lshr_b32 s17, s11, 31
	s_ashr_i32 s11, s11, 3
	s_add_i32 s11, s11, s17
	s_lshl_b32 s17, s24, 8
	s_mul_i32 s10, s11, 0xffffef00
	s_add_i32 s10, s10, s17
	s_cmpk_gt_i32 s10, 0xff
	s_cbranch_scc1 .Lg3e_lat
	s_load_dwordx2 s[28:29], s[0:1], 0x118
	s_load_dwordx2 s[26:27], s[0:1], 0x10
	s_lshl_b32 s17, s11, 21
	s_mov_b32 s11, 4
	s_waitcnt lgkmcnt(0)
	s_add_u32 s28, s28, 0x7f8000
	s_addc_u32 s29, s29, 0
	s_cmp_eq_u32 s76, 0
	s_cbranch_scc1 .Lg3e_ptr
	s_mov_b64 s[26:27], s[28:29]
	s_branch .Lg3e_ptr

; #define G8_STAGE(bufoff, gbase, voff) do { _Pragma("unroll") for (int _i = 0; _i < 2; ++_i) \
;     __builtin_amdgcn_global_load_lds((const unsigned*)((const char*)(gbase) + (voff)[_i]), (LAS unsigned*)(lds + (bufoff) + ldsw + _i * 8192), 16, 0, 0); } while (0)
; #define G8_LDA(dst, b, h) do { _Pragma("unroll") for (int m = 0; m < 4; ++m) _Pragma("unroll") for (int k = 0; k < 2; ++k) dst[m][k] = *(const LAS bf16x8*)(lds + G8_SA(b, h) + aoff + m * 2048 + k * 1024); } while (0)
; #define G8_LDB(dst, b, h) do { _Pragma("unroll") for (int n = 0; n < 2; ++n) _Pragma("unroll") for (int k = 0; k < 2; ++k) dst[n][k] = *(const LAS bf16x8*)(lds + G8_SB(b, h) + boff + n * 2048 + k * 1024); } while (0)
; #define G8_MMA(ai, bj, At, Bt) do { __builtin_amdgcn_s_setprio(1); _Pragma("unroll") for (int m = 0; m < 4; ++m) _Pragma("unroll") for (int n = 0; n < 2; ++n) _Pragma("unroll") for (int k = 0; k < 2; ++k) \
;     acc[ai][bj][m][n] = __builtin_amdgcn_mfma_f32_16x16x32_bf16(Bt[n][k], At[m][k], acc[ai][bj][m][n], 0, 0, 0); __builtin_amdgcn_s_setprio(0); } while (0)
; #define G8_WAIT_L(n) asm volatile("s_waitcnt lgkmcnt(" #n ")" ::: "memory")
; #define G8_BAR __builtin_amdgcn_s_barrier()
; #define G8_SCHED __builtin_amdgcn_sched_barrier(0)
; template <class Epi, class Sched>
; __device__ __forceinline__ void gemm_phase(const int wv_, LAS unsigned char* lds, const int lda, const int ldb, const int K, const Sched& S, const Epi& E) {
;     ...
;     for (int t = 0; t < nt; t += 2) {
;       const bool last = (t == nt - 2);
;       const char* a1 = cA + (size_t)(t + 1) * kstep;
;       const char* a2 = last ? nA : cA + (size_t)(t + 2) * kstep; const char* b2 = last ? nB : cB + (size_t)(t + 2) * kstep;
;       const char* a3 = a2 + kstep; const char* b3 = b2 + kstep;
;       G8_LDB(B0, 0, 0); G8_SCHED; G8_LDA(At, 0, 0); G8_STAGE(G8_SA(1, 1), a1 + hstepA, voffA);
;       G8_WAIT_L(8); G8_BAR; G8_WAIT_L(0); G8_MMA(0, 0, At, B0); G8_BAR; G8_SCHED;
;       G8_LDB(B1, 0, 1); G8_STAGE(G8_SB(0, 0), b2, voffB);
;       G8_BAR; G8_WAIT_L(0); G8_MMA(0, 1, At, B1); G8_BAR;
;       G8_LDA(At, 0, 1); G8_STAGE(G8_SA(0, 0), a2, voffA);
;       G8_BAR; G8_WAIT_L(0); G8_MMA(1, 0, At, B0); G8_BAR; G8_SCHED;
.Lg4_noprio:
.LBB0_1173:
	s_add_u32 s28, s26, 0xfff80080
	s_addc_u32 s29, s27, -1
	s_add_i32 s51, 0, 0x10000
	v_add_u32_e32 v149, s51, v146
	ds_read_b128 v[142:145], v149
	ds_read_b128 v[156:159], v149 offset:1024
	ds_read_b128 v[160:163], v149 offset:2048
	ds_read_b128 v[164:167], v149 offset:3072
	s_cmp_eq_u32 s50, 28
	s_cselect_b32 s31, s19, s29
	s_cselect_b32 s30, s18, s28
	s_cselect_b32 s29, s21, s17
	s_cselect_b32 s28, s20, s13
	v_lshl_add_u64 v[150:151], s[26:27], 0, v[138:139]
	s_add_i32 m0, s23, 0xc000
	ds_read_b128 v[190:193], v148
	ds_read_b128 v[194:197], v148 offset:1024
	ds_read_b128 v[198:201], v148 offset:2048
	ds_read_b128 v[202:205], v148 offset:3072
	ds_read_b128 v[206:209], v148 offset:4096
	ds_read_b128 v[210:213], v148 offset:5120
	ds_read_b128 v[214:217], v148 offset:6144
	ds_read_b128 v[218:221], v148 offset:7168
	global_load_lds_dwordx4 v[150:151], off
	v_lshl_add_u64 v[150:151], s[26:27], 0, v[140:141]
	s_add_i32 m0, s23, 0xe000
	s_nop 0
	global_load_lds_dwordx4 v[150:151], off
	s_waitcnt lgkmcnt(8)
	s_barrier
	s_waitcnt lgkmcnt(0)
	v_mfma_f32_16x16x32_bf16 v[128:131], v[142:145], v[190:193], v[128:131]
	v_mfma_f32_16x16x32_bf16 v[124:127], v[160:163], v[190:193], v[124:127]
	v_mfma_f32_16x16x32_bf16 v[112:115], v[142:145], v[198:201], v[112:115]
	v_mfma_f32_16x16x32_bf16 v[108:111], v[160:163], v[198:201], v[108:111]
	v_mfma_f32_16x16x32_bf16 v[96:99], v[142:145], v[206:209], v[96:99]
	v_mfma_f32_16x16x32_bf16 v[92:95], v[160:163], v[206:209], v[92:95]
	v_mfma_f32_16x16x32_bf16 v[80:83], v[142:145], v[214:217], v[80:83]
	v_mfma_f32_16x16x32_bf16 v[76:79], v[160:163], v[214:217], v[76:79]
	v_mfma_f32_16x16x32_bf16 v[128:131], v[156:159], v[194:197], v[128:131]
	v_mfma_f32_16x16x32_bf16 v[124:127], v[164:167], v[194:197], v[124:127]
	v_mfma_f32_16x16x32_bf16 v[112:115], v[156:159], v[202:205], v[112:115]
	v_mfma_f32_16x16x32_bf16 v[108:111], v[164:167], v[202:205], v[108:111]
	v_mfma_f32_16x16x32_bf16 v[96:99], v[156:159], v[210:213], v[96:99]
	v_mfma_f32_16x16x32_bf16 v[92:95], v[164:167], v[210:213], v[92:95]
	v_mfma_f32_16x16x32_bf16 v[80:83], v[156:159], v[218:221], v[80:83]
	v_mfma_f32_16x16x32_bf16 v[76:79], v[164:167], v[218:221], v[76:79]
	s_barrier
	s_add_i32 s68, 0, 0x14000
	s_add_i32 s51, s51, s40
	v_add_u32_e32 v149, s68, v146
	v_lshl_add_u64 v[150:151], s[28:29], 0, v[132:133]
	s_mov_b32 m0, s51
	ds_read_b128 v[222:225], v149
	ds_read_b128 v[226:229], v149 offset:1024
	ds_read_b128 v[230:233], v149 offset:2048
	ds_read_b128 v[234:237], v149 offset:3072
	global_load_lds_dwordx4 v[150:151], off
	v_lshl_add_u64 v[168:169], s[28:29], 0, v[136:137]
	s_add_i32 m0, s51, 0x2000
	s_nop 0
	global_load_lds_dwordx4 v[168:169], off
	s_barrier
	s_waitcnt lgkmcnt(0)
	v_mfma_f32_16x16x32_bf16 v[120:123], v[222:225], v[190:193], v[120:123]
	v_mfma_f32_16x16x32_bf16 v[116:119], v[230:233], v[190:193], v[116:119]
	v_mfma_f32_16x16x32_bf16 v[104:107], v[222:225], v[198:201], v[104:107]
	v_mfma_f32_16x16x32_bf16 v[100:103], v[230:233], v[198:201], v[100:103]
	v_mfma_f32_16x16x32_bf16 v[88:91], v[222:225], v[206:209], v[88:91]
	v_mfma_f32_16x16x32_bf16 v[84:87], v[230:233], v[206:209], v[84:87]
	v_mfma_f32_16x16x32_bf16 v[72:75], v[222:225], v[214:217], v[72:75]
	v_mfma_f32_16x16x32_bf16 v[68:71], v[230:233], v[214:217], v[68:71]
	v_mfma_f32_16x16x32_bf16 v[120:123], v[226:229], v[194:197], v[120:123]
	v_mfma_f32_16x16x32_bf16 v[116:119], v[234:237], v[194:197], v[116:119]
	v_mfma_f32_16x16x32_bf16 v[104:107], v[226:229], v[202:205], v[104:107]
	v_mfma_f32_16x16x32_bf16 v[100:103], v[234:237], v[202:205], v[100:103]
	v_mfma_f32_16x16x32_bf16 v[88:91], v[226:229], v[210:213], v[88:91]
	v_mfma_f32_16x16x32_bf16 v[84:87], v[234:237], v[210:213], v[84:87]
	v_mfma_f32_16x16x32_bf16 v[72:75], v[226:229], v[218:221], v[72:75]
	v_mfma_f32_16x16x32_bf16 v[68:71], v[234:237], v[218:221], v[68:71]
	s_mov_b32 m0, s23
	v_lshl_add_u64 v[238:239], s[30:31], 0, v[0:1]
	s_barrier
	ds_read_b128 v[190:193], v148 offset:16384
	ds_read_b128 v[194:197], v148 offset:17408
	ds_read_b128 v[198:201], v148 offset:18432
	ds_read_b128 v[202:205], v148 offset:19456
	ds_read_b128 v[206:209], v148 offset:20480
	ds_read_b128 v[210:213], v148 offset:21504
	ds_read_b128 v[214:217], v148 offset:22528
	ds_read_b128 v[218:221], v148 offset:23552
	global_load_lds_dwordx4 v[238:239], off
	v_lshl_add_u64 v[240:241], s[30:31], 0, v[134:135]
	s_mov_b32 m0, s25
	s_nop 0
	global_load_lds_dwordx4 v[240:241], off
	s_barrier
	s_waitcnt lgkmcnt(0)
	v_mfma_f32_16x16x32_bf16 v[64:67], v[142:145], v[190:193], v[64:67]
	v_mfma_f32_16x16x32_bf16 v[60:63], v[160:163], v[190:193], v[60:63]
	v_mfma_f32_16x16x32_bf16 v[48:51], v[142:145], v[198:201], v[48:51]
	v_mfma_f32_16x16x32_bf16 v[44:47], v[160:163], v[198:201], v[44:47]
	v_mfma_f32_16x16x32_bf16 v[32:35], v[142:145], v[206:209], v[32:35]
	v_mfma_f32_16x16x32_bf16 v[28:31], v[160:163], v[206:209], v[28:31]
	v_mfma_f32_16x16x32_bf16 v[16:19], v[142:145], v[214:217], v[16:19]
	v_mfma_f32_16x16x32_bf16 v[12:15], v[160:163], v[214:217], v[12:15]
	v_mfma_f32_16x16x32_bf16 v[64:67], v[156:159], v[194:197], v[64:67]
	v_mfma_f32_16x16x32_bf16 v[60:63], v[164:167], v[194:197], v[60:63]
	v_mfma_f32_16x16x32_bf16 v[48:51], v[156:159], v[202:205], v[48:51]
	v_mfma_f32_16x16x32_bf16 v[44:47], v[164:167], v[202:205], v[44:47]
	v_mfma_f32_16x16x32_bf16 v[32:35], v[156:159], v[210:213], v[32:35]
	v_mfma_f32_16x16x32_bf16 v[28:31], v[164:167], v[210:213], v[28:31]
	v_mfma_f32_16x16x32_bf16 v[16:19], v[156:159], v[218:221], v[16:19]
	v_mfma_f32_16x16x32_bf16 v[12:15], v[164:167], v[218:221], v[12:15]
	s_barrier
; #define G8_STAGE(bufoff, gbase, voff) do { _Pragma("unroll") for (int _i = 0; _i < 2; ++_i) \
;     __builtin_amdgcn_global_load_lds((const unsigned*)((const char*)(gbase) + (voff)[_i]), (LAS unsigned*)(lds + (bufoff) + ldsw + _i * 8192), 16, 0, 0); } while (0)
; #define G8_LDA(dst, b, h) do { _Pragma("unroll") for (int m = 0; m < 4; ++m) _Pragma("unroll") for (int k = 0; k < 2; ++k) dst[m][k] = *(const LAS bf16x8*)(lds + G8_SA(b, h) + aoff + m * 2048 + k * 1024); } while (0)
; #define G8_LDB(dst, b, h) do { _Pragma("unroll") for (int n = 0; n < 2; ++n) _Pragma("unroll") for (int k = 0; k < 2; ++k) dst[n][k] = *(const LAS bf16x8*)(lds + G8_SB(b, h) + boff + n * 2048 + k * 1024); } while (0)
; #define G8_MMA(ai, bj, At, Bt) do { __builtin_amdgcn_s_setprio(1); _Pragma("unroll") for (int m = 0; m < 4; ++m) _Pragma("unroll") for (int n = 0; n < 2; ++n) _Pragma("unroll") for (int k = 0; k < 2; ++k) \
;     acc[ai][bj][m][n] = __builtin_amdgcn_mfma_f32_16x16x32_bf16(Bt[n][k], At[m][k], acc[ai][bj][m][n], 0, 0, 0); __builtin_amdgcn_s_setprio(0); } while (0)
; #define G8_WAIT_V(n) asm volatile("s_waitcnt vmcnt(" #n ")" ::: "memory")
; #define G8_WAIT_L(n) asm volatile("s_waitcnt lgkmcnt(" #n ")" ::: "memory")
; #define G8_BAR __builtin_amdgcn_s_barrier()
; #define G8_SCHED __builtin_amdgcn_sched_barrier(0)
; template <class Epi, class Sched>
; __device__ __forceinline__ void gemm_phase(const int wv_, LAS unsigned char* lds, const int lda, const int ldb, const int K, const Sched& S, const Epi& E) {
;     ...
;       G8_STAGE(G8_SB(0, 1), b2 + hstepB, voffB);
;       G8_WAIT_V(6); G8_BAR; G8_MMA(1, 1, At, B1); G8_BAR;
;       G8_LDB(B0, 1, 0); G8_SCHED; G8_LDA(At, 1, 0); G8_STAGE(G8_SA(0, 1), a2 + hstepA, voffA);
;       G8_WAIT_L(8); G8_BAR; G8_WAIT_L(0); G8_MMA(0, 0, At, B0); G8_BAR; G8_SCHED;
;       G8_LDB(B1, 1, 1); G8_STAGE(G8_SB(1, 0), b3, voffB);
;       G8_BAR; G8_WAIT_L(0); G8_MMA(0, 1, At, B1); G8_BAR;
;       G8_LDA(At, 1, 1); G8_STAGE(G8_SA(1, 0), a3, voffA);
	s_add_u32 s58, s28, 0x80000
	s_addc_u32 s59, s29, 0
	s_add_i32 s51, s68, s40
	v_lshl_add_u64 v[142:143], s[58:59], 0, v[132:133]
	s_mov_b32 m0, s51
	s_nop 0
	global_load_lds_dwordx4 v[142:143], off
	v_lshl_add_u64 v[142:143], s[58:59], 0, v[136:137]
	s_add_i32 m0, s51, 0x2000
	s_nop 0
	global_load_lds_dwordx4 v[142:143], off
	s_waitcnt vmcnt(6)
	s_barrier
	v_mfma_f32_16x16x32_bf16 v[56:59], v[222:225], v[190:193], v[56:59]
	v_mfma_f32_16x16x32_bf16 v[52:55], v[230:233], v[190:193], v[52:55]
	v_mfma_f32_16x16x32_bf16 v[40:43], v[222:225], v[198:201], v[40:43]
	v_mfma_f32_16x16x32_bf16 v[36:39], v[230:233], v[198:201], v[36:39]
	v_mfma_f32_16x16x32_bf16 v[24:27], v[222:225], v[206:209], v[24:27]
	v_mfma_f32_16x16x32_bf16 v[20:23], v[230:233], v[206:209], v[20:23]
	v_mfma_f32_16x16x32_bf16 v[8:11], v[222:225], v[214:217], v[8:11]
	v_mfma_f32_16x16x32_bf16 v[4:7], v[230:233], v[214:217], v[4:7]
	v_mfma_f32_16x16x32_bf16 v[56:59], v[226:229], v[194:197], v[56:59]
	v_mfma_f32_16x16x32_bf16 v[52:55], v[234:237], v[194:197], v[52:55]
	v_mfma_f32_16x16x32_bf16 v[40:43], v[226:229], v[202:205], v[40:43]
	v_mfma_f32_16x16x32_bf16 v[36:39], v[234:237], v[202:205], v[36:39]
	v_mfma_f32_16x16x32_bf16 v[24:27], v[226:229], v[210:213], v[24:27]
	v_mfma_f32_16x16x32_bf16 v[20:23], v[234:237], v[210:213], v[20:23]
	v_mfma_f32_16x16x32_bf16 v[8:11], v[226:229], v[218:221], v[8:11]
	v_mfma_f32_16x16x32_bf16 v[4:7], v[234:237], v[218:221], v[4:7]
	s_add_i32 s51, 0, 0x18000
	v_add_u32_e32 v149, s51, v146
	s_barrier
	ds_read_b128 v[142:145], v149
	ds_read_b128 v[156:159], v149 offset:1024
	ds_read_b128 v[160:163], v149 offset:2048
	ds_read_b128 v[164:167], v149 offset:3072
	s_add_u32 s30, s30, 0x80000
	s_addc_u32 s31, s31, 0
	s_mov_b32 m0, s41
	v_lshl_add_u64 v[222:223], s[30:31], 0, v[0:1]
	ds_read_b128 v[190:193], v148 offset:32768
	ds_read_b128 v[194:197], v148 offset:33792
	ds_read_b128 v[198:201], v148 offset:34816
	ds_read_b128 v[202:205], v148 offset:35840
	ds_read_b128 v[206:209], v148 offset:36864
	ds_read_b128 v[210:213], v148 offset:37888
	ds_read_b128 v[214:217], v148 offset:38912
	ds_read_b128 v[218:221], v148 offset:39936
	global_load_lds_dwordx4 v[222:223], off
	v_lshl_add_u64 v[222:223], s[30:31], 0, v[134:135]
	s_mov_b32 m0, s42
	s_nop 0
	global_load_lds_dwordx4 v[222:223], off
	s_waitcnt lgkmcnt(8)
	s_barrier
	s_waitcnt lgkmcnt(0)
	v_mfma_f32_16x16x32_bf16 v[128:131], v[142:145], v[190:193], v[128:131]
	v_mfma_f32_16x16x32_bf16 v[124:127], v[160:163], v[190:193], v[124:127]
	v_mfma_f32_16x16x32_bf16 v[112:115], v[142:145], v[198:201], v[112:115]
	v_mfma_f32_16x16x32_bf16 v[108:111], v[160:163], v[198:201], v[108:111]
	v_mfma_f32_16x16x32_bf16 v[96:99], v[142:145], v[206:209], v[96:99]
	v_mfma_f32_16x16x32_bf16 v[92:95], v[160:163], v[206:209], v[92:95]
	v_mfma_f32_16x16x32_bf16 v[80:83], v[142:145], v[214:217], v[80:83]
	v_mfma_f32_16x16x32_bf16 v[76:79], v[160:163], v[214:217], v[76:79]
	v_mfma_f32_16x16x32_bf16 v[128:131], v[156:159], v[194:197], v[128:131]
	v_mfma_f32_16x16x32_bf16 v[124:127], v[164:167], v[194:197], v[124:127]
	v_mfma_f32_16x16x32_bf16 v[112:115], v[156:159], v[202:205], v[112:115]
	v_mfma_f32_16x16x32_bf16 v[108:111], v[164:167], v[202:205], v[108:111]
	v_mfma_f32_16x16x32_bf16 v[96:99], v[156:159], v[210:213], v[96:99]
	v_mfma_f32_16x16x32_bf16 v[92:95], v[164:167], v[210:213], v[92:95]
	v_mfma_f32_16x16x32_bf16 v[80:83], v[156:159], v[218:221], v[80:83]
	v_mfma_f32_16x16x32_bf16 v[76:79], v[164:167], v[218:221], v[76:79]
	s_barrier
	s_add_i32 s30, 0, 0x1c000
	s_add_i32 s31, s51, s40
	v_add_u32_e32 v149, s30, v146
	v_lshl_add_u64 v[150:151], v[150:151], 0, s[90:91]
	s_mov_b32 m0, s31
	ds_read_b128 v[222:225], v149
	ds_read_b128 v[226:229], v149 offset:1024
	ds_read_b128 v[230:233], v149 offset:2048
	ds_read_b128 v[234:237], v149 offset:3072
	global_load_lds_dwordx4 v[150:151], off
	v_lshl_add_u64 v[150:151], v[168:169], 0, s[90:91]
	s_add_i32 m0, s31, 0x2000
	s_nop 0
	global_load_lds_dwordx4 v[150:151], off
	s_barrier
	s_waitcnt lgkmcnt(0)
	v_mfma_f32_16x16x32_bf16 v[120:123], v[222:225], v[190:193], v[120:123]
	v_mfma_f32_16x16x32_bf16 v[116:119], v[230:233], v[190:193], v[116:119]
	v_mfma_f32_16x16x32_bf16 v[104:107], v[222:225], v[198:201], v[104:107]
	v_mfma_f32_16x16x32_bf16 v[100:103], v[230:233], v[198:201], v[100:103]
	v_mfma_f32_16x16x32_bf16 v[88:91], v[222:225], v[206:209], v[88:91]
	v_mfma_f32_16x16x32_bf16 v[84:87], v[230:233], v[206:209], v[84:87]
	v_mfma_f32_16x16x32_bf16 v[72:75], v[222:225], v[214:217], v[72:75]
	v_mfma_f32_16x16x32_bf16 v[68:71], v[230:233], v[214:217], v[68:71]
	v_mfma_f32_16x16x32_bf16 v[120:123], v[226:229], v[194:197], v[120:123]
	v_mfma_f32_16x16x32_bf16 v[116:119], v[234:237], v[194:197], v[116:119]
	v_mfma_f32_16x16x32_bf16 v[104:107], v[226:229], v[202:205], v[104:107]
	v_mfma_f32_16x16x32_bf16 v[100:103], v[234:237], v[202:205], v[100:103]
	v_mfma_f32_16x16x32_bf16 v[88:91], v[226:229], v[210:213], v[88:91]
	v_mfma_f32_16x16x32_bf16 v[84:87], v[234:237], v[210:213], v[84:87]
	v_mfma_f32_16x16x32_bf16 v[72:75], v[226:229], v[218:221], v[72:75]
	v_mfma_f32_16x16x32_bf16 v[68:71], v[234:237], v[218:221], v[68:71]
	s_mov_b32 m0, s43
	v_lshl_add_u64 v[150:151], v[238:239], 0, s[90:91]
	s_barrier
	ds_read_b128 v[190:193], v148 offset:49152
	ds_read_b128 v[194:197], v148 offset:50176
	ds_read_b128 v[198:201], v148 offset:51200
	ds_read_b128 v[202:205], v148 offset:52224
	ds_read_b128 v[206:209], v148 offset:53248
	ds_read_b128 v[210:213], v148 offset:54272
	ds_read_b128 v[214:217], v148 offset:55296
	ds_read_b128 v[218:221], v148 offset:56320
	global_load_lds_dwordx4 v[150:151], off
	v_lshl_add_u64 v[150:151], v[240:241], 0, s[90:91]
	s_mov_b32 m0, s46
	s_nop 0
	global_load_lds_dwordx4 v[150:151], off
	s_barrier
; __device__ __forceinline__ unsigned pk2(float lo, float hi) { f32x2n v = {lo, hi}; bf16x2n b = __builtin_convertvector(v, bf16x2n); return __builtin_bit_cast(unsigned, b); }
; #define G8_STAGE(bufoff, gbase, voff) do { _Pragma("unroll") for (int _i = 0; _i < 2; ++_i) \
;     __builtin_amdgcn_global_load_lds((const unsigned*)((const char*)(gbase) + (voff)[_i]), (LAS unsigned*)(lds + (bufoff) + ldsw + _i * 8192), 16, 0, 0); } while (0)
; #define G8_MMA(ai, bj, At, Bt) do { __builtin_amdgcn_s_setprio(1); _Pragma("unroll") for (int m = 0; m < 4; ++m) _Pragma("unroll") for (int n = 0; n < 2; ++n) _Pragma("unroll") for (int k = 0; k < 2; ++k) \
;     acc[ai][bj][m][n] = __builtin_amdgcn_mfma_f32_16x16x32_bf16(Bt[n][k], At[m][k], acc[ai][bj][m][n], 0, 0, 0); __builtin_amdgcn_s_setprio(0); } while (0)
; #define G8_WAIT_V(n) asm volatile("s_waitcnt vmcnt(" #n ")" ::: "memory")
; #define G8_WAIT_L(n) asm volatile("s_waitcnt lgkmcnt(" #n ")" ::: "memory")
; #define G8_BAR __builtin_amdgcn_s_barrier()
; #define G8_SCHED __builtin_amdgcn_sched_barrier(0)
; template <class Epi, class Sched>
; __device__ __forceinline__ void gemm_phase(const int wv_, LAS unsigned char* lds, const int lda, const int ldb, const int K, const Sched& S, const Epi& E) {
;     ...
;       G8_BAR; G8_WAIT_L(0); G8_MMA(1, 0, At, B0); G8_BAR; G8_SCHED;
;       G8_STAGE(G8_SB(1, 1), b3 + hstepB, voffB);
;       G8_WAIT_V(6); G8_BAR; G8_MMA(1, 1, At, B1); G8_BAR;
;     }
;   __device__ __forceinline__ bool operator()(f32x4 (&acc)[2][2][4][2], const Unit& u, int wr, int wc, int fr, int fq) const {
;     const int row0 = u.pm * BM + wr * 64 + fr, col0 = u.pn * BM + wc * 32 + 8 * fq;
; #pragma unroll
;     for (int ai = 0; ai < 2; ++ai)
; #pragma unroll
;       for (int m = 0; m < 4; ++m) { size_t off = (size_t)(row0 + ai * HALF + m * 16) * HID + col0; asm volatile("" : "+v"(off)); bf16_t* rowp = hid + off;
; #pragma unroll
;         for (int bj = 0; bj < 2; ++bj) { f32x4 v0 = acc[ai][bj][m][0], v1 = acc[ai][bj][m][1];
; #pragma unroll
;           for (int e = 0; e < 4; ++e) { float a = fmaxf(v0[e], 0.f), b = fmaxf(v1[e], 0.f); v0[e] = a * a; v1[e] = b * b; }
;           u32x4 w; w.x = pk2(v0[0], v0[1]); w.y = pk2(v0[2], v0[3]); w.z = pk2(v1[0], v1[1]); w.w = pk2(v1[2], v1[3]);
;           *(u32x4*)(rowp + bj * HALF) = w; } }
	s_waitcnt lgkmcnt(0)
	v_mfma_f32_16x16x32_bf16 v[64:67], v[142:145], v[190:193], v[64:67]
	v_mfma_f32_16x16x32_bf16 v[60:63], v[160:163], v[190:193], v[60:63]
	v_mfma_f32_16x16x32_bf16 v[48:51], v[142:145], v[198:201], v[48:51]
	v_mfma_f32_16x16x32_bf16 v[44:47], v[160:163], v[198:201], v[44:47]
	v_mfma_f32_16x16x32_bf16 v[32:35], v[142:145], v[206:209], v[32:35]
	v_mfma_f32_16x16x32_bf16 v[28:31], v[160:163], v[206:209], v[28:31]
	v_mfma_f32_16x16x32_bf16 v[16:19], v[142:145], v[214:217], v[16:19]
	v_mfma_f32_16x16x32_bf16 v[12:15], v[160:163], v[214:217], v[12:15]
	v_mfma_f32_16x16x32_bf16 v[64:67], v[156:159], v[194:197], v[64:67]
	v_mfma_f32_16x16x32_bf16 v[60:63], v[164:167], v[194:197], v[60:63]
	v_mfma_f32_16x16x32_bf16 v[48:51], v[156:159], v[202:205], v[48:51]
	v_mfma_f32_16x16x32_bf16 v[44:47], v[164:167], v[202:205], v[44:47]
	v_mfma_f32_16x16x32_bf16 v[32:35], v[156:159], v[210:213], v[32:35]
	v_mfma_f32_16x16x32_bf16 v[28:31], v[164:167], v[210:213], v[28:31]
	v_mfma_f32_16x16x32_bf16 v[16:19], v[156:159], v[218:221], v[16:19]
	v_mfma_f32_16x16x32_bf16 v[12:15], v[164:167], v[218:221], v[12:15]
	s_barrier
	s_add_u32 s28, s28, 0x80080
	s_addc_u32 s29, s29, 0
	s_add_i32 s30, s30, s40
	v_lshl_add_u64 v[142:143], s[28:29], 0, v[132:133]
	s_mov_b32 m0, s30
	s_nop 0
	global_load_lds_dwordx4 v[142:143], off
	v_lshl_add_u64 v[142:143], s[28:29], 0, v[136:137]
	s_add_i32 m0, s30, 0x2000
	s_nop 0
	global_load_lds_dwordx4 v[142:143], off
	s_waitcnt vmcnt(6)
	s_barrier
	v_mfma_f32_16x16x32_bf16 v[56:59], v[222:225], v[190:193], v[56:59]
	v_mfma_f32_16x16x32_bf16 v[52:55], v[230:233], v[190:193], v[52:55]
	v_mfma_f32_16x16x32_bf16 v[40:43], v[222:225], v[198:201], v[40:43]
	v_mfma_f32_16x16x32_bf16 v[36:39], v[230:233], v[198:201], v[36:39]
	v_mfma_f32_16x16x32_bf16 v[24:27], v[222:225], v[206:209], v[24:27]
	v_mfma_f32_16x16x32_bf16 v[20:23], v[230:233], v[206:209], v[20:23]
	v_mfma_f32_16x16x32_bf16 v[8:11], v[222:225], v[214:217], v[8:11]
	v_mfma_f32_16x16x32_bf16 v[4:7], v[230:233], v[214:217], v[4:7]
	v_mfma_f32_16x16x32_bf16 v[56:59], v[226:229], v[194:197], v[56:59]
	v_mfma_f32_16x16x32_bf16 v[52:55], v[234:237], v[194:197], v[52:55]
	v_mfma_f32_16x16x32_bf16 v[40:43], v[226:229], v[202:205], v[40:43]
	v_mfma_f32_16x16x32_bf16 v[36:39], v[234:237], v[202:205], v[36:39]
	v_mfma_f32_16x16x32_bf16 v[24:27], v[226:229], v[210:213], v[24:27]
	v_mfma_f32_16x16x32_bf16 v[20:23], v[234:237], v[210:213], v[20:23]
	v_mfma_f32_16x16x32_bf16 v[8:11], v[226:229], v[218:221], v[8:11]
	v_mfma_f32_16x16x32_bf16 v[4:7], v[234:237], v[218:221], v[4:7]
	s_add_i32 s50, s50, 2
	s_add_u32 s26, s26, 0x100
	s_addc_u32 s27, s27, 0
	s_add_u32 s13, s13, 0x100
	s_addc_u32 s17, s17, 0
	s_cmp_gt_u32 s50, 29
	s_barrier
	s_cbranch_scc0 .LBB0_1173
	s_setprio 0
	v_lshl_add_u32 v150, s24, 8, v3
	v_max_f32_e32 v124, v124, v124
	v_max_f32_e32 v125, v125, v125
	v_lshl_or_b32 v144, s22, 8, v147
	v_ashrrev_i32_e32 v151, 31, v150
	v_max_f32_e32 v124, 0, v124
	v_max_f32_e32 v125, 0, v125
	v_ashrrev_i32_e32 v145, 31, v144
	v_lshlrev_b64 v[142:143], 13, v[150:151]
	v_pk_mul_f32 v[158:159], v[124:125], v[124:125]
	v_max_f32_e32 v125, v126, v126
	v_lshl_add_u64 v[142:143], v[142:143], 0, v[144:145]
	v_max_f32_e32 v128, v128, v128
	v_max_f32_e32 v129, v129, v129
	v_max_f32_e32 v124, v130, v130
	v_max_f32_e32 v126, 0, v125
	v_max_f32_e32 v125, v131, v131
	v_max_f32_e32 v127, v127, v127
	v_mov_b64_e32 v[156:157], v[142:143]
	v_max_f32_e32 v128, 0, v128
	v_max_f32_e32 v129, 0, v129
	v_max_f32_e32 v124, 0, v124
	v_max_f32_e32 v125, 0, v125
	v_max_f32_e32 v127, 0, v127
	v_pk_mul_f32 v[128:129], v[128:129], v[128:129]
	v_pk_mul_f32 v[130:131], v[124:125], v[124:125]
	v_pk_mul_f32 v[160:161], v[126:127], v[126:127]
	v_max_f32_e32 v116, v116, v116
	v_max_f32_e32 v117, v117, v117
	v_lshl_add_u64 v[156:157], v[156:157], 1, s[10:11]
	v_cvt_pk_bf16_f32 v124, v128, v129
	v_cvt_pk_bf16_f32 v125, v130, v131
	v_cvt_pk_bf16_f32 v126, v158, v159
	v_cvt_pk_bf16_f32 v127, v160, v161
	v_max_f32_e32 v116, 0, v116
	v_max_f32_e32 v117, 0, v117
	global_store_dwordx4 v[156:157], v[124:127], off
	v_max_f32_e32 v120, v120, v120
	v_max_f32_e32 v121, v121, v121
	v_pk_mul_f32 v[124:125], v[116:117], v[116:117]
	v_max_f32_e32 v117, v118, v118
	v_max_f32_e32 v116, v122, v122
	v_max_f32_e32 v118, 0, v117
	v_max_f32_e32 v117, v123, v123
	v_max_f32_e32 v119, v119, v119
	v_max_f32_e32 v120, 0, v120
	v_max_f32_e32 v121, 0, v121
	v_max_f32_e32 v116, 0, v116
	v_max_f32_e32 v117, 0, v117
	v_max_f32_e32 v119, 0, v119
	v_pk_mul_f32 v[120:121], v[120:121], v[120:121]
	v_pk_mul_f32 v[122:123], v[116:117], v[116:117]
	v_pk_mul_f32 v[126:127], v[118:119], v[118:119]
	v_cvt_pk_bf16_f32 v116, v120, v121
	v_cvt_pk_bf16_f32 v117, v122, v123
	v_cvt_pk_bf16_f32 v118, v124, v125
	v_cvt_pk_bf16_f32 v119, v126, v127
	v_max_f32_e32 v108, v108, v108
	v_max_f32_e32 v109, v109, v109
	global_store_dwordx4 v[156:157], v[116:119], off offset:256
	v_max_f32_e32 v108, 0, v108
	v_max_f32_e32 v109, 0, v109
	v_or_b32_e32 v116, 16, v150
	v_ashrrev_i32_e32 v117, 31, v116
	v_pk_mul_f32 v[118:119], v[108:109], v[108:109]
	v_max_f32_e32 v109, v110, v110
	v_lshlrev_b64 v[116:117], 13, v[116:117]
	v_max_f32_e32 v112, v112, v112
	v_max_f32_e32 v113, v113, v113
	v_max_f32_e32 v108, v114, v114
	v_max_f32_e32 v110, 0, v109
	v_max_f32_e32 v109, v115, v115
	v_max_f32_e32 v111, v111, v111
	v_lshl_add_u64 v[116:117], v[116:117], 0, v[144:145]
	v_max_f32_e32 v112, 0, v112
	v_max_f32_e32 v113, 0, v113
	v_max_f32_e32 v108, 0, v108
	v_max_f32_e32 v109, 0, v109
	v_max_f32_e32 v111, 0, v111
	v_pk_mul_f32 v[112:113], v[112:113], v[112:113]
; __device__ __forceinline__ unsigned pk2(float lo, float hi) { f32x2n v = {lo, hi}; bf16x2n b = __builtin_convertvector(v, bf16x2n); return __builtin_bit_cast(unsigned, b); }
;   __device__ __forceinline__ bool operator()(f32x4 (&acc)[2][2][4][2], const Unit& u, int wr, int wc, int fr, int fq) const {
;     ...
;     for (int ai = 0; ai < 2; ++ai)
; #pragma unroll
;       for (int m = 0; m < 4; ++m) { size_t off = (size_t)(row0 + ai * HALF + m * 16) * HID + col0; asm volatile("" : "+v"(off)); bf16_t* rowp = hid + off;
; #pragma unroll
;         for (int bj = 0; bj < 2; ++bj) { f32x4 v0 = acc[ai][bj][m][0], v1 = acc[ai][bj][m][1];
; #pragma unroll
;           for (int e = 0; e < 4; ++e) { float a = fmaxf(v0[e], 0.f), b = fmaxf(v1[e], 0.f); v0[e] = a * a; v1[e] = b * b; }
;           u32x4 w; w.x = pk2(v0[0], v0[1]); w.y = pk2(v0[2], v0[3]); w.z = pk2(v1[0], v1[1]); w.w = pk2(v1[2], v1[3]);
;           *(u32x4*)(rowp + bj * HALF) = w; } }
	v_pk_mul_f32 v[114:115], v[108:109], v[108:109]
	v_pk_mul_f32 v[120:121], v[110:111], v[110:111]
	v_max_f32_e32 v100, v100, v100
	v_max_f32_e32 v101, v101, v101
	v_lshl_add_u64 v[116:117], v[116:117], 1, s[10:11]
	v_cvt_pk_bf16_f32 v108, v112, v113
	v_cvt_pk_bf16_f32 v109, v114, v115
	v_cvt_pk_bf16_f32 v110, v118, v119
	v_cvt_pk_bf16_f32 v111, v120, v121
	v_max_f32_e32 v100, 0, v100
	v_max_f32_e32 v101, 0, v101
	global_store_dwordx4 v[116:117], v[108:111], off
	v_max_f32_e32 v104, v104, v104
	v_max_f32_e32 v105, v105, v105
	v_pk_mul_f32 v[108:109], v[100:101], v[100:101]
	v_max_f32_e32 v101, v102, v102
	v_max_f32_e32 v100, v106, v106
	v_max_f32_e32 v102, 0, v101
	v_max_f32_e32 v101, v107, v107
	v_max_f32_e32 v103, v103, v103
	v_max_f32_e32 v104, 0, v104
	v_max_f32_e32 v105, 0, v105
	v_max_f32_e32 v100, 0, v100
	v_max_f32_e32 v101, 0, v101
	v_max_f32_e32 v103, 0, v103
	v_pk_mul_f32 v[104:105], v[104:105], v[104:105]
	v_pk_mul_f32 v[106:107], v[100:101], v[100:101]
	v_pk_mul_f32 v[110:111], v[102:103], v[102:103]
	v_cvt_pk_bf16_f32 v100, v104, v105
	v_cvt_pk_bf16_f32 v101, v106, v107
	v_cvt_pk_bf16_f32 v102, v108, v109
	v_cvt_pk_bf16_f32 v103, v110, v111
	v_max_f32_e32 v92, v92, v92
	v_max_f32_e32 v93, v93, v93
	global_store_dwordx4 v[116:117], v[100:103], off offset:256
	v_max_f32_e32 v92, 0, v92
	v_max_f32_e32 v93, 0, v93
	v_or_b32_e32 v100, 32, v150
	v_ashrrev_i32_e32 v101, 31, v100
	v_pk_mul_f32 v[102:103], v[92:93], v[92:93]
	v_max_f32_e32 v93, v94, v94
	v_lshlrev_b64 v[100:101], 13, v[100:101]
	v_max_f32_e32 v96, v96, v96
	v_max_f32_e32 v97, v97, v97
	v_max_f32_e32 v92, v98, v98
	v_max_f32_e32 v94, 0, v93
	v_max_f32_e32 v93, v99, v99
	v_max_f32_e32 v95, v95, v95
	v_lshl_add_u64 v[100:101], v[100:101], 0, v[144:145]
	v_max_f32_e32 v96, 0, v96
	v_max_f32_e32 v97, 0, v97
	v_max_f32_e32 v92, 0, v92
	v_max_f32_e32 v93, 0, v93
	v_max_f32_e32 v95, 0, v95
	v_pk_mul_f32 v[96:97], v[96:97], v[96:97]
	v_pk_mul_f32 v[98:99], v[92:93], v[92:93]
	v_pk_mul_f32 v[104:105], v[94:95], v[94:95]
	v_max_f32_e32 v84, v84, v84
	v_max_f32_e32 v85, v85, v85
	v_lshl_add_u64 v[100:101], v[100:101], 1, s[10:11]
	v_cvt_pk_bf16_f32 v92, v96, v97
	v_cvt_pk_bf16_f32 v93, v98, v99
	v_cvt_pk_bf16_f32 v94, v102, v103
	v_cvt_pk_bf16_f32 v95, v104, v105
	v_max_f32_e32 v84, 0, v84
	v_max_f32_e32 v85, 0, v85
	global_store_dwordx4 v[100:101], v[92:95], off
	v_max_f32_e32 v88, v88, v88
	v_max_f32_e32 v89, v89, v89
	v_pk_mul_f32 v[92:93], v[84:85], v[84:85]
	v_max_f32_e32 v85, v86, v86
	v_max_f32_e32 v84, v90, v90
	v_max_f32_e32 v86, 0, v85
	v_max_f32_e32 v85, v91, v91
	v_max_f32_e32 v87, v87, v87
	v_max_f32_e32 v88, 0, v88
	v_max_f32_e32 v89, 0, v89
	v_max_f32_e32 v84, 0, v84
	v_max_f32_e32 v85, 0, v85
	v_max_f32_e32 v87, 0, v87
	v_pk_mul_f32 v[88:89], v[88:89], v[88:89]
	v_pk_mul_f32 v[90:91], v[84:85], v[84:85]
	v_pk_mul_f32 v[94:95], v[86:87], v[86:87]
	v_cvt_pk_bf16_f32 v84, v88, v89
	v_cvt_pk_bf16_f32 v85, v90, v91
	v_cvt_pk_bf16_f32 v86, v92, v93
	v_cvt_pk_bf16_f32 v87, v94, v95
	v_max_f32_e32 v76, v76, v76
	v_max_f32_e32 v77, v77, v77
	global_store_dwordx4 v[100:101], v[84:87], off offset:256
	v_max_f32_e32 v76, 0, v76
	v_max_f32_e32 v77, 0, v77
	v_or_b32_e32 v84, 48, v150
	v_ashrrev_i32_e32 v85, 31, v84
	v_pk_mul_f32 v[86:87], v[76:77], v[76:77]
	v_max_f32_e32 v77, v78, v78
	v_lshlrev_b64 v[84:85], 13, v[84:85]
	v_max_f32_e32 v80, v80, v80
	v_max_f32_e32 v81, v81, v81
	v_max_f32_e32 v76, v82, v82
	v_max_f32_e32 v78, 0, v77
	v_max_f32_e32 v77, v83, v83
	v_max_f32_e32 v79, v79, v79
	v_lshl_add_u64 v[84:85], v[84:85], 0, v[144:145]
	v_max_f32_e32 v80, 0, v80
	v_max_f32_e32 v81, 0, v81
	v_max_f32_e32 v76, 0, v76
	v_max_f32_e32 v77, 0, v77
	v_max_f32_e32 v79, 0, v79
	v_pk_mul_f32 v[80:81], v[80:81], v[80:81]
	v_pk_mul_f32 v[82:83], v[76:77], v[76:77]
	v_pk_mul_f32 v[88:89], v[78:79], v[78:79]
	v_max_f32_e32 v68, v68, v68
	v_max_f32_e32 v69, v69, v69
	v_lshl_add_u64 v[84:85], v[84:85], 1, s[10:11]
	v_cvt_pk_bf16_f32 v76, v80, v81
	v_cvt_pk_bf16_f32 v77, v82, v83
	v_cvt_pk_bf16_f32 v78, v86, v87
	v_cvt_pk_bf16_f32 v79, v88, v89
	v_max_f32_e32 v68, 0, v68
	v_max_f32_e32 v69, 0, v69
	global_store_dwordx4 v[84:85], v[76:79], off
	v_max_f32_e32 v72, v72, v72
	v_max_f32_e32 v73, v73, v73
	v_pk_mul_f32 v[76:77], v[68:69], v[68:69]
	v_max_f32_e32 v69, v70, v70
	v_max_f32_e32 v68, v74, v74
	v_max_f32_e32 v70, 0, v69
	v_max_f32_e32 v69, v75, v75
	v_max_f32_e32 v71, v71, v71
	v_max_f32_e32 v72, 0, v72
	v_max_f32_e32 v73, 0, v73
	v_max_f32_e32 v68, 0, v68
	v_max_f32_e32 v69, 0, v69
	v_max_f32_e32 v71, 0, v71
	v_pk_mul_f32 v[72:73], v[72:73], v[72:73]
	v_pk_mul_f32 v[74:75], v[68:69], v[68:69]
	v_pk_mul_f32 v[78:79], v[70:71], v[70:71]
	v_max_f32_e32 v60, v60, v60
	v_max_f32_e32 v61, v61, v61
	v_cvt_pk_bf16_f32 v68, v72, v73
	v_cvt_pk_bf16_f32 v69, v74, v75
	v_cvt_pk_bf16_f32 v70, v76, v77
	v_cvt_pk_bf16_f32 v71, v78, v79
	v_max_f32_e32 v60, 0, v60
	v_max_f32_e32 v61, 0, v61
	global_store_dwordx4 v[84:85], v[68:71], off offset:256
	s_mov_b64 s[26:27], 0x100000
	v_max_f32_e32 v64, v64, v64
	v_pk_mul_f32 v[70:71], v[60:61], v[60:61]
	v_max_f32_e32 v61, v62, v62
	v_max_f32_e32 v65, v65, v65
	v_max_f32_e32 v60, v66, v66
	v_max_f32_e32 v62, 0, v61
	v_max_f32_e32 v61, v67, v67
	v_max_f32_e32 v63, v63, v63
	v_lshl_add_u64 v[68:69], v[142:143], 0, s[26:27]
	v_max_f32_e32 v64, 0, v64
	v_max_f32_e32 v65, 0, v65
	v_max_f32_e32 v60, 0, v60
	v_max_f32_e32 v61, 0, v61
	v_max_f32_e32 v63, 0, v63
	v_pk_mul_f32 v[64:65], v[64:65], v[64:65]
	v_pk_mul_f32 v[66:67], v[60:61], v[60:61]
	v_pk_mul_f32 v[72:73], v[62:63], v[62:63]
	v_max_f32_e32 v52, v52, v52
	v_max_f32_e32 v53, v53, v53
; __device__ __forceinline__ unsigned pk2(float lo, float hi) { f32x2n v = {lo, hi}; bf16x2n b = __builtin_convertvector(v, bf16x2n); return __builtin_bit_cast(unsigned, b); }
; #define G8_WAIT_V(n) asm volatile("s_waitcnt vmcnt(" #n ")" ::: "memory")
; #define G8_BAR __builtin_amdgcn_s_barrier()
; template <class Epi, class Sched>
; __device__ __forceinline__ void gemm_phase(const int wv_, LAS unsigned char* lds, const int lda, const int ldb, const int K, const Sched& S, const Epi& E) {
;     ...
;     const bool zero = E(acc, cur, wr, wc, fr, fq);
;     if (!has_next) break;
;     if (zero) {
; #pragma unroll
;       for (int a = 0; a < 2; ++a)
; #pragma unroll
;         for (int b = 0; b < 2; ++b)
; #pragma unroll
;           for (int m = 0; m < 4; ++m)
; #pragma unroll
;             for (int n = 0; n < 2; ++n) acc[a][b][m][n] = (f32x4){0.f, 0.f, 0.f, 0.f};
;     }
;     cur = nxt; cA = nA; cB = nB; ++ui;
;   }
;   G8_WAIT_V(0);
;   if (wr == 0) G8_BAR;
;   G8_BAR;
;   __device__ __forceinline__ bool operator()(f32x4 (&acc)[2][2][4][2], const Unit& u, int wr, int wc, int fr, int fq) const {
;     ...
;     for (int ai = 0; ai < 2; ++ai)
; #pragma unroll
;       for (int m = 0; m < 4; ++m) { size_t off = (size_t)(row0 + ai * HALF + m * 16) * HID + col0; asm volatile("" : "+v"(off)); bf16_t* rowp = hid + off;
; #pragma unroll
;         for (int bj = 0; bj < 2; ++bj) { f32x4 v0 = acc[ai][bj][m][0], v1 = acc[ai][bj][m][1];
; #pragma unroll
;           for (int e = 0; e < 4; ++e) { float a = fmaxf(v0[e], 0.f), b = fmaxf(v1[e], 0.f); v0[e] = a * a; v1[e] = b * b; }
;           u32x4 w; w.x = pk2(v0[0], v0[1]); w.y = pk2(v0[2], v0[3]); w.z = pk2(v1[0], v1[1]); w.w = pk2(v1[2], v1[3]);
;           *(u32x4*)(rowp + bj * HALF) = w; } }
	v_lshl_add_u64 v[68:69], v[68:69], 1, s[10:11]
	v_cvt_pk_bf16_f32 v60, v64, v65
	v_cvt_pk_bf16_f32 v61, v66, v67
	v_cvt_pk_bf16_f32 v62, v70, v71
	v_cvt_pk_bf16_f32 v63, v72, v73
	v_max_f32_e32 v52, 0, v52
	v_max_f32_e32 v53, 0, v53
	global_store_dwordx4 v[68:69], v[60:63], off
	v_max_f32_e32 v56, v56, v56
	v_max_f32_e32 v57, v57, v57
	v_pk_mul_f32 v[60:61], v[52:53], v[52:53]
	v_max_f32_e32 v53, v54, v54
	v_max_f32_e32 v52, v58, v58
	v_max_f32_e32 v54, 0, v53
	v_max_f32_e32 v53, v59, v59
	v_max_f32_e32 v55, v55, v55
	v_max_f32_e32 v56, 0, v56
	v_max_f32_e32 v57, 0, v57
	v_max_f32_e32 v52, 0, v52
	v_max_f32_e32 v53, 0, v53
	v_max_f32_e32 v55, 0, v55
	v_pk_mul_f32 v[56:57], v[56:57], v[56:57]
	v_pk_mul_f32 v[58:59], v[52:53], v[52:53]
	v_pk_mul_f32 v[62:63], v[54:55], v[54:55]
	v_max_f32_e32 v44, v44, v44
	v_max_f32_e32 v45, v45, v45
	v_cvt_pk_bf16_f32 v52, v56, v57
	v_cvt_pk_bf16_f32 v53, v58, v59
	v_cvt_pk_bf16_f32 v54, v60, v61
	v_cvt_pk_bf16_f32 v55, v62, v63
	v_max_f32_e32 v44, 0, v44
	v_max_f32_e32 v45, 0, v45
	global_store_dwordx4 v[68:69], v[52:55], off offset:256
	s_mov_b64 s[26:27], 0x120000
	v_max_f32_e32 v48, v48, v48
	v_pk_mul_f32 v[54:55], v[44:45], v[44:45]
	v_max_f32_e32 v45, v46, v46
	v_max_f32_e32 v49, v49, v49
	v_max_f32_e32 v44, v50, v50
	v_max_f32_e32 v46, 0, v45
	v_max_f32_e32 v45, v51, v51
	v_max_f32_e32 v47, v47, v47
	v_lshl_add_u64 v[52:53], v[142:143], 0, s[26:27]
	v_max_f32_e32 v48, 0, v48
	v_max_f32_e32 v49, 0, v49
	v_max_f32_e32 v44, 0, v44
	v_max_f32_e32 v45, 0, v45
	v_max_f32_e32 v47, 0, v47
	v_pk_mul_f32 v[48:49], v[48:49], v[48:49]
	v_pk_mul_f32 v[50:51], v[44:45], v[44:45]
	v_pk_mul_f32 v[56:57], v[46:47], v[46:47]
	v_max_f32_e32 v36, v36, v36
	v_max_f32_e32 v37, v37, v37
	v_lshl_add_u64 v[52:53], v[52:53], 1, s[10:11]
	v_cvt_pk_bf16_f32 v44, v48, v49
	v_cvt_pk_bf16_f32 v45, v50, v51
	v_cvt_pk_bf16_f32 v46, v54, v55
	v_cvt_pk_bf16_f32 v47, v56, v57
	v_max_f32_e32 v36, 0, v36
	v_max_f32_e32 v37, 0, v37
	global_store_dwordx4 v[52:53], v[44:47], off
	v_max_f32_e32 v40, v40, v40
	v_max_f32_e32 v41, v41, v41
	v_pk_mul_f32 v[44:45], v[36:37], v[36:37]
	v_max_f32_e32 v37, v38, v38
	v_max_f32_e32 v36, v42, v42
	v_max_f32_e32 v38, 0, v37
	v_max_f32_e32 v37, v43, v43
	v_max_f32_e32 v39, v39, v39
	v_max_f32_e32 v40, 0, v40
	v_max_f32_e32 v41, 0, v41
	v_max_f32_e32 v36, 0, v36
	v_max_f32_e32 v37, 0, v37
	v_max_f32_e32 v39, 0, v39
	v_pk_mul_f32 v[40:41], v[40:41], v[40:41]
	v_pk_mul_f32 v[42:43], v[36:37], v[36:37]
	v_pk_mul_f32 v[46:47], v[38:39], v[38:39]
	v_max_f32_e32 v28, v28, v28
	v_max_f32_e32 v29, v29, v29
	v_cvt_pk_bf16_f32 v36, v40, v41
	v_cvt_pk_bf16_f32 v37, v42, v43
	v_cvt_pk_bf16_f32 v38, v44, v45
	v_cvt_pk_bf16_f32 v39, v46, v47
	v_max_f32_e32 v28, 0, v28
	v_max_f32_e32 v29, 0, v29
	global_store_dwordx4 v[52:53], v[36:39], off offset:256
	s_mov_b64 s[26:27], 0x140000
	v_max_f32_e32 v32, v32, v32
	v_pk_mul_f32 v[38:39], v[28:29], v[28:29]
	v_max_f32_e32 v29, v30, v30
	v_max_f32_e32 v33, v33, v33
	v_max_f32_e32 v28, v34, v34
	v_max_f32_e32 v30, 0, v29
	v_max_f32_e32 v29, v35, v35
	v_max_f32_e32 v31, v31, v31
	v_lshl_add_u64 v[36:37], v[142:143], 0, s[26:27]
	v_max_f32_e32 v32, 0, v32
	v_max_f32_e32 v33, 0, v33
	v_max_f32_e32 v28, 0, v28
	v_max_f32_e32 v29, 0, v29
	v_max_f32_e32 v31, 0, v31
	v_pk_mul_f32 v[32:33], v[32:33], v[32:33]
	v_pk_mul_f32 v[34:35], v[28:29], v[28:29]
	v_pk_mul_f32 v[40:41], v[30:31], v[30:31]
	v_max_f32_e32 v20, v20, v20
	v_max_f32_e32 v21, v21, v21
	v_lshl_add_u64 v[36:37], v[36:37], 1, s[10:11]
	v_cvt_pk_bf16_f32 v28, v32, v33
	v_cvt_pk_bf16_f32 v29, v34, v35
	v_cvt_pk_bf16_f32 v30, v38, v39
	v_cvt_pk_bf16_f32 v31, v40, v41
	v_max_f32_e32 v20, 0, v20
	v_max_f32_e32 v21, 0, v21
	global_store_dwordx4 v[36:37], v[28:31], off
	v_max_f32_e32 v24, v24, v24
	v_max_f32_e32 v25, v25, v25
	v_pk_mul_f32 v[28:29], v[20:21], v[20:21]
	v_max_f32_e32 v21, v22, v22
	v_max_f32_e32 v20, v26, v26
	v_max_f32_e32 v22, 0, v21
	v_max_f32_e32 v21, v27, v27
	v_max_f32_e32 v23, v23, v23
	v_max_f32_e32 v24, 0, v24
	v_max_f32_e32 v25, 0, v25
	v_max_f32_e32 v20, 0, v20
	v_max_f32_e32 v21, 0, v21
	v_max_f32_e32 v23, 0, v23
	v_pk_mul_f32 v[24:25], v[24:25], v[24:25]
	v_pk_mul_f32 v[26:27], v[20:21], v[20:21]
	v_pk_mul_f32 v[30:31], v[22:23], v[22:23]
	v_max_f32_e32 v12, v12, v12
	v_max_f32_e32 v13, v13, v13
	v_cvt_pk_bf16_f32 v20, v24, v25
	v_cvt_pk_bf16_f32 v21, v26, v27
	v_cvt_pk_bf16_f32 v22, v28, v29
	v_cvt_pk_bf16_f32 v23, v30, v31
	v_max_f32_e32 v12, 0, v12
	v_max_f32_e32 v13, 0, v13
	global_store_dwordx4 v[36:37], v[20:23], off offset:256
	s_mov_b64 s[26:27], 0x160000
	v_max_f32_e32 v16, v16, v16
	v_pk_mul_f32 v[22:23], v[12:13], v[12:13]
	v_max_f32_e32 v13, v14, v14
	v_max_f32_e32 v17, v17, v17
	v_max_f32_e32 v12, v18, v18
	v_max_f32_e32 v14, 0, v13
	v_max_f32_e32 v13, v19, v19
	v_max_f32_e32 v15, v15, v15
	v_lshl_add_u64 v[20:21], v[142:143], 0, s[26:27]
	v_max_f32_e32 v16, 0, v16
	v_max_f32_e32 v17, 0, v17
	v_max_f32_e32 v12, 0, v12
	v_max_f32_e32 v13, 0, v13
	v_max_f32_e32 v15, 0, v15
	v_pk_mul_f32 v[16:17], v[16:17], v[16:17]
	v_pk_mul_f32 v[18:19], v[12:13], v[12:13]
	v_pk_mul_f32 v[24:25], v[14:15], v[14:15]
	v_max_f32_e32 v4, v4, v4
	v_max_f32_e32 v5, v5, v5
	v_lshl_add_u64 v[20:21], v[20:21], 1, s[10:11]
	v_cvt_pk_bf16_f32 v12, v16, v17
	v_cvt_pk_bf16_f32 v13, v18, v19
	v_cvt_pk_bf16_f32 v14, v22, v23
	v_cvt_pk_bf16_f32 v15, v24, v25
	v_max_f32_e32 v4, 0, v4
	v_max_f32_e32 v5, 0, v5
	global_store_dwordx4 v[20:21], v[12:15], off
	v_max_f32_e32 v8, v8, v8
	v_max_f32_e32 v9, v9, v9
	v_pk_mul_f32 v[12:13], v[4:5], v[4:5]
	v_max_f32_e32 v5, v6, v6
	v_max_f32_e32 v4, v10, v10
	v_max_f32_e32 v6, 0, v5
	v_max_f32_e32 v5, v11, v11
	v_max_f32_e32 v7, v7, v7
	v_max_f32_e32 v8, 0, v8
	v_max_f32_e32 v9, 0, v9
	v_max_f32_e32 v4, 0, v4
	v_max_f32_e32 v5, 0, v5
	v_max_f32_e32 v7, 0, v7
	v_pk_mul_f32 v[8:9], v[8:9], v[8:9]
	v_pk_mul_f32 v[10:11], v[4:5], v[4:5]
	v_pk_mul_f32 v[14:15], v[6:7], v[6:7]
	v_cvt_pk_bf16_f32 v4, v8, v9
	v_cvt_pk_bf16_f32 v5, v10, v11
	v_cvt_pk_bf16_f32 v6, v12, v13
	v_cvt_pk_bf16_f32 v7, v14, v15
	s_and_b64 vcc, exec, s[8:9]
	s_mov_b32 s22, s12
	s_mov_b32 s24, s16
	s_mov_b64 s[28:29], s[20:21]
	s_mov_b64 s[26:27], s[18:19]
	global_store_dwordx4 v[20:21], v[4:7], off offset:256
	s_cbranch_vccz .LBB0_1168
	s_waitcnt vmcnt(0)
	s_cmpk_gt_u32 s15, 0xff
	s_cbranch_scc1 .LBB0_1177
	s_barrier

; #define G8_STAGE(bufoff, gbase, voff) do { _Pragma("unroll") for (int _i = 0; _i < 2; ++_i) \
;     __builtin_amdgcn_global_load_lds((const unsigned*)((const char*)(gbase) + (voff)[_i]), (LAS unsigned*)(lds + (bufoff) + ldsw + _i * 8192), 16, 0, 0); } while (0)
; #define G8_LDA(dst, b, h) do { _Pragma("unroll") for (int m = 0; m < 4; ++m) _Pragma("unroll") for (int k = 0; k < 2; ++k) dst[m][k] = *(const LAS bf16x8*)(lds + G8_SA(b, h) + aoff + m * 2048 + k * 1024); } while (0)
; #define G8_LDB(dst, b, h) do { _Pragma("unroll") for (int n = 0; n < 2; ++n) _Pragma("unroll") for (int k = 0; k < 2; ++k) dst[n][k] = *(const LAS bf16x8*)(lds + G8_SB(b, h) + boff + n * 2048 + k * 1024); } while (0)
; #define G8_MMA(ai, bj, At, Bt) do { __builtin_amdgcn_s_setprio(1); _Pragma("unroll") for (int m = 0; m < 4; ++m) _Pragma("unroll") for (int n = 0; n < 2; ++n) _Pragma("unroll") for (int k = 0; k < 2; ++k) \
;     acc[ai][bj][m][n] = __builtin_amdgcn_mfma_f32_16x16x32_bf16(Bt[n][k], At[m][k], acc[ai][bj][m][n], 0, 0, 0); __builtin_amdgcn_s_setprio(0); } while (0)
; #define G8_WAIT_L(n) asm volatile("s_waitcnt lgkmcnt(" #n ")" ::: "memory")
; #define G8_BAR __builtin_amdgcn_s_barrier()
; #define G8_SCHED __builtin_amdgcn_sched_barrier(0)
; template <class Epi, class Sched>
; __device__ __forceinline__ void gemm_phase(const int wv_, LAS unsigned char* lds, const int lda, const int ldb, const int K, const Sched& S, const Epi& E) {
;     ...
;     for (int t = 0; t < nt; t += 2) {
;       const bool last = (t == nt - 2);
;       const char* a1 = cA + (size_t)(t + 1) * kstep;
;       const char* a2 = last ? nA : cA + (size_t)(t + 2) * kstep; const char* b2 = last ? nB : cB + (size_t)(t + 2) * kstep;
;       const char* a3 = a2 + kstep; const char* b3 = b2 + kstep;
;       G8_LDB(B0, 0, 0); G8_SCHED; G8_LDA(At, 0, 0); G8_STAGE(G8_SA(1, 1), a1 + hstepA, voffA);
;       G8_WAIT_L(8); G8_BAR; G8_WAIT_L(0); G8_MMA(0, 0, At, B0); G8_BAR; G8_SCHED;
;       G8_LDB(B1, 0, 1); G8_STAGE(G8_SB(0, 0), b2, voffB);
;       G8_BAR; G8_WAIT_L(0); G8_MMA(0, 1, At, B1); G8_BAR;
;       G8_LDA(At, 0, 1); G8_STAGE(G8_SA(0, 0), a2, voffA);
;       G8_BAR; G8_WAIT_L(0); G8_MMA(1, 0, At, B0); G8_BAR; G8_SCHED;
.Lg5_noprio:
.LBB0_1246:
	s_add_u32 s21, s26, 0xffe00080
	s_addc_u32 s28, s27, -1
	s_add_i32 s51, 0, 0x10000
	v_add_u32_e32 v80, s51, v168
	ds_read_b128 v[68:71], v80
	ds_read_b128 v[72:75], v80 offset:1024
	ds_read_b128 v[76:79], v80 offset:2048
	ds_read_b128 v[80:83], v80 offset:3072
	s_cmpk_eq_i32 s19, 0x7c
	s_cselect_b32 s31, s23, s28
	s_cselect_b32 s30, s22, s21
	s_cselect_b32 s29, s25, s11
	s_cselect_b32 s28, s24, s9
	v_lshl_add_u64 v[166:167], s[26:27], 0, v[150:151]
	s_add_i32 m0, s40, 0xc000
	ds_read_b128 v[158:161], v189
	ds_read_b128 v[162:165], v189 offset:1024
	ds_read_b128 v[190:193], v189 offset:2048
	ds_read_b128 v[194:197], v189 offset:3072
	ds_read_b128 v[198:201], v189 offset:4096
	ds_read_b128 v[202:205], v189 offset:5120
	ds_read_b128 v[206:209], v189 offset:6144
	ds_read_b128 v[210:213], v189 offset:7168
	global_load_lds_dwordx4 v[166:167], off
	v_lshl_add_u64 v[166:167], s[26:27], 0, v[156:157]
	s_add_i32 m0, s40, 0xe000
	s_nop 0
	global_load_lds_dwordx4 v[166:167], off
	s_waitcnt lgkmcnt(8)
	s_barrier
	s_waitcnt lgkmcnt(0)
	v_mfma_f32_16x16x32_bf16 v[144:147], v[68:71], v[158:161], v[144:147]
	v_mfma_f32_16x16x32_bf16 v[140:143], v[76:79], v[158:161], v[140:143]
	v_mfma_f32_16x16x32_bf16 v[128:131], v[68:71], v[190:193], v[128:131]
	v_mfma_f32_16x16x32_bf16 v[124:127], v[76:79], v[190:193], v[124:127]
	v_mfma_f32_16x16x32_bf16 v[112:115], v[68:71], v[198:201], v[112:115]
	v_mfma_f32_16x16x32_bf16 v[108:111], v[76:79], v[198:201], v[108:111]
	v_mfma_f32_16x16x32_bf16 v[96:99], v[68:71], v[206:209], v[96:99]
	v_mfma_f32_16x16x32_bf16 v[92:95], v[76:79], v[206:209], v[92:95]
	v_mfma_f32_16x16x32_bf16 v[144:147], v[72:75], v[162:165], v[144:147]
	v_mfma_f32_16x16x32_bf16 v[140:143], v[80:83], v[162:165], v[140:143]
	v_mfma_f32_16x16x32_bf16 v[128:131], v[72:75], v[194:197], v[128:131]
	v_mfma_f32_16x16x32_bf16 v[124:127], v[80:83], v[194:197], v[124:127]
	v_mfma_f32_16x16x32_bf16 v[112:115], v[72:75], v[202:205], v[112:115]
	v_mfma_f32_16x16x32_bf16 v[108:111], v[80:83], v[202:205], v[108:111]
	v_mfma_f32_16x16x32_bf16 v[96:99], v[72:75], v[210:213], v[96:99]
	v_mfma_f32_16x16x32_bf16 v[92:95], v[80:83], v[210:213], v[92:95]
	s_barrier
	s_add_i32 s21, 0, 0x14000
	v_add_u32_e32 v166, s21, v168
	s_add_i32 s51, s51, s39
	ds_read_b128 v[214:217], v166
	ds_read_b128 v[218:221], v166 offset:1024
	ds_read_b128 v[222:225], v166 offset:2048
	ds_read_b128 v[226:229], v166 offset:3072
	v_lshl_add_u64 v[166:167], s[28:29], 0, v[0:1]
	s_mov_b32 m0, s51
	v_lshl_add_u64 v[230:231], s[28:29], 0, v[148:149]
	global_load_lds_dwordx4 v[166:167], off
	s_add_i32 m0, s51, 0x2000
	s_nop 0
	global_load_lds_dwordx4 v[230:231], off
	s_barrier
	s_waitcnt lgkmcnt(0)
	v_mfma_f32_16x16x32_bf16 v[136:139], v[214:217], v[158:161], v[136:139]
	v_mfma_f32_16x16x32_bf16 v[132:135], v[222:225], v[158:161], v[132:135]
	v_mfma_f32_16x16x32_bf16 v[120:123], v[214:217], v[190:193], v[120:123]
	v_mfma_f32_16x16x32_bf16 v[116:119], v[222:225], v[190:193], v[116:119]
	v_mfma_f32_16x16x32_bf16 v[104:107], v[214:217], v[198:201], v[104:107]
	v_mfma_f32_16x16x32_bf16 v[100:103], v[222:225], v[198:201], v[100:103]
	v_mfma_f32_16x16x32_bf16 v[88:91], v[214:217], v[206:209], v[88:91]
	v_mfma_f32_16x16x32_bf16 v[84:87], v[222:225], v[206:209], v[84:87]
	v_mfma_f32_16x16x32_bf16 v[136:139], v[218:221], v[162:165], v[136:139]
	v_mfma_f32_16x16x32_bf16 v[132:135], v[226:229], v[162:165], v[132:135]
	v_mfma_f32_16x16x32_bf16 v[120:123], v[218:221], v[194:197], v[120:123]
	v_mfma_f32_16x16x32_bf16 v[116:119], v[226:229], v[194:197], v[116:119]
	v_mfma_f32_16x16x32_bf16 v[104:107], v[218:221], v[202:205], v[104:107]
	v_mfma_f32_16x16x32_bf16 v[100:103], v[226:229], v[202:205], v[100:103]
	v_mfma_f32_16x16x32_bf16 v[88:91], v[218:221], v[210:213], v[88:91]
	v_mfma_f32_16x16x32_bf16 v[84:87], v[226:229], v[210:213], v[84:87]
	s_mov_b32 m0, s40
	v_lshl_add_u64 v[232:233], s[30:31], 0, v[0:1]
	s_barrier
	ds_read_b128 v[158:161], v189 offset:16384
	ds_read_b128 v[162:165], v189 offset:17408
	ds_read_b128 v[190:193], v189 offset:18432
	ds_read_b128 v[194:197], v189 offset:19456
	ds_read_b128 v[198:201], v189 offset:20480
	ds_read_b128 v[202:205], v189 offset:21504
	ds_read_b128 v[206:209], v189 offset:22528
	ds_read_b128 v[210:213], v189 offset:23552
	global_load_lds_dwordx4 v[232:233], off
	v_lshl_add_u64 v[234:235], s[30:31], 0, v[148:149]
	s_mov_b32 m0, s41
	s_nop 0
	global_load_lds_dwordx4 v[234:235], off
	s_barrier
	s_waitcnt lgkmcnt(0)
	v_mfma_f32_16x16x32_bf16 v[64:67], v[68:71], v[158:161], v[64:67]
	v_mfma_f32_16x16x32_bf16 v[60:63], v[76:79], v[158:161], v[60:63]
	v_mfma_f32_16x16x32_bf16 v[48:51], v[68:71], v[190:193], v[48:51]
	v_mfma_f32_16x16x32_bf16 v[44:47], v[76:79], v[190:193], v[44:47]
	v_mfma_f32_16x16x32_bf16 v[32:35], v[68:71], v[198:201], v[32:35]
	v_mfma_f32_16x16x32_bf16 v[28:31], v[76:79], v[198:201], v[28:31]
	v_mfma_f32_16x16x32_bf16 v[16:19], v[68:71], v[206:209], v[16:19]
	v_mfma_f32_16x16x32_bf16 v[12:15], v[76:79], v[206:209], v[12:15]
	v_mfma_f32_16x16x32_bf16 v[64:67], v[72:75], v[162:165], v[64:67]
	v_mfma_f32_16x16x32_bf16 v[60:63], v[80:83], v[162:165], v[60:63]
	v_mfma_f32_16x16x32_bf16 v[48:51], v[72:75], v[194:197], v[48:51]
	v_mfma_f32_16x16x32_bf16 v[44:47], v[80:83], v[194:197], v[44:47]
	v_mfma_f32_16x16x32_bf16 v[32:35], v[72:75], v[202:205], v[32:35]
	v_mfma_f32_16x16x32_bf16 v[28:31], v[80:83], v[202:205], v[28:31]
	v_mfma_f32_16x16x32_bf16 v[16:19], v[72:75], v[210:213], v[16:19]
	v_mfma_f32_16x16x32_bf16 v[12:15], v[80:83], v[210:213], v[12:15]
	s_barrier
; #define G8_STAGE(bufoff, gbase, voff) do { _Pragma("unroll") for (int _i = 0; _i < 2; ++_i) \
;     __builtin_amdgcn_global_load_lds((const unsigned*)((const char*)(gbase) + (voff)[_i]), (LAS unsigned*)(lds + (bufoff) + ldsw + _i * 8192), 16, 0, 0); } while (0)
; #define G8_LDA(dst, b, h) do { _Pragma("unroll") for (int m = 0; m < 4; ++m) _Pragma("unroll") for (int k = 0; k < 2; ++k) dst[m][k] = *(const LAS bf16x8*)(lds + G8_SA(b, h) + aoff + m * 2048 + k * 1024); } while (0)
; #define G8_LDB(dst, b, h) do { _Pragma("unroll") for (int n = 0; n < 2; ++n) _Pragma("unroll") for (int k = 0; k < 2; ++k) dst[n][k] = *(const LAS bf16x8*)(lds + G8_SB(b, h) + boff + n * 2048 + k * 1024); } while (0)
; #define G8_MMA(ai, bj, At, Bt) do { __builtin_amdgcn_s_setprio(1); _Pragma("unroll") for (int m = 0; m < 4; ++m) _Pragma("unroll") for (int n = 0; n < 2; ++n) _Pragma("unroll") for (int k = 0; k < 2; ++k) \
;     acc[ai][bj][m][n] = __builtin_amdgcn_mfma_f32_16x16x32_bf16(Bt[n][k], At[m][k], acc[ai][bj][m][n], 0, 0, 0); __builtin_amdgcn_s_setprio(0); } while (0)
; #define G8_WAIT_V(n) asm volatile("s_waitcnt vmcnt(" #n ")" ::: "memory")
; #define G8_WAIT_L(n) asm volatile("s_waitcnt lgkmcnt(" #n ")" ::: "memory")
; #define G8_BAR __builtin_amdgcn_s_barrier()
; #define G8_SCHED __builtin_amdgcn_sched_barrier(0)
; template <class Epi, class Sched>
; __device__ __forceinline__ void gemm_phase(const int wv_, LAS unsigned char* lds, const int lda, const int ldb, const int K, const Sched& S, const Epi& E) {
;     ...
;       G8_STAGE(G8_SB(0, 1), b2 + hstepB, voffB);
;       G8_WAIT_V(6); G8_BAR; G8_MMA(1, 1, At, B1); G8_BAR;
;       G8_LDB(B0, 1, 0); G8_SCHED; G8_LDA(At, 1, 0); G8_STAGE(G8_SA(0, 1), a2 + hstepA, voffA);
;       G8_WAIT_L(8); G8_BAR; G8_WAIT_L(0); G8_MMA(0, 0, At, B0); G8_BAR; G8_SCHED;
;       G8_LDB(B1, 1, 1); G8_STAGE(G8_SB(1, 0), b3, voffB);
;       G8_BAR; G8_WAIT_L(0); G8_MMA(0, 1, At, B1); G8_BAR;
;       G8_LDA(At, 1, 1); G8_STAGE(G8_SA(1, 0), a3, voffA);
;       G8_BAR; G8_WAIT_L(0); G8_MMA(1, 0, At, B0); G8_BAR; G8_SCHED;
	s_add_u32 s58, s28, 0x200000
	s_addc_u32 s59, s29, 0
	s_add_i32 s21, s21, s39
	v_lshl_add_u64 v[68:69], s[58:59], 0, v[0:1]
	s_mov_b32 m0, s21
	s_nop 0
	global_load_lds_dwordx4 v[68:69], off
	v_lshl_add_u64 v[68:69], s[58:59], 0, v[148:149]
	s_add_i32 m0, s21, 0x2000
	s_nop 0
	global_load_lds_dwordx4 v[68:69], off
	s_waitcnt vmcnt(6)
	s_barrier
	v_mfma_f32_16x16x32_bf16 v[56:59], v[214:217], v[158:161], v[56:59]
	v_mfma_f32_16x16x32_bf16 v[52:55], v[222:225], v[158:161], v[52:55]
	v_mfma_f32_16x16x32_bf16 v[40:43], v[214:217], v[190:193], v[40:43]
	v_mfma_f32_16x16x32_bf16 v[36:39], v[222:225], v[190:193], v[36:39]
	v_mfma_f32_16x16x32_bf16 v[24:27], v[214:217], v[198:201], v[24:27]
	v_mfma_f32_16x16x32_bf16 v[20:23], v[222:225], v[198:201], v[20:23]
	v_mfma_f32_16x16x32_bf16 v[8:11], v[214:217], v[206:209], v[8:11]
	v_mfma_f32_16x16x32_bf16 v[4:7], v[222:225], v[206:209], v[4:7]
	v_mfma_f32_16x16x32_bf16 v[56:59], v[218:221], v[162:165], v[56:59]
	v_mfma_f32_16x16x32_bf16 v[52:55], v[226:229], v[162:165], v[52:55]
	v_mfma_f32_16x16x32_bf16 v[40:43], v[218:221], v[194:197], v[40:43]
	v_mfma_f32_16x16x32_bf16 v[36:39], v[226:229], v[194:197], v[36:39]
	v_mfma_f32_16x16x32_bf16 v[24:27], v[218:221], v[202:205], v[24:27]
	v_mfma_f32_16x16x32_bf16 v[20:23], v[226:229], v[202:205], v[20:23]
	v_mfma_f32_16x16x32_bf16 v[8:11], v[218:221], v[210:213], v[8:11]
	v_mfma_f32_16x16x32_bf16 v[4:7], v[226:229], v[210:213], v[4:7]
	s_add_i32 s21, 0, 0x18000
	v_add_u32_e32 v80, s21, v168
	s_barrier
	ds_read_b128 v[68:71], v80
	ds_read_b128 v[72:75], v80 offset:1024
	ds_read_b128 v[76:79], v80 offset:2048
	ds_read_b128 v[80:83], v80 offset:3072
	s_add_u32 s30, s30, 0x200000
	s_addc_u32 s31, s31, 0
	s_mov_b32 m0, s42
	v_lshl_add_u64 v[214:215], s[30:31], 0, v[0:1]
	ds_read_b128 v[158:161], v189 offset:32768
	ds_read_b128 v[162:165], v189 offset:33792
	ds_read_b128 v[190:193], v189 offset:34816
	ds_read_b128 v[194:197], v189 offset:35840
	ds_read_b128 v[198:201], v189 offset:36864
	ds_read_b128 v[202:205], v189 offset:37888
	ds_read_b128 v[206:209], v189 offset:38912
	ds_read_b128 v[210:213], v189 offset:39936
	global_load_lds_dwordx4 v[214:215], off
	v_lshl_add_u64 v[214:215], s[30:31], 0, v[148:149]
	s_mov_b32 m0, s43
	s_nop 0
	global_load_lds_dwordx4 v[214:215], off
	s_waitcnt lgkmcnt(8)
	s_barrier
	s_waitcnt lgkmcnt(0)
	v_mfma_f32_16x16x32_bf16 v[144:147], v[68:71], v[158:161], v[144:147]
	v_mfma_f32_16x16x32_bf16 v[140:143], v[76:79], v[158:161], v[140:143]
	v_mfma_f32_16x16x32_bf16 v[128:131], v[68:71], v[190:193], v[128:131]
	v_mfma_f32_16x16x32_bf16 v[124:127], v[76:79], v[190:193], v[124:127]
	v_mfma_f32_16x16x32_bf16 v[112:115], v[68:71], v[198:201], v[112:115]
	v_mfma_f32_16x16x32_bf16 v[108:111], v[76:79], v[198:201], v[108:111]
	v_mfma_f32_16x16x32_bf16 v[96:99], v[68:71], v[206:209], v[96:99]
	v_mfma_f32_16x16x32_bf16 v[92:95], v[76:79], v[206:209], v[92:95]
	v_mfma_f32_16x16x32_bf16 v[144:147], v[72:75], v[162:165], v[144:147]
	v_mfma_f32_16x16x32_bf16 v[140:143], v[80:83], v[162:165], v[140:143]
	v_mfma_f32_16x16x32_bf16 v[128:131], v[72:75], v[194:197], v[128:131]
	v_mfma_f32_16x16x32_bf16 v[124:127], v[80:83], v[194:197], v[124:127]
	v_mfma_f32_16x16x32_bf16 v[112:115], v[72:75], v[202:205], v[112:115]
	v_mfma_f32_16x16x32_bf16 v[108:111], v[80:83], v[202:205], v[108:111]
	v_mfma_f32_16x16x32_bf16 v[96:99], v[72:75], v[210:213], v[96:99]
	v_mfma_f32_16x16x32_bf16 v[92:95], v[80:83], v[210:213], v[92:95]
	s_barrier
	s_add_i32 s30, 0, 0x1c000
	s_add_i32 s21, s21, s39
	v_add_u32_e32 v226, s30, v168
	v_lshl_add_u64 v[166:167], v[166:167], 0, s[90:91]
	s_mov_b32 m0, s21
	ds_read_b128 v[214:217], v226
	ds_read_b128 v[218:221], v226 offset:1024
	ds_read_b128 v[222:225], v226 offset:2048
	ds_read_b128 v[226:229], v226 offset:3072
	global_load_lds_dwordx4 v[166:167], off
	v_lshl_add_u64 v[166:167], v[230:231], 0, s[90:91]
	s_add_i32 m0, s21, 0x2000
	s_nop 0
	global_load_lds_dwordx4 v[166:167], off
	s_barrier
; #define G8_STAGE(bufoff, gbase, voff) do { _Pragma("unroll") for (int _i = 0; _i < 2; ++_i) \
;     __builtin_amdgcn_global_load_lds((const unsigned*)((const char*)(gbase) + (voff)[_i]), (LAS unsigned*)(lds + (bufoff) + ldsw + _i * 8192), 16, 0, 0); } while (0)
; #define G8_MMA(ai, bj, At, Bt) do { __builtin_amdgcn_s_setprio(1); _Pragma("unroll") for (int m = 0; m < 4; ++m) _Pragma("unroll") for (int n = 0; n < 2; ++n) _Pragma("unroll") for (int k = 0; k < 2; ++k) \
;     acc[ai][bj][m][n] = __builtin_amdgcn_mfma_f32_16x16x32_bf16(Bt[n][k], At[m][k], acc[ai][bj][m][n], 0, 0, 0); __builtin_amdgcn_s_setprio(0); } while (0)
; #define G8_WAIT_V(n) asm volatile("s_waitcnt vmcnt(" #n ")" ::: "memory")
; #define G8_WAIT_L(n) asm volatile("s_waitcnt lgkmcnt(" #n ")" ::: "memory")
; #define G8_BAR __builtin_amdgcn_s_barrier()
; #define G8_SCHED __builtin_amdgcn_sched_barrier(0)
; #define p (kparams())
; template <class Epi, class Sched>
; __device__ __forceinline__ void gemm_phase(const int wv_, LAS unsigned char* lds, const int lda, const int ldb, const int K, const Sched& S, const Epi& E) {
;     ...
;       G8_BAR; G8_WAIT_L(0); G8_MMA(1, 0, At, B0); G8_BAR; G8_SCHED;
;       G8_STAGE(G8_SB(1, 1), b3 + hstepB, voffB);
;       G8_WAIT_V(6); G8_BAR; G8_MMA(1, 1, At, B1); G8_BAR;
;     }
;   __device__ __forceinline__ bool operator()(f32x4 (&acc)[2][2][4][2], const Unit& u, int wr, int wc, int fr, int fq) const {
;     const int row0 = u.pm * BM + wr * 64 + fr, col0 = u.pn * BM + wc * 32 + 4 * fq;
;     const int who = row_who(u.pm * BM);
;     const float* gp = modl + (size_t)who * 12288 + part * 2048 + col0;
;     f32x4 gv[2][2];
; #pragma unroll
;     for (int bj = 0; bj < 2; ++bj)
; #pragma unroll
;       for (int n = 0; n < 2; ++n) gv[bj][n] = *(const f32x4*)(gp + bj * HALF + n * 16);
; #pragma unroll
;     for (int ai = 0; ai < 2; ++ai)
; #pragma unroll
;       for (int m = 0; m < 4; ++m) { const int row = row0 + ai * HALF + m * 16;
;         KPR p = (KParams*)__builtin_amdgcn_kernarg_segment_ptr();
;         const float* src = xrow_ptr(p, layer_src, row) + col0; float* dst = xrow_dst(p, row) + col0;
	s_waitcnt lgkmcnt(0)
	v_mfma_f32_16x16x32_bf16 v[136:139], v[214:217], v[158:161], v[136:139]
	v_mfma_f32_16x16x32_bf16 v[132:135], v[222:225], v[158:161], v[132:135]
	v_mfma_f32_16x16x32_bf16 v[120:123], v[214:217], v[190:193], v[120:123]
	v_mfma_f32_16x16x32_bf16 v[116:119], v[222:225], v[190:193], v[116:119]
	v_mfma_f32_16x16x32_bf16 v[104:107], v[214:217], v[198:201], v[104:107]
	v_mfma_f32_16x16x32_bf16 v[100:103], v[222:225], v[198:201], v[100:103]
	v_mfma_f32_16x16x32_bf16 v[88:91], v[214:217], v[206:209], v[88:91]
	v_mfma_f32_16x16x32_bf16 v[84:87], v[222:225], v[206:209], v[84:87]
	v_mfma_f32_16x16x32_bf16 v[136:139], v[218:221], v[162:165], v[136:139]
	v_mfma_f32_16x16x32_bf16 v[132:135], v[226:229], v[162:165], v[132:135]
	v_mfma_f32_16x16x32_bf16 v[120:123], v[218:221], v[194:197], v[120:123]
	v_mfma_f32_16x16x32_bf16 v[116:119], v[226:229], v[194:197], v[116:119]
	v_mfma_f32_16x16x32_bf16 v[104:107], v[218:221], v[202:205], v[104:107]
	v_mfma_f32_16x16x32_bf16 v[100:103], v[226:229], v[202:205], v[100:103]
	v_mfma_f32_16x16x32_bf16 v[88:91], v[218:221], v[210:213], v[88:91]
	v_mfma_f32_16x16x32_bf16 v[84:87], v[226:229], v[210:213], v[84:87]
	s_mov_b32 m0, s46
	v_lshl_add_u64 v[166:167], v[232:233], 0, s[90:91]
	s_barrier
	ds_read_b128 v[158:161], v189 offset:49152
	ds_read_b128 v[162:165], v189 offset:50176
	ds_read_b128 v[190:193], v189 offset:51200
	ds_read_b128 v[194:197], v189 offset:52224
	ds_read_b128 v[198:201], v189 offset:53248
	ds_read_b128 v[202:205], v189 offset:54272
	ds_read_b128 v[206:209], v189 offset:55296
	ds_read_b128 v[210:213], v189 offset:56320
	global_load_lds_dwordx4 v[166:167], off
	v_lshl_add_u64 v[166:167], v[234:235], 0, s[90:91]
	s_mov_b32 m0, s47
	s_nop 0
	global_load_lds_dwordx4 v[166:167], off
	s_barrier
	s_waitcnt lgkmcnt(0)
	v_mfma_f32_16x16x32_bf16 v[64:67], v[68:71], v[158:161], v[64:67]
	v_mfma_f32_16x16x32_bf16 v[60:63], v[76:79], v[158:161], v[60:63]
	v_mfma_f32_16x16x32_bf16 v[48:51], v[68:71], v[190:193], v[48:51]
	v_mfma_f32_16x16x32_bf16 v[44:47], v[76:79], v[190:193], v[44:47]
	v_mfma_f32_16x16x32_bf16 v[32:35], v[68:71], v[198:201], v[32:35]
	v_mfma_f32_16x16x32_bf16 v[28:31], v[76:79], v[198:201], v[28:31]
	v_mfma_f32_16x16x32_bf16 v[16:19], v[68:71], v[206:209], v[16:19]
	v_mfma_f32_16x16x32_bf16 v[12:15], v[76:79], v[206:209], v[12:15]
	v_mfma_f32_16x16x32_bf16 v[64:67], v[72:75], v[162:165], v[64:67]
	v_mfma_f32_16x16x32_bf16 v[60:63], v[80:83], v[162:165], v[60:63]
	v_mfma_f32_16x16x32_bf16 v[48:51], v[72:75], v[194:197], v[48:51]
	v_mfma_f32_16x16x32_bf16 v[44:47], v[80:83], v[194:197], v[44:47]
	v_mfma_f32_16x16x32_bf16 v[32:35], v[72:75], v[202:205], v[32:35]
	v_mfma_f32_16x16x32_bf16 v[28:31], v[80:83], v[202:205], v[28:31]
	v_mfma_f32_16x16x32_bf16 v[16:19], v[72:75], v[210:213], v[16:19]
	v_mfma_f32_16x16x32_bf16 v[12:15], v[80:83], v[210:213], v[12:15]
	s_barrier
	s_add_u32 s28, s28, 0x200080
	s_addc_u32 s29, s29, 0
	s_add_i32 s21, s30, s39
	v_lshl_add_u64 v[68:69], s[28:29], 0, v[0:1]
	s_mov_b32 m0, s21
	s_nop 0
	global_load_lds_dwordx4 v[68:69], off
	v_lshl_add_u64 v[68:69], s[28:29], 0, v[148:149]
	s_add_i32 m0, s21, 0x2000
	s_nop 0
	global_load_lds_dwordx4 v[68:69], off
	s_waitcnt vmcnt(6)
	s_barrier
	v_mfma_f32_16x16x32_bf16 v[56:59], v[214:217], v[158:161], v[56:59]
	v_mfma_f32_16x16x32_bf16 v[52:55], v[222:225], v[158:161], v[52:55]
	v_mfma_f32_16x16x32_bf16 v[40:43], v[214:217], v[190:193], v[40:43]
	v_mfma_f32_16x16x32_bf16 v[36:39], v[222:225], v[190:193], v[36:39]
	v_mfma_f32_16x16x32_bf16 v[24:27], v[214:217], v[198:201], v[24:27]
	v_mfma_f32_16x16x32_bf16 v[20:23], v[222:225], v[198:201], v[20:23]
	v_mfma_f32_16x16x32_bf16 v[8:11], v[214:217], v[206:209], v[8:11]
	v_mfma_f32_16x16x32_bf16 v[4:7], v[222:225], v[206:209], v[4:7]
	v_mfma_f32_16x16x32_bf16 v[56:59], v[218:221], v[162:165], v[56:59]
	v_mfma_f32_16x16x32_bf16 v[52:55], v[226:229], v[162:165], v[52:55]
	v_mfma_f32_16x16x32_bf16 v[40:43], v[218:221], v[194:197], v[40:43]
	v_mfma_f32_16x16x32_bf16 v[36:39], v[226:229], v[194:197], v[36:39]
	v_mfma_f32_16x16x32_bf16 v[24:27], v[218:221], v[202:205], v[24:27]
	v_mfma_f32_16x16x32_bf16 v[20:23], v[226:229], v[202:205], v[20:23]
	v_mfma_f32_16x16x32_bf16 v[8:11], v[218:221], v[210:213], v[8:11]
	v_mfma_f32_16x16x32_bf16 v[4:7], v[226:229], v[210:213], v[4:7]
	s_add_i32 s19, s19, 2
	s_add_u32 s26, s26, 0x100
	s_addc_u32 s27, s27, 0
	s_add_u32 s9, s9, 0x100
	s_addc_u32 s11, s11, 0
	s_cmpk_gt_u32 s19, 0x7d
	s_barrier
	s_cbranch_scc0 .LBB0_1246
	s_setprio 0
	v_readlane_b32 s9, v242, 62
	s_cmp_eq_u32 s50, 3
	s_cselect_b32 s9, s9, 0
	s_cmp_lg_u32 s9, 0
	s_cbranch_scc1 .Lg5s_epi
	v_lshl_or_b32 v158, s18, 8, v169
	s_mul_hi_i32 s11, s20, 0x78787879
	s_lshr_b32 s9, s11, 31
	s_ashr_i32 s11, s11, 3
	s_add_i32 s11, s11, s9
	s_lshl_b32 s9, s20, 8
	s_mul_i32 s18, s11, 0xffffef00
	s_add_i32 s18, s18, s9
	s_cmpk_gt_i32 s18, 0xff
	s_cbranch_scc1 .Lg5e_lat
	s_load_dwordx2 s[20:21], s[0:1], 0x118
	s_lshl_b32 s9, s11, 21
	s_mov_b32 s11, 4
	s_waitcnt lgkmcnt(0)
	s_add_u32 s20, s20, 0x7f8000
	s_addc_u32 s21, s21, 0
	s_branch .Lg5e_ptr
